# static s_setprio 1 for the trailing half-workgroup (waves 4..7) at kernel entry, per-MFMA-block priority toggles removed
# speedup vs baseline: 1.0225x; 1.0225x over previous
; #define LAS __attribute__((address_space(3)))
; __device__ __forceinline__ const float* kin(int k) { KArgs p = (KArgs)__builtin_amdgcn_kernarg_segment_ptr(); asm volatile("" : "+s"(p)); return p->in[k]; }
; __device__ __forceinline__ void conv_mat(const float* W, const float* g, int ldw, int K, int ncols, bf16* WT, int mode, int roff, LAS float* scr, int lane, int gw, int NGW) {
;     const int nitems = (K / 64) * (ncols / 32);
;     for (int it = gw; it < nitems; it += NGW) transpose_item(W, g, ldw, K, ncols, WT, mode, roff, scr, it, lane);
; }
; __device__ __forceinline__ void conv_w13(const float* w1, const float* w3, const float* g, unsigned char* ws, LAS float* scr, int lane, int gw, int NGW) {
;     bf16* W13 = (bf16*)(ws + WS_W13);
;     conv_mat(w1, g, DFF, DM, DFF, W13, 1, 0, scr, lane, gw, NGW);
; __global__ void __launch_bounds__(NWAVES * 64, 2) mk_fwd(Args args) {
;     ...
;     const int NGW = F.G * NWAVES;
;     const unsigned phmask = args.mask;
;     const int first_idle = 1496 % F.G, n_idle = first_idle ? F.G - first_idle : F.G, my_idle = first_idle ? (int)blockIdx.x - first_idle : (int)blockIdx.x;
;     const int INGW = n_idle * NWAVES;
;     ...
;     int probe_two = 2; asm volatile("" : "+s"(probe_two));
;     ...
;     if (phmask & (1u << 0)) {
;     ...
;     for (int rep_ = 0; rep_ < 3; ++rep_)
;     ...
;     {
;         conv_w13(kin(6), kin(7), nullptr, ws, SCR_, F.lane, GW_, NGW);
.LBB0_13:
	s_or_b64 exec, exec, s[6:7]
	s_lshr_b32 s50, s3, 6
	s_cmp_lt_u32 s50, 4
	s_cbranch_scc1 .Lprio_lead
	s_setprio 1
.Lprio_lead:
	s_add_u32 s30, s22, 0x2080000
	s_addc_u32 s31, s23, 0
	s_lshl_b32 s76, s18, 3
	s_bitcmp0_b32 s74, 0
	v_and_b32_e32 v189, 63, v0
	s_cbranch_scc1 .LBB0_63
	s_mov_b64 s[10:11], s[0:1]
	s_mov_b64 s[6:7], s[0:1]
	s_load_dwordx2 s[8:9], s[6:7], 0x38
	s_lshl_b32 s3, s50, 14
	s_lshl_b32 s14, s33, 3
	s_add_i32 s3, s3, 0
	s_add_i32 s14, s14, s50
	s_add_u32 s6, s22, 0x1000000
	s_addc_u32 s7, s23, 0
	s_cmpk_gt_i32 s14, 0x57f
	v_lshrrev_b32_e32 v4, 5, v189
	v_and_b32_e32 v2, 31, v0
	v_lshrrev_b32_e32 v3, 3, v189
	v_lshlrev_b32_e32 v5, 3, v0
	s_cbranch_scc1 .LBB0_19
	s_load_dwordx2 s[10:11], s[10:11], 0x30
	v_lshlrev_b32_e32 v10, 2, v2
	v_mov_b32_e32 v11, 0
	v_and_b32_e32 v1, 56, v5
	v_add_u32_e32 v6, s3, v10
	s_waitcnt lgkmcnt(0)
	v_lshl_add_u64 v[8:9], s[10:11], 0, v[10:11]
	v_mul_u32_u24_e32 v7, 0x84, v1
	v_lshlrev_b32_e32 v10, 1, v1
	v_lshlrev_b32_e32 v1, 2, v3
	s_movk_i32 s12, 0x84
	v_lshl_add_u64 v[10:11], s[6:7], 0, v[10:11]
	v_add3_u32 v7, s3, v7, v1
	v_or_b32_e32 v14, 8, v3
	v_or_b32_e32 v15, 32, v3
	v_or_b32_e32 v16, 40, v3
	v_mov_b32_e32 v1, v4
	s_movk_i32 s13, 0x2c00
	s_mov_b32 s15, s14

; #define PG8_STAGE(bufoff, gbase, voff) do { _Pragma("unroll") for (int _i = 0; _i < 2; ++_i) \
;         __builtin_amdgcn_global_load_lds((const unsigned*)((const char*)(gbase) + (voff)[_i]), (PG8_LAS unsigned*)(lds + (bufoff) + ldsw + _i * 8192), 16, 0, 0); } while (0)
; #define PG8_LDA(dst, b, h) do { _Pragma("unroll") for (int m = 0; m < 4; ++m) _Pragma("unroll") for (int k = 0; k < 2; ++k) dst[m][k] = *(const PG8_LAS bf16x8*)(lds + PG8_SA(b, h) + aoff + m * 2048 + k * 1024); } while (0)
; #define PG8_LDB(dst, b, h) do { _Pragma("unroll") for (int n = 0; n < 2; ++n) _Pragma("unroll") for (int k = 0; k < 2; ++k) dst[n][k] = *(const PG8_LAS bf16x8*)(lds + PG8_SB(b, h) + boff + n * 2048 + k * 1024); } while (0)
; #define PG8_MMA(ai, bj, At, Bt) do { __builtin_amdgcn_s_setprio(1); _Pragma("unroll") for (int m = 0; m < 4; ++m) _Pragma("unroll") for (int n = 0; n < 2; ++n) _Pragma("unroll") for (int k = 0; k < 2; ++k) \
;         acc[ai][bj][m][n] = __builtin_amdgcn_mfma_f32_16x16x32_bf16(Bt[n][k], At[m][k], acc[ai][bj][m][n], 0, 0, 0); __builtin_amdgcn_s_setprio(0); } while (0)
; #define PG8_WAIT_V(n) asm volatile("s_waitcnt vmcnt(" #n ")" ::: "memory")
; #define PG8_BAR __builtin_amdgcn_s_barrier()
; template <class Epi, class Sched, bool ALIGN_EPI = false, bool SP2 = false>
; __device__ __forceinline__ void gemm_phase(PG8_LAS unsigned char* lds, const Gemm g, const Sched& S, const Epi& E) {
;     ...
;         for (int t = 0; t < nt; t += 2) {
;             const bool last = (t == nt - 2);
;             const char* a1 = cA + (size_t)(t + 1) * kstep;
;             const char* a2 = last ? nA : cA + (size_t)(t + 2) * kstep; const char* b2 = last ? nB : cB + (size_t)(t + 2) * kstep;
;             const char* a3 = a2 + kstep; const char* b3 = b2 + kstep;
;             if (last && has_next) S.a_ready(nxt);
;             if constexpr (SP2) {
;             PG8_LDB(B0, 0, 0); PG8_LDB(B1, 0, 1); PG8_SCHED; PG8_LDA(At, 0, 0); PG8_STAGE(PG8_SA(1, 1), a1 + hstep, voffA);
;             PG8_WAIT_V(8); PG8_WAIT_L(0); PG8_BAR; PG8_MMA(0, 0, At, B0); PG8_MMA(0, 1, At, B1); PG8_BAR; PG8_SCHED;
;             PG8_LDA(At, 0, 1); PG8_STAGE(PG8_SB(0, 0), b2, voffB); PG8_STAGE(PG8_SB(0, 1), b2 + hstep, voffB); PG8_STAGE(PG8_SA(0, 0), a2, voffA);
;             PG8_WAIT_V(8); PG8_WAIT_L(0); PG8_BAR; PG8_MMA(1, 0, At, B0); PG8_MMA(1, 1, At, B1); PG8_BAR; PG8_SCHED;
.LBB0_117:
	ds_read_b128 v[66:69], v220
	ds_read_b128 v[78:81], v220 offset:1024
	ds_read_b128 v[82:85], v220 offset:2048
	ds_read_b128 v[86:89], v220 offset:3072
	ds_read_b128 v[146:149], v221
	ds_read_b128 v[150:153], v221 offset:1024
	ds_read_b128 v[154:157], v221 offset:2048
	ds_read_b128 v[158:161], v221 offset:3072
	s_add_u32 s34, s12, 0xfff50080
	s_addc_u32 s35, s13, -1
	s_cmp_eq_u32 s86, 40
	s_cselect_b32 s61, s55, s35
	s_cselect_b32 s60, s54, s34
	s_cselect_b32 s59, s57, s85
	s_cselect_b32 s58, s56, s84
	v_lshl_add_u64 v[182:183], s[12:13], 0, v[190:191]
	s_add_i32 m0, s19, 0xc000
	ds_read_b128 v[162:165], v222
	ds_read_b128 v[166:169], v222 offset:1024
	ds_read_b128 v[170:173], v222 offset:2048
	ds_read_b128 v[174:177], v222 offset:3072
	ds_read_b128 v[178:181], v222 offset:4096
	ds_read_b128 v[198:201], v222 offset:5120
	ds_read_b128 v[202:205], v222 offset:6144
	ds_read_b128 v[206:209], v222 offset:7168
	global_load_lds_dwordx4 v[182:183], off
	v_lshl_add_u64 v[182:183], s[12:13], 0, v[192:193]
	s_add_i32 m0, s19, 0xe000
	s_nop 0
	global_load_lds_dwordx4 v[182:183], off
	s_waitcnt vmcnt(8)
	s_waitcnt lgkmcnt(0)
	s_barrier
	s_waitcnt lgkmcnt(0)
	v_mfma_f32_16x16x32_bf16 v[142:145], v[66:69], v[162:165], v[142:145]
	v_mfma_f32_16x16x32_bf16 v[138:141], v[82:85], v[162:165], v[138:141]
	v_mfma_f32_16x16x32_bf16 v[130:133], v[66:69], v[170:173], v[130:133]
	v_mfma_f32_16x16x32_bf16 v[122:125], v[82:85], v[170:173], v[122:125]
	v_mfma_f32_16x16x32_bf16 v[110:113], v[66:69], v[178:181], v[110:113]
	v_mfma_f32_16x16x32_bf16 v[106:109], v[82:85], v[178:181], v[106:109]
	v_mfma_f32_16x16x32_bf16 v[98:101], v[66:69], v[202:205], v[98:101]
	v_mfma_f32_16x16x32_bf16 v[90:93], v[82:85], v[202:205], v[90:93]
	v_mfma_f32_16x16x32_bf16 v[142:145], v[78:81], v[166:169], v[142:145]
	v_mfma_f32_16x16x32_bf16 v[138:141], v[86:89], v[166:169], v[138:141]
	v_mfma_f32_16x16x32_bf16 v[130:133], v[78:81], v[174:177], v[130:133]
	v_mfma_f32_16x16x32_bf16 v[122:125], v[86:89], v[174:177], v[122:125]
	v_mfma_f32_16x16x32_bf16 v[110:113], v[78:81], v[198:201], v[110:113]
	v_mfma_f32_16x16x32_bf16 v[106:109], v[86:89], v[198:201], v[106:109]
	v_mfma_f32_16x16x32_bf16 v[98:101], v[78:81], v[206:209], v[98:101]
	v_mfma_f32_16x16x32_bf16 v[90:93], v[86:89], v[206:209], v[90:93]
	v_mfma_f32_16x16x32_bf16 v[134:137], v[146:149], v[162:165], v[134:137]
	v_mfma_f32_16x16x32_bf16 v[126:129], v[154:157], v[162:165], v[126:129]
	v_mfma_f32_16x16x32_bf16 v[118:121], v[146:149], v[170:173], v[118:121]
	v_mfma_f32_16x16x32_bf16 v[114:117], v[154:157], v[170:173], v[114:117]
	v_mfma_f32_16x16x32_bf16 v[102:105], v[146:149], v[178:181], v[102:105]
	v_mfma_f32_16x16x32_bf16 v[94:97], v[154:157], v[178:181], v[94:97]
	v_mfma_f32_16x16x32_bf16 v[74:77], v[146:149], v[202:205], v[74:77]
	v_mfma_f32_16x16x32_bf16 v[70:73], v[154:157], v[202:205], v[70:73]
	v_mfma_f32_16x16x32_bf16 v[134:137], v[150:153], v[166:169], v[134:137]
	v_mfma_f32_16x16x32_bf16 v[126:129], v[158:161], v[166:169], v[126:129]
	v_mfma_f32_16x16x32_bf16 v[118:121], v[150:153], v[174:177], v[118:121]
	v_mfma_f32_16x16x32_bf16 v[114:117], v[158:161], v[174:177], v[114:117]
	v_mfma_f32_16x16x32_bf16 v[102:105], v[150:153], v[198:201], v[102:105]
	v_mfma_f32_16x16x32_bf16 v[94:97], v[158:161], v[198:201], v[94:97]
	v_mfma_f32_16x16x32_bf16 v[74:77], v[150:153], v[206:209], v[74:77]
	v_mfma_f32_16x16x32_bf16 v[70:73], v[158:161], v[206:209], v[70:73]
	s_barrier
	s_add_i32 s34, s73, s3
	v_lshl_add_u64 v[182:183], s[58:59], 0, v[184:185]
	s_mov_b32 m0, s34
	ds_read_b128 v[162:165], v222 offset:16384
	ds_read_b128 v[166:169], v222 offset:17408
	ds_read_b128 v[170:173], v222 offset:18432
	ds_read_b128 v[174:177], v222 offset:19456
	ds_read_b128 v[178:181], v222 offset:20480
	ds_read_b128 v[198:201], v222 offset:21504
	ds_read_b128 v[202:205], v222 offset:22528
	ds_read_b128 v[206:209], v222 offset:23552
	global_load_lds_dwordx4 v[182:183], off
	s_add_i32 m0, s34, 0x2000
	s_add_u32 s88, s58, 0xb0000
	v_lshl_add_u64 v[210:211], s[58:59], 0, v[186:187]
	s_addc_u32 s89, s59, 0
	s_add_i32 s34, s77, s3
	global_load_lds_dwordx4 v[210:211], off
	v_lshl_add_u64 v[212:213], s[88:89], 0, v[184:185]
	s_mov_b32 m0, s34
	v_lshl_add_u64 v[214:215], s[60:61], 0, v[186:187]
	global_load_lds_dwordx4 v[212:213], off
	v_lshl_add_u64 v[212:213], s[88:89], 0, v[186:187]
	s_add_i32 m0, s34, 0x2000
	s_nop 0
	global_load_lds_dwordx4 v[212:213], off
	v_lshl_add_u64 v[212:213], s[60:61], 0, v[184:185]
	s_mov_b32 m0, s19
	s_nop 0
	global_load_lds_dwordx4 v[212:213], off
	s_mov_b32 m0, s62
	s_nop 0
	global_load_lds_dwordx4 v[214:215], off
	s_waitcnt vmcnt(8)
	s_waitcnt lgkmcnt(0)
	s_barrier
; #define PG8_STAGE(bufoff, gbase, voff) do { _Pragma("unroll") for (int _i = 0; _i < 2; ++_i) \
;         __builtin_amdgcn_global_load_lds((const unsigned*)((const char*)(gbase) + (voff)[_i]), (PG8_LAS unsigned*)(lds + (bufoff) + ldsw + _i * 8192), 16, 0, 0); } while (0)
; #define PG8_LDA(dst, b, h) do { _Pragma("unroll") for (int m = 0; m < 4; ++m) _Pragma("unroll") for (int k = 0; k < 2; ++k) dst[m][k] = *(const PG8_LAS bf16x8*)(lds + PG8_SA(b, h) + aoff + m * 2048 + k * 1024); } while (0)
; #define PG8_LDB(dst, b, h) do { _Pragma("unroll") for (int n = 0; n < 2; ++n) _Pragma("unroll") for (int k = 0; k < 2; ++k) dst[n][k] = *(const PG8_LAS bf16x8*)(lds + PG8_SB(b, h) + boff + n * 2048 + k * 1024); } while (0)
; #define PG8_MMA(ai, bj, At, Bt) do { __builtin_amdgcn_s_setprio(1); _Pragma("unroll") for (int m = 0; m < 4; ++m) _Pragma("unroll") for (int n = 0; n < 2; ++n) _Pragma("unroll") for (int k = 0; k < 2; ++k) \
;         acc[ai][bj][m][n] = __builtin_amdgcn_mfma_f32_16x16x32_bf16(Bt[n][k], At[m][k], acc[ai][bj][m][n], 0, 0, 0); __builtin_amdgcn_s_setprio(0); } while (0)
; #define PG8_WAIT_V(n) asm volatile("s_waitcnt vmcnt(" #n ")" ::: "memory")
; #define PG8_WAIT_L(n) asm volatile("s_waitcnt lgkmcnt(" #n ")" ::: "memory")
; #define PG8_BAR __builtin_amdgcn_s_barrier()
; #define PG8_SCHED __builtin_amdgcn_sched_barrier(0)
; template <class Epi, class Sched, bool ALIGN_EPI = false, bool SP2 = false>
; __device__ __forceinline__ void gemm_phase(PG8_LAS unsigned char* lds, const Gemm g, const Sched& S, const Epi& E) {
;     ...
;             PG8_LDA(At, 0, 1); PG8_STAGE(PG8_SB(0, 0), b2, voffB); PG8_STAGE(PG8_SB(0, 1), b2 + hstep, voffB); PG8_STAGE(PG8_SA(0, 0), a2, voffA);
;             PG8_WAIT_V(8); PG8_WAIT_L(0); PG8_BAR; PG8_MMA(1, 0, At, B0); PG8_MMA(1, 1, At, B1); PG8_BAR; PG8_SCHED;
;             PG8_LDB(B0, 1, 0); PG8_LDB(B1, 1, 1); PG8_SCHED; PG8_LDA(At, 1, 0); PG8_STAGE(PG8_SA(0, 1), a2 + hstep, voffA);
;             PG8_WAIT_V(8); PG8_WAIT_L(0); PG8_BAR; PG8_MMA(0, 0, At, B0); PG8_MMA(0, 1, At, B1); PG8_BAR; PG8_SCHED;
;             PG8_LDA(At, 1, 1); PG8_STAGE(PG8_SB(1, 0), b3, voffB); PG8_STAGE(PG8_SB(1, 1), b3 + hstep, voffB); PG8_STAGE(PG8_SA(1, 0), a3, voffA);
	s_waitcnt lgkmcnt(0)
	v_mfma_f32_16x16x32_bf16 v[62:65], v[66:69], v[162:165], v[62:65]
	v_mfma_f32_16x16x32_bf16 v[58:61], v[82:85], v[162:165], v[58:61]
	v_mfma_f32_16x16x32_bf16 v[50:53], v[66:69], v[170:173], v[50:53]
	v_mfma_f32_16x16x32_bf16 v[42:45], v[82:85], v[170:173], v[42:45]
	v_mfma_f32_16x16x32_bf16 v[30:33], v[66:69], v[178:181], v[30:33]
	v_mfma_f32_16x16x32_bf16 v[26:29], v[82:85], v[178:181], v[26:29]
	v_mfma_f32_16x16x32_bf16 v[18:21], v[66:69], v[202:205], v[18:21]
	v_mfma_f32_16x16x32_bf16 v[10:13], v[82:85], v[202:205], v[10:13]
	v_mfma_f32_16x16x32_bf16 v[62:65], v[78:81], v[166:169], v[62:65]
	v_mfma_f32_16x16x32_bf16 v[58:61], v[86:89], v[166:169], v[58:61]
	v_mfma_f32_16x16x32_bf16 v[50:53], v[78:81], v[174:177], v[50:53]
	v_mfma_f32_16x16x32_bf16 v[42:45], v[86:89], v[174:177], v[42:45]
	v_mfma_f32_16x16x32_bf16 v[30:33], v[78:81], v[198:201], v[30:33]
	v_mfma_f32_16x16x32_bf16 v[26:29], v[86:89], v[198:201], v[26:29]
	v_mfma_f32_16x16x32_bf16 v[18:21], v[78:81], v[206:209], v[18:21]
	v_mfma_f32_16x16x32_bf16 v[10:13], v[86:89], v[206:209], v[10:13]
	v_mfma_f32_16x16x32_bf16 v[54:57], v[146:149], v[162:165], v[54:57]
	v_mfma_f32_16x16x32_bf16 v[46:49], v[154:157], v[162:165], v[46:49]
	v_mfma_f32_16x16x32_bf16 v[38:41], v[146:149], v[170:173], v[38:41]
	v_mfma_f32_16x16x32_bf16 v[34:37], v[154:157], v[170:173], v[34:37]
	v_mfma_f32_16x16x32_bf16 v[22:25], v[146:149], v[178:181], v[22:25]
	v_mfma_f32_16x16x32_bf16 v[14:17], v[154:157], v[178:181], v[14:17]
	v_mfma_f32_16x16x32_bf16 v[6:9], v[146:149], v[202:205], v[6:9]
	v_mfma_f32_16x16x32_bf16 v[2:5], v[154:157], v[202:205], v[2:5]
	v_mfma_f32_16x16x32_bf16 v[54:57], v[150:153], v[166:169], v[54:57]
	v_mfma_f32_16x16x32_bf16 v[46:49], v[158:161], v[166:169], v[46:49]
	v_mfma_f32_16x16x32_bf16 v[38:41], v[150:153], v[174:177], v[38:41]
	v_mfma_f32_16x16x32_bf16 v[34:37], v[158:161], v[174:177], v[34:37]
	v_mfma_f32_16x16x32_bf16 v[22:25], v[150:153], v[198:201], v[22:25]
	v_mfma_f32_16x16x32_bf16 v[14:17], v[158:161], v[198:201], v[14:17]
	v_mfma_f32_16x16x32_bf16 v[6:9], v[150:153], v[206:209], v[6:9]
	v_mfma_f32_16x16x32_bf16 v[2:5], v[158:161], v[206:209], v[2:5]
	s_barrier
	s_add_i32 s34, 0, 0x18000
	s_add_i32 s35, 0, 0x1c000
	v_add_u32_e32 v86, s34, v216
	v_add_u32_e32 v158, s35, v216
	ds_read_b128 v[66:69], v86
	ds_read_b128 v[78:81], v86 offset:1024
	ds_read_b128 v[82:85], v86 offset:2048
	ds_read_b128 v[86:89], v86 offset:3072
	ds_read_b128 v[146:149], v158
	ds_read_b128 v[150:153], v158 offset:1024
	ds_read_b128 v[154:157], v158 offset:2048
	ds_read_b128 v[158:161], v158 offset:3072
	s_add_u32 s60, s60, 0xb0000
	s_addc_u32 s61, s61, 0
	s_mov_b32 m0, s63
	v_lshl_add_u64 v[224:225], s[60:61], 0, v[184:185]
	ds_read_b128 v[162:165], v222 offset:32768
	ds_read_b128 v[166:169], v222 offset:33792
	ds_read_b128 v[170:173], v222 offset:34816
	ds_read_b128 v[174:177], v222 offset:35840
	ds_read_b128 v[178:181], v222 offset:36864
	ds_read_b128 v[198:201], v222 offset:37888
	ds_read_b128 v[202:205], v222 offset:38912
	ds_read_b128 v[206:209], v222 offset:39936
	global_load_lds_dwordx4 v[224:225], off
	v_lshl_add_u64 v[224:225], s[60:61], 0, v[186:187]
	s_mov_b32 m0, s64
	s_nop 0
	global_load_lds_dwordx4 v[224:225], off
	s_waitcnt vmcnt(8)
	s_waitcnt lgkmcnt(0)
	s_barrier
	s_waitcnt lgkmcnt(0)
	v_mfma_f32_16x16x32_bf16 v[142:145], v[66:69], v[162:165], v[142:145]
	v_mfma_f32_16x16x32_bf16 v[138:141], v[82:85], v[162:165], v[138:141]
	v_mfma_f32_16x16x32_bf16 v[130:133], v[66:69], v[170:173], v[130:133]
	v_mfma_f32_16x16x32_bf16 v[122:125], v[82:85], v[170:173], v[122:125]
	v_mfma_f32_16x16x32_bf16 v[110:113], v[66:69], v[178:181], v[110:113]
	v_mfma_f32_16x16x32_bf16 v[106:109], v[82:85], v[178:181], v[106:109]
	v_mfma_f32_16x16x32_bf16 v[98:101], v[66:69], v[202:205], v[98:101]
	v_mfma_f32_16x16x32_bf16 v[90:93], v[82:85], v[202:205], v[90:93]
	v_mfma_f32_16x16x32_bf16 v[142:145], v[78:81], v[166:169], v[142:145]
	v_mfma_f32_16x16x32_bf16 v[138:141], v[86:89], v[166:169], v[138:141]
	v_mfma_f32_16x16x32_bf16 v[130:133], v[78:81], v[174:177], v[130:133]
	v_mfma_f32_16x16x32_bf16 v[122:125], v[86:89], v[174:177], v[122:125]
	v_mfma_f32_16x16x32_bf16 v[110:113], v[78:81], v[198:201], v[110:113]
	v_mfma_f32_16x16x32_bf16 v[106:109], v[86:89], v[198:201], v[106:109]
	v_mfma_f32_16x16x32_bf16 v[98:101], v[78:81], v[206:209], v[98:101]
	v_mfma_f32_16x16x32_bf16 v[90:93], v[86:89], v[206:209], v[90:93]
	v_mfma_f32_16x16x32_bf16 v[134:137], v[146:149], v[162:165], v[134:137]
	v_mfma_f32_16x16x32_bf16 v[126:129], v[154:157], v[162:165], v[126:129]
	v_mfma_f32_16x16x32_bf16 v[118:121], v[146:149], v[170:173], v[118:121]
	v_mfma_f32_16x16x32_bf16 v[114:117], v[154:157], v[170:173], v[114:117]
	v_mfma_f32_16x16x32_bf16 v[102:105], v[146:149], v[178:181], v[102:105]
	v_mfma_f32_16x16x32_bf16 v[94:97], v[154:157], v[178:181], v[94:97]
	v_mfma_f32_16x16x32_bf16 v[74:77], v[146:149], v[202:205], v[74:77]
	v_mfma_f32_16x16x32_bf16 v[70:73], v[154:157], v[202:205], v[70:73]
	v_mfma_f32_16x16x32_bf16 v[134:137], v[150:153], v[166:169], v[134:137]
	v_mfma_f32_16x16x32_bf16 v[126:129], v[158:161], v[166:169], v[126:129]
	v_mfma_f32_16x16x32_bf16 v[118:121], v[150:153], v[174:177], v[118:121]
	v_mfma_f32_16x16x32_bf16 v[114:117], v[158:161], v[174:177], v[114:117]
	v_mfma_f32_16x16x32_bf16 v[102:105], v[150:153], v[198:201], v[102:105]
	v_mfma_f32_16x16x32_bf16 v[94:97], v[158:161], v[198:201], v[94:97]
	v_mfma_f32_16x16x32_bf16 v[74:77], v[150:153], v[206:209], v[74:77]
	v_mfma_f32_16x16x32_bf16 v[70:73], v[158:161], v[206:209], v[70:73]
	s_barrier
; #define PG8_STAGE(bufoff, gbase, voff) do { _Pragma("unroll") for (int _i = 0; _i < 2; ++_i) \
;         __builtin_amdgcn_global_load_lds((const unsigned*)((const char*)(gbase) + (voff)[_i]), (PG8_LAS unsigned*)(lds + (bufoff) + ldsw + _i * 8192), 16, 0, 0); } while (0)
; #define PG8_LDA(dst, b, h) do { _Pragma("unroll") for (int m = 0; m < 4; ++m) _Pragma("unroll") for (int k = 0; k < 2; ++k) dst[m][k] = *(const PG8_LAS bf16x8*)(lds + PG8_SA(b, h) + aoff + m * 2048 + k * 1024); } while (0)
; #define PG8_MMA(ai, bj, At, Bt) do { __builtin_amdgcn_s_setprio(1); _Pragma("unroll") for (int m = 0; m < 4; ++m) _Pragma("unroll") for (int n = 0; n < 2; ++n) _Pragma("unroll") for (int k = 0; k < 2; ++k) \
;         acc[ai][bj][m][n] = __builtin_amdgcn_mfma_f32_16x16x32_bf16(Bt[n][k], At[m][k], acc[ai][bj][m][n], 0, 0, 0); __builtin_amdgcn_s_setprio(0); } while (0)
; #define PG8_WAIT_V(n) asm volatile("s_waitcnt vmcnt(" #n ")" ::: "memory")
; #define PG8_WAIT_L(n) asm volatile("s_waitcnt lgkmcnt(" #n ")" ::: "memory")
; #define PG8_BAR __builtin_amdgcn_s_barrier()
; #define PG8_SCHED __builtin_amdgcn_sched_barrier(0)
; template <class Epi, class Sched, bool ALIGN_EPI = false, bool SP2 = false>
; __device__ __forceinline__ void gemm_phase(PG8_LAS unsigned char* lds, const Gemm g, const Sched& S, const Epi& E) {
;     ...
;             PG8_LDA(At, 1, 1); PG8_STAGE(PG8_SB(1, 0), b3, voffB); PG8_STAGE(PG8_SB(1, 1), b3 + hstep, voffB); PG8_STAGE(PG8_SA(1, 0), a3, voffA);
;             PG8_WAIT_V(8); PG8_WAIT_L(0); PG8_BAR; PG8_MMA(1, 0, At, B0); PG8_MMA(1, 1, At, B1); PG8_BAR; PG8_SCHED;
	s_add_i32 s34, s34, s3
	v_lshl_add_u64 v[182:183], v[182:183], 0, s[48:49]
	s_mov_b32 m0, s34
	ds_read_b128 v[162:165], v222 offset:49152
	ds_read_b128 v[166:169], v222 offset:50176
	ds_read_b128 v[170:173], v222 offset:51200
	ds_read_b128 v[174:177], v222 offset:52224
	ds_read_b128 v[178:181], v222 offset:53248
	ds_read_b128 v[198:201], v222 offset:54272
	ds_read_b128 v[202:205], v222 offset:55296
	ds_read_b128 v[206:209], v222 offset:56320
	global_load_lds_dwordx4 v[182:183], off
	s_add_i32 m0, s34, 0x2000
	s_add_u32 s58, s58, 0xb0080
	v_lshl_add_u64 v[182:183], v[210:211], 0, s[48:49]
	s_addc_u32 s59, s59, 0
	s_add_i32 s34, s35, s3
	global_load_lds_dwordx4 v[182:183], off
	v_lshl_add_u64 v[182:183], s[58:59], 0, v[184:185]
	s_mov_b32 m0, s34
	s_nop 0
	global_load_lds_dwordx4 v[182:183], off
	v_lshl_add_u64 v[182:183], s[58:59], 0, v[186:187]
	s_add_i32 m0, s34, 0x2000
	s_nop 0
	global_load_lds_dwordx4 v[182:183], off
	v_lshl_add_u64 v[182:183], v[212:213], 0, s[48:49]
	s_mov_b32 m0, s67
	s_nop 0
	global_load_lds_dwordx4 v[182:183], off
	v_lshl_add_u64 v[182:183], v[214:215], 0, s[48:49]
	s_mov_b32 m0, s68
	s_nop 0
	global_load_lds_dwordx4 v[182:183], off
	s_waitcnt vmcnt(8)
	s_waitcnt lgkmcnt(0)
	s_barrier
	s_waitcnt lgkmcnt(0)
	v_mfma_f32_16x16x32_bf16 v[62:65], v[66:69], v[162:165], v[62:65]
	v_mfma_f32_16x16x32_bf16 v[58:61], v[82:85], v[162:165], v[58:61]
	v_mfma_f32_16x16x32_bf16 v[50:53], v[66:69], v[170:173], v[50:53]
	v_mfma_f32_16x16x32_bf16 v[42:45], v[82:85], v[170:173], v[42:45]
	v_mfma_f32_16x16x32_bf16 v[30:33], v[66:69], v[178:181], v[30:33]
	v_mfma_f32_16x16x32_bf16 v[26:29], v[82:85], v[178:181], v[26:29]
	v_mfma_f32_16x16x32_bf16 v[18:21], v[66:69], v[202:205], v[18:21]
	v_mfma_f32_16x16x32_bf16 v[10:13], v[82:85], v[202:205], v[10:13]
	v_mfma_f32_16x16x32_bf16 v[62:65], v[78:81], v[166:169], v[62:65]
	v_mfma_f32_16x16x32_bf16 v[58:61], v[86:89], v[166:169], v[58:61]
	v_mfma_f32_16x16x32_bf16 v[50:53], v[78:81], v[174:177], v[50:53]
	v_mfma_f32_16x16x32_bf16 v[42:45], v[86:89], v[174:177], v[42:45]
	v_mfma_f32_16x16x32_bf16 v[30:33], v[78:81], v[198:201], v[30:33]
	v_mfma_f32_16x16x32_bf16 v[26:29], v[86:89], v[198:201], v[26:29]
	v_mfma_f32_16x16x32_bf16 v[18:21], v[78:81], v[206:209], v[18:21]
	v_mfma_f32_16x16x32_bf16 v[10:13], v[86:89], v[206:209], v[10:13]
	v_mfma_f32_16x16x32_bf16 v[54:57], v[146:149], v[162:165], v[54:57]
	v_mfma_f32_16x16x32_bf16 v[46:49], v[154:157], v[162:165], v[46:49]
	v_mfma_f32_16x16x32_bf16 v[38:41], v[146:149], v[170:173], v[38:41]
	v_mfma_f32_16x16x32_bf16 v[34:37], v[154:157], v[170:173], v[34:37]
	v_mfma_f32_16x16x32_bf16 v[22:25], v[146:149], v[178:181], v[22:25]
	v_mfma_f32_16x16x32_bf16 v[14:17], v[154:157], v[178:181], v[14:17]
	v_mfma_f32_16x16x32_bf16 v[6:9], v[146:149], v[202:205], v[6:9]
	v_mfma_f32_16x16x32_bf16 v[2:5], v[154:157], v[202:205], v[2:5]
	v_mfma_f32_16x16x32_bf16 v[54:57], v[150:153], v[166:169], v[54:57]
	v_mfma_f32_16x16x32_bf16 v[46:49], v[158:161], v[166:169], v[46:49]
	v_mfma_f32_16x16x32_bf16 v[38:41], v[150:153], v[174:177], v[38:41]
	v_mfma_f32_16x16x32_bf16 v[34:37], v[158:161], v[174:177], v[34:37]
	v_mfma_f32_16x16x32_bf16 v[22:25], v[150:153], v[198:201], v[22:25]
	v_mfma_f32_16x16x32_bf16 v[14:17], v[158:161], v[198:201], v[14:17]
	v_mfma_f32_16x16x32_bf16 v[6:9], v[150:153], v[206:209], v[6:9]
	v_mfma_f32_16x16x32_bf16 v[2:5], v[158:161], v[206:209], v[2:5]
	s_barrier
	s_add_i32 s86, s86, 2
	s_add_u32 s12, s12, 0x100
	s_addc_u32 s13, s13, 0
	s_add_u32 s84, s84, 0x100
	s_addc_u32 s85, s85, 0
	s_cmp_gt_u32 s86, 41
	s_cbranch_scc0 .LBB0_117
	s_and_b64 vcc, exec, s[50:51]
	s_cbranch_vccz .LBB0_120
	s_barrier

; #define PG8_STAGE(bufoff, gbase, voff) do { _Pragma("unroll") for (int _i = 0; _i < 2; ++_i) \
;         __builtin_amdgcn_global_load_lds((const unsigned*)((const char*)(gbase) + (voff)[_i]), (PG8_LAS unsigned*)(lds + (bufoff) + ldsw + _i * 8192), 16, 0, 0); } while (0)
; #define PG8_LDA(dst, b, h) do { _Pragma("unroll") for (int m = 0; m < 4; ++m) _Pragma("unroll") for (int k = 0; k < 2; ++k) dst[m][k] = *(const PG8_LAS bf16x8*)(lds + PG8_SA(b, h) + aoff + m * 2048 + k * 1024); } while (0)
; #define PG8_LDB(dst, b, h) do { _Pragma("unroll") for (int n = 0; n < 2; ++n) _Pragma("unroll") for (int k = 0; k < 2; ++k) dst[n][k] = *(const PG8_LAS bf16x8*)(lds + PG8_SB(b, h) + boff + n * 2048 + k * 1024); } while (0)
; #define PG8_MMA(ai, bj, At, Bt) do { __builtin_amdgcn_s_setprio(1); _Pragma("unroll") for (int m = 0; m < 4; ++m) _Pragma("unroll") for (int n = 0; n < 2; ++n) _Pragma("unroll") for (int k = 0; k < 2; ++k) \
;         acc[ai][bj][m][n] = __builtin_amdgcn_mfma_f32_16x16x32_bf16(Bt[n][k], At[m][k], acc[ai][bj][m][n], 0, 0, 0); __builtin_amdgcn_s_setprio(0); } while (0)
; #define PG8_WAIT_V(n) asm volatile("s_waitcnt vmcnt(" #n ")" ::: "memory")
; #define PG8_BAR __builtin_amdgcn_s_barrier()
; template <class Epi, class Sched, bool ALIGN_EPI = false, bool SP2 = false>
; __device__ __forceinline__ void gemm_phase(PG8_LAS unsigned char* lds, const Gemm g, const Sched& S, const Epi& E) {
;     ...
;         for (int t = 0; t < nt; t += 2) {
;             const bool last = (t == nt - 2);
;             const char* a1 = cA + (size_t)(t + 1) * kstep;
;             const char* a2 = last ? nA : cA + (size_t)(t + 2) * kstep; const char* b2 = last ? nB : cB + (size_t)(t + 2) * kstep;
;             const char* a3 = a2 + kstep; const char* b3 = b2 + kstep;
;             if (last && has_next) S.a_ready(nxt);
;             if constexpr (SP2) {
;             PG8_LDB(B0, 0, 0); PG8_LDB(B1, 0, 1); PG8_SCHED; PG8_LDA(At, 0, 0); PG8_STAGE(PG8_SA(1, 1), a1 + hstep, voffA);
;             PG8_WAIT_V(8); PG8_WAIT_L(0); PG8_BAR; PG8_MMA(0, 0, At, B0); PG8_MMA(0, 1, At, B1); PG8_BAR; PG8_SCHED;
;             PG8_LDA(At, 0, 1); PG8_STAGE(PG8_SB(0, 0), b2, voffB); PG8_STAGE(PG8_SB(0, 1), b2 + hstep, voffB); PG8_STAGE(PG8_SA(0, 0), a2, voffA);
;             PG8_WAIT_V(8); PG8_WAIT_L(0); PG8_BAR; PG8_MMA(1, 0, At, B0); PG8_MMA(1, 1, At, B1); PG8_BAR; PG8_SCHED;
.LBB0_228:
	ds_read_b128 v[66:69], v220
	ds_read_b128 v[78:81], v220 offset:1024
	ds_read_b128 v[82:85], v220 offset:2048
	ds_read_b128 v[86:89], v220 offset:3072
	ds_read_b128 v[146:149], v221
	ds_read_b128 v[150:153], v221 offset:1024
	ds_read_b128 v[154:157], v221 offset:2048
	ds_read_b128 v[158:161], v221 offset:3072
	s_add_u32 s34, s12, 0xfff50080
	s_addc_u32 s35, s13, -1
	s_cmp_eq_u32 s84, 40
	s_cselect_b32 s59, s43, s35
	s_cselect_b32 s58, s42, s34
	s_cselect_b32 s57, s55, s83
	s_cselect_b32 s56, s54, s82
	v_lshl_add_u64 v[182:183], s[12:13], 0, v[190:191]
	s_add_i32 m0, s19, 0xc000
	ds_read_b128 v[162:165], v222
	ds_read_b128 v[166:169], v222 offset:1024
	ds_read_b128 v[170:173], v222 offset:2048
	ds_read_b128 v[174:177], v222 offset:3072
	ds_read_b128 v[178:181], v222 offset:4096
	ds_read_b128 v[198:201], v222 offset:5120
	ds_read_b128 v[202:205], v222 offset:6144
	ds_read_b128 v[206:209], v222 offset:7168
	global_load_lds_dwordx4 v[182:183], off
	v_lshl_add_u64 v[182:183], s[12:13], 0, v[192:193]
	s_add_i32 m0, s19, 0xe000
	s_nop 0
	global_load_lds_dwordx4 v[182:183], off
	s_waitcnt vmcnt(8)
	s_waitcnt lgkmcnt(0)
	s_barrier
	s_waitcnt lgkmcnt(0)
	v_mfma_f32_16x16x32_bf16 v[142:145], v[66:69], v[162:165], v[142:145]
	v_mfma_f32_16x16x32_bf16 v[138:141], v[82:85], v[162:165], v[138:141]
	v_mfma_f32_16x16x32_bf16 v[130:133], v[66:69], v[170:173], v[130:133]
	v_mfma_f32_16x16x32_bf16 v[122:125], v[82:85], v[170:173], v[122:125]
	v_mfma_f32_16x16x32_bf16 v[110:113], v[66:69], v[178:181], v[110:113]
	v_mfma_f32_16x16x32_bf16 v[106:109], v[82:85], v[178:181], v[106:109]
	v_mfma_f32_16x16x32_bf16 v[98:101], v[66:69], v[202:205], v[98:101]
	v_mfma_f32_16x16x32_bf16 v[90:93], v[82:85], v[202:205], v[90:93]
	v_mfma_f32_16x16x32_bf16 v[142:145], v[78:81], v[166:169], v[142:145]
	v_mfma_f32_16x16x32_bf16 v[138:141], v[86:89], v[166:169], v[138:141]
	v_mfma_f32_16x16x32_bf16 v[130:133], v[78:81], v[174:177], v[130:133]
	v_mfma_f32_16x16x32_bf16 v[122:125], v[86:89], v[174:177], v[122:125]
	v_mfma_f32_16x16x32_bf16 v[110:113], v[78:81], v[198:201], v[110:113]
	v_mfma_f32_16x16x32_bf16 v[106:109], v[86:89], v[198:201], v[106:109]
	v_mfma_f32_16x16x32_bf16 v[98:101], v[78:81], v[206:209], v[98:101]
	v_mfma_f32_16x16x32_bf16 v[90:93], v[86:89], v[206:209], v[90:93]
	v_mfma_f32_16x16x32_bf16 v[134:137], v[146:149], v[162:165], v[134:137]
	v_mfma_f32_16x16x32_bf16 v[126:129], v[154:157], v[162:165], v[126:129]
	v_mfma_f32_16x16x32_bf16 v[118:121], v[146:149], v[170:173], v[118:121]
	v_mfma_f32_16x16x32_bf16 v[114:117], v[154:157], v[170:173], v[114:117]
	v_mfma_f32_16x16x32_bf16 v[102:105], v[146:149], v[178:181], v[102:105]
	v_mfma_f32_16x16x32_bf16 v[94:97], v[154:157], v[178:181], v[94:97]
	v_mfma_f32_16x16x32_bf16 v[74:77], v[146:149], v[202:205], v[74:77]
	v_mfma_f32_16x16x32_bf16 v[70:73], v[154:157], v[202:205], v[70:73]
	v_mfma_f32_16x16x32_bf16 v[134:137], v[150:153], v[166:169], v[134:137]
	v_mfma_f32_16x16x32_bf16 v[126:129], v[158:161], v[166:169], v[126:129]
	v_mfma_f32_16x16x32_bf16 v[118:121], v[150:153], v[174:177], v[118:121]
	v_mfma_f32_16x16x32_bf16 v[114:117], v[158:161], v[174:177], v[114:117]
	v_mfma_f32_16x16x32_bf16 v[102:105], v[150:153], v[198:201], v[102:105]
	v_mfma_f32_16x16x32_bf16 v[94:97], v[158:161], v[198:201], v[94:97]
	v_mfma_f32_16x16x32_bf16 v[74:77], v[150:153], v[206:209], v[74:77]
	v_mfma_f32_16x16x32_bf16 v[70:73], v[158:161], v[206:209], v[70:73]
	s_barrier
	s_add_i32 s34, s71, s3
	v_lshl_add_u64 v[182:183], s[56:57], 0, v[184:185]
	s_mov_b32 m0, s34
	ds_read_b128 v[162:165], v222 offset:16384
	ds_read_b128 v[166:169], v222 offset:17408
	ds_read_b128 v[170:173], v222 offset:18432
	ds_read_b128 v[174:177], v222 offset:19456
	ds_read_b128 v[178:181], v222 offset:20480
	ds_read_b128 v[198:201], v222 offset:21504
	ds_read_b128 v[202:205], v222 offset:22528
	ds_read_b128 v[206:209], v222 offset:23552
	global_load_lds_dwordx4 v[182:183], off
	s_add_i32 m0, s34, 0x2000
	s_add_u32 s86, s56, 0xb0000
	v_lshl_add_u64 v[210:211], s[56:57], 0, v[186:187]
	s_addc_u32 s87, s57, 0
	s_add_i32 s34, s72, s3
	global_load_lds_dwordx4 v[210:211], off
	v_lshl_add_u64 v[212:213], s[86:87], 0, v[184:185]
	s_mov_b32 m0, s34
	v_lshl_add_u64 v[214:215], s[58:59], 0, v[186:187]
	global_load_lds_dwordx4 v[212:213], off
	v_lshl_add_u64 v[212:213], s[86:87], 0, v[186:187]
	s_add_i32 m0, s34, 0x2000
	s_nop 0
	global_load_lds_dwordx4 v[212:213], off
	v_lshl_add_u64 v[212:213], s[58:59], 0, v[184:185]
	s_mov_b32 m0, s19
	s_nop 0
	global_load_lds_dwordx4 v[212:213], off
	s_mov_b32 m0, s60
	s_nop 0
	global_load_lds_dwordx4 v[214:215], off
	s_waitcnt vmcnt(8)
	s_waitcnt lgkmcnt(0)
	s_barrier
; #define PG8_STAGE(bufoff, gbase, voff) do { _Pragma("unroll") for (int _i = 0; _i < 2; ++_i) \
;         __builtin_amdgcn_global_load_lds((const unsigned*)((const char*)(gbase) + (voff)[_i]), (PG8_LAS unsigned*)(lds + (bufoff) + ldsw + _i * 8192), 16, 0, 0); } while (0)
; #define PG8_LDA(dst, b, h) do { _Pragma("unroll") for (int m = 0; m < 4; ++m) _Pragma("unroll") for (int k = 0; k < 2; ++k) dst[m][k] = *(const PG8_LAS bf16x8*)(lds + PG8_SA(b, h) + aoff + m * 2048 + k * 1024); } while (0)
; #define PG8_LDB(dst, b, h) do { _Pragma("unroll") for (int n = 0; n < 2; ++n) _Pragma("unroll") for (int k = 0; k < 2; ++k) dst[n][k] = *(const PG8_LAS bf16x8*)(lds + PG8_SB(b, h) + boff + n * 2048 + k * 1024); } while (0)
; #define PG8_MMA(ai, bj, At, Bt) do { __builtin_amdgcn_s_setprio(1); _Pragma("unroll") for (int m = 0; m < 4; ++m) _Pragma("unroll") for (int n = 0; n < 2; ++n) _Pragma("unroll") for (int k = 0; k < 2; ++k) \
;         acc[ai][bj][m][n] = __builtin_amdgcn_mfma_f32_16x16x32_bf16(Bt[n][k], At[m][k], acc[ai][bj][m][n], 0, 0, 0); __builtin_amdgcn_s_setprio(0); } while (0)
; #define PG8_WAIT_V(n) asm volatile("s_waitcnt vmcnt(" #n ")" ::: "memory")
; #define PG8_WAIT_L(n) asm volatile("s_waitcnt lgkmcnt(" #n ")" ::: "memory")
; #define PG8_BAR __builtin_amdgcn_s_barrier()
; #define PG8_SCHED __builtin_amdgcn_sched_barrier(0)
; template <class Epi, class Sched, bool ALIGN_EPI = false, bool SP2 = false>
; __device__ __forceinline__ void gemm_phase(PG8_LAS unsigned char* lds, const Gemm g, const Sched& S, const Epi& E) {
;     ...
;             PG8_LDA(At, 0, 1); PG8_STAGE(PG8_SB(0, 0), b2, voffB); PG8_STAGE(PG8_SB(0, 1), b2 + hstep, voffB); PG8_STAGE(PG8_SA(0, 0), a2, voffA);
;             PG8_WAIT_V(8); PG8_WAIT_L(0); PG8_BAR; PG8_MMA(1, 0, At, B0); PG8_MMA(1, 1, At, B1); PG8_BAR; PG8_SCHED;
;             PG8_LDB(B0, 1, 0); PG8_LDB(B1, 1, 1); PG8_SCHED; PG8_LDA(At, 1, 0); PG8_STAGE(PG8_SA(0, 1), a2 + hstep, voffA);
;             PG8_WAIT_V(8); PG8_WAIT_L(0); PG8_BAR; PG8_MMA(0, 0, At, B0); PG8_MMA(0, 1, At, B1); PG8_BAR; PG8_SCHED;
;             PG8_LDA(At, 1, 1); PG8_STAGE(PG8_SB(1, 0), b3, voffB); PG8_STAGE(PG8_SB(1, 1), b3 + hstep, voffB); PG8_STAGE(PG8_SA(1, 0), a3, voffA);
	s_waitcnt lgkmcnt(0)
	v_mfma_f32_16x16x32_bf16 v[62:65], v[66:69], v[162:165], v[62:65]
	v_mfma_f32_16x16x32_bf16 v[58:61], v[82:85], v[162:165], v[58:61]
	v_mfma_f32_16x16x32_bf16 v[50:53], v[66:69], v[170:173], v[50:53]
	v_mfma_f32_16x16x32_bf16 v[42:45], v[82:85], v[170:173], v[42:45]
	v_mfma_f32_16x16x32_bf16 v[30:33], v[66:69], v[178:181], v[30:33]
	v_mfma_f32_16x16x32_bf16 v[26:29], v[82:85], v[178:181], v[26:29]
	v_mfma_f32_16x16x32_bf16 v[18:21], v[66:69], v[202:205], v[18:21]
	v_mfma_f32_16x16x32_bf16 v[10:13], v[82:85], v[202:205], v[10:13]
	v_mfma_f32_16x16x32_bf16 v[62:65], v[78:81], v[166:169], v[62:65]
	v_mfma_f32_16x16x32_bf16 v[58:61], v[86:89], v[166:169], v[58:61]
	v_mfma_f32_16x16x32_bf16 v[50:53], v[78:81], v[174:177], v[50:53]
	v_mfma_f32_16x16x32_bf16 v[42:45], v[86:89], v[174:177], v[42:45]
	v_mfma_f32_16x16x32_bf16 v[30:33], v[78:81], v[198:201], v[30:33]
	v_mfma_f32_16x16x32_bf16 v[26:29], v[86:89], v[198:201], v[26:29]
	v_mfma_f32_16x16x32_bf16 v[18:21], v[78:81], v[206:209], v[18:21]
	v_mfma_f32_16x16x32_bf16 v[10:13], v[86:89], v[206:209], v[10:13]
	v_mfma_f32_16x16x32_bf16 v[54:57], v[146:149], v[162:165], v[54:57]
	v_mfma_f32_16x16x32_bf16 v[46:49], v[154:157], v[162:165], v[46:49]
	v_mfma_f32_16x16x32_bf16 v[38:41], v[146:149], v[170:173], v[38:41]
	v_mfma_f32_16x16x32_bf16 v[34:37], v[154:157], v[170:173], v[34:37]
	v_mfma_f32_16x16x32_bf16 v[22:25], v[146:149], v[178:181], v[22:25]
	v_mfma_f32_16x16x32_bf16 v[14:17], v[154:157], v[178:181], v[14:17]
	v_mfma_f32_16x16x32_bf16 v[6:9], v[146:149], v[202:205], v[6:9]
	v_mfma_f32_16x16x32_bf16 v[2:5], v[154:157], v[202:205], v[2:5]
	v_mfma_f32_16x16x32_bf16 v[54:57], v[150:153], v[166:169], v[54:57]
	v_mfma_f32_16x16x32_bf16 v[46:49], v[158:161], v[166:169], v[46:49]
	v_mfma_f32_16x16x32_bf16 v[38:41], v[150:153], v[174:177], v[38:41]
	v_mfma_f32_16x16x32_bf16 v[34:37], v[158:161], v[174:177], v[34:37]
	v_mfma_f32_16x16x32_bf16 v[22:25], v[150:153], v[198:201], v[22:25]
	v_mfma_f32_16x16x32_bf16 v[14:17], v[158:161], v[198:201], v[14:17]
	v_mfma_f32_16x16x32_bf16 v[6:9], v[150:153], v[206:209], v[6:9]
	v_mfma_f32_16x16x32_bf16 v[2:5], v[158:161], v[206:209], v[2:5]
	s_barrier
	s_add_i32 s34, 0, 0x18000
	s_add_i32 s35, 0, 0x1c000
	v_add_u32_e32 v86, s34, v216
	v_add_u32_e32 v158, s35, v216
	ds_read_b128 v[66:69], v86
	ds_read_b128 v[78:81], v86 offset:1024
	ds_read_b128 v[82:85], v86 offset:2048
	ds_read_b128 v[86:89], v86 offset:3072
	ds_read_b128 v[146:149], v158
	ds_read_b128 v[150:153], v158 offset:1024
	ds_read_b128 v[154:157], v158 offset:2048
	ds_read_b128 v[158:161], v158 offset:3072
	s_add_u32 s58, s58, 0xb0000
	s_addc_u32 s59, s59, 0
	s_mov_b32 m0, s61
	v_lshl_add_u64 v[224:225], s[58:59], 0, v[184:185]
	ds_read_b128 v[162:165], v222 offset:32768
	ds_read_b128 v[166:169], v222 offset:33792
	ds_read_b128 v[170:173], v222 offset:34816
	ds_read_b128 v[174:177], v222 offset:35840
	ds_read_b128 v[178:181], v222 offset:36864
	ds_read_b128 v[198:201], v222 offset:37888
	ds_read_b128 v[202:205], v222 offset:38912
	ds_read_b128 v[206:209], v222 offset:39936
	global_load_lds_dwordx4 v[224:225], off
	v_lshl_add_u64 v[224:225], s[58:59], 0, v[186:187]
	s_mov_b32 m0, s62
	s_nop 0
	global_load_lds_dwordx4 v[224:225], off
	s_waitcnt vmcnt(8)
	s_waitcnt lgkmcnt(0)
	s_barrier
	s_waitcnt lgkmcnt(0)
	v_mfma_f32_16x16x32_bf16 v[142:145], v[66:69], v[162:165], v[142:145]
	v_mfma_f32_16x16x32_bf16 v[138:141], v[82:85], v[162:165], v[138:141]
	v_mfma_f32_16x16x32_bf16 v[130:133], v[66:69], v[170:173], v[130:133]
	v_mfma_f32_16x16x32_bf16 v[122:125], v[82:85], v[170:173], v[122:125]
	v_mfma_f32_16x16x32_bf16 v[110:113], v[66:69], v[178:181], v[110:113]
	v_mfma_f32_16x16x32_bf16 v[106:109], v[82:85], v[178:181], v[106:109]
	v_mfma_f32_16x16x32_bf16 v[98:101], v[66:69], v[202:205], v[98:101]
	v_mfma_f32_16x16x32_bf16 v[90:93], v[82:85], v[202:205], v[90:93]
	v_mfma_f32_16x16x32_bf16 v[142:145], v[78:81], v[166:169], v[142:145]
	v_mfma_f32_16x16x32_bf16 v[138:141], v[86:89], v[166:169], v[138:141]
	v_mfma_f32_16x16x32_bf16 v[130:133], v[78:81], v[174:177], v[130:133]
	v_mfma_f32_16x16x32_bf16 v[122:125], v[86:89], v[174:177], v[122:125]
	v_mfma_f32_16x16x32_bf16 v[110:113], v[78:81], v[198:201], v[110:113]
	v_mfma_f32_16x16x32_bf16 v[106:109], v[86:89], v[198:201], v[106:109]
	v_mfma_f32_16x16x32_bf16 v[98:101], v[78:81], v[206:209], v[98:101]
	v_mfma_f32_16x16x32_bf16 v[90:93], v[86:89], v[206:209], v[90:93]
	v_mfma_f32_16x16x32_bf16 v[134:137], v[146:149], v[162:165], v[134:137]
	v_mfma_f32_16x16x32_bf16 v[126:129], v[154:157], v[162:165], v[126:129]
	v_mfma_f32_16x16x32_bf16 v[118:121], v[146:149], v[170:173], v[118:121]
	v_mfma_f32_16x16x32_bf16 v[114:117], v[154:157], v[170:173], v[114:117]
	v_mfma_f32_16x16x32_bf16 v[102:105], v[146:149], v[178:181], v[102:105]
	v_mfma_f32_16x16x32_bf16 v[94:97], v[154:157], v[178:181], v[94:97]
	v_mfma_f32_16x16x32_bf16 v[74:77], v[146:149], v[202:205], v[74:77]
	v_mfma_f32_16x16x32_bf16 v[70:73], v[154:157], v[202:205], v[70:73]
	v_mfma_f32_16x16x32_bf16 v[134:137], v[150:153], v[166:169], v[134:137]
	v_mfma_f32_16x16x32_bf16 v[126:129], v[158:161], v[166:169], v[126:129]
	v_mfma_f32_16x16x32_bf16 v[118:121], v[150:153], v[174:177], v[118:121]
	v_mfma_f32_16x16x32_bf16 v[114:117], v[158:161], v[174:177], v[114:117]
	v_mfma_f32_16x16x32_bf16 v[102:105], v[150:153], v[198:201], v[102:105]
	v_mfma_f32_16x16x32_bf16 v[94:97], v[158:161], v[198:201], v[94:97]
	v_mfma_f32_16x16x32_bf16 v[74:77], v[150:153], v[206:209], v[74:77]
	v_mfma_f32_16x16x32_bf16 v[70:73], v[158:161], v[206:209], v[70:73]
	s_barrier
; #define PG8_STAGE(bufoff, gbase, voff) do { _Pragma("unroll") for (int _i = 0; _i < 2; ++_i) \
;         __builtin_amdgcn_global_load_lds((const unsigned*)((const char*)(gbase) + (voff)[_i]), (PG8_LAS unsigned*)(lds + (bufoff) + ldsw + _i * 8192), 16, 0, 0); } while (0)
; #define PG8_LDA(dst, b, h) do { _Pragma("unroll") for (int m = 0; m < 4; ++m) _Pragma("unroll") for (int k = 0; k < 2; ++k) dst[m][k] = *(const PG8_LAS bf16x8*)(lds + PG8_SA(b, h) + aoff + m * 2048 + k * 1024); } while (0)
; #define PG8_MMA(ai, bj, At, Bt) do { __builtin_amdgcn_s_setprio(1); _Pragma("unroll") for (int m = 0; m < 4; ++m) _Pragma("unroll") for (int n = 0; n < 2; ++n) _Pragma("unroll") for (int k = 0; k < 2; ++k) \
;         acc[ai][bj][m][n] = __builtin_amdgcn_mfma_f32_16x16x32_bf16(Bt[n][k], At[m][k], acc[ai][bj][m][n], 0, 0, 0); __builtin_amdgcn_s_setprio(0); } while (0)
; #define PG8_WAIT_V(n) asm volatile("s_waitcnt vmcnt(" #n ")" ::: "memory")
; #define PG8_WAIT_L(n) asm volatile("s_waitcnt lgkmcnt(" #n ")" ::: "memory")
; #define PG8_BAR __builtin_amdgcn_s_barrier()
; #define PG8_SCHED __builtin_amdgcn_sched_barrier(0)
; template <class Epi, class Sched, bool ALIGN_EPI = false, bool SP2 = false>
; __device__ __forceinline__ void gemm_phase(PG8_LAS unsigned char* lds, const Gemm g, const Sched& S, const Epi& E) {
;     ...
;             PG8_LDA(At, 1, 1); PG8_STAGE(PG8_SB(1, 0), b3, voffB); PG8_STAGE(PG8_SB(1, 1), b3 + hstep, voffB); PG8_STAGE(PG8_SA(1, 0), a3, voffA);
;             PG8_WAIT_V(8); PG8_WAIT_L(0); PG8_BAR; PG8_MMA(1, 0, At, B0); PG8_MMA(1, 1, At, B1); PG8_BAR; PG8_SCHED;
	s_add_i32 s34, s34, s3
	v_lshl_add_u64 v[182:183], v[182:183], 0, s[48:49]
	s_mov_b32 m0, s34
	ds_read_b128 v[162:165], v222 offset:49152
	ds_read_b128 v[166:169], v222 offset:50176
	ds_read_b128 v[170:173], v222 offset:51200
	ds_read_b128 v[174:177], v222 offset:52224
	ds_read_b128 v[178:181], v222 offset:53248
	ds_read_b128 v[198:201], v222 offset:54272
	ds_read_b128 v[202:205], v222 offset:55296
	ds_read_b128 v[206:209], v222 offset:56320
	global_load_lds_dwordx4 v[182:183], off
	s_add_i32 m0, s34, 0x2000
	s_add_u32 s56, s56, 0xb0080
	v_lshl_add_u64 v[182:183], v[210:211], 0, s[48:49]
	s_addc_u32 s57, s57, 0
	s_add_i32 s34, s35, s3
	global_load_lds_dwordx4 v[182:183], off
	v_lshl_add_u64 v[182:183], s[56:57], 0, v[184:185]
	s_mov_b32 m0, s34
	s_nop 0
	global_load_lds_dwordx4 v[182:183], off
	v_lshl_add_u64 v[182:183], s[56:57], 0, v[186:187]
	s_add_i32 m0, s34, 0x2000
	s_nop 0
	global_load_lds_dwordx4 v[182:183], off
	v_lshl_add_u64 v[182:183], v[212:213], 0, s[48:49]
	s_mov_b32 m0, s65
	s_nop 0
	global_load_lds_dwordx4 v[182:183], off
	v_lshl_add_u64 v[182:183], v[214:215], 0, s[48:49]
	s_mov_b32 m0, s66
	s_nop 0
	global_load_lds_dwordx4 v[182:183], off
	s_waitcnt vmcnt(8)
	s_waitcnt lgkmcnt(0)
	s_barrier
	s_waitcnt lgkmcnt(0)
	v_mfma_f32_16x16x32_bf16 v[62:65], v[66:69], v[162:165], v[62:65]
	v_mfma_f32_16x16x32_bf16 v[58:61], v[82:85], v[162:165], v[58:61]
	v_mfma_f32_16x16x32_bf16 v[50:53], v[66:69], v[170:173], v[50:53]
	v_mfma_f32_16x16x32_bf16 v[42:45], v[82:85], v[170:173], v[42:45]
	v_mfma_f32_16x16x32_bf16 v[30:33], v[66:69], v[178:181], v[30:33]
	v_mfma_f32_16x16x32_bf16 v[26:29], v[82:85], v[178:181], v[26:29]
	v_mfma_f32_16x16x32_bf16 v[18:21], v[66:69], v[202:205], v[18:21]
	v_mfma_f32_16x16x32_bf16 v[10:13], v[82:85], v[202:205], v[10:13]
	v_mfma_f32_16x16x32_bf16 v[62:65], v[78:81], v[166:169], v[62:65]
	v_mfma_f32_16x16x32_bf16 v[58:61], v[86:89], v[166:169], v[58:61]
	v_mfma_f32_16x16x32_bf16 v[50:53], v[78:81], v[174:177], v[50:53]
	v_mfma_f32_16x16x32_bf16 v[42:45], v[86:89], v[174:177], v[42:45]
	v_mfma_f32_16x16x32_bf16 v[30:33], v[78:81], v[198:201], v[30:33]
	v_mfma_f32_16x16x32_bf16 v[26:29], v[86:89], v[198:201], v[26:29]
	v_mfma_f32_16x16x32_bf16 v[18:21], v[78:81], v[206:209], v[18:21]
	v_mfma_f32_16x16x32_bf16 v[10:13], v[86:89], v[206:209], v[10:13]
	v_mfma_f32_16x16x32_bf16 v[54:57], v[146:149], v[162:165], v[54:57]
	v_mfma_f32_16x16x32_bf16 v[46:49], v[154:157], v[162:165], v[46:49]
	v_mfma_f32_16x16x32_bf16 v[38:41], v[146:149], v[170:173], v[38:41]
	v_mfma_f32_16x16x32_bf16 v[34:37], v[154:157], v[170:173], v[34:37]
	v_mfma_f32_16x16x32_bf16 v[22:25], v[146:149], v[178:181], v[22:25]
	v_mfma_f32_16x16x32_bf16 v[14:17], v[154:157], v[178:181], v[14:17]
	v_mfma_f32_16x16x32_bf16 v[6:9], v[146:149], v[202:205], v[6:9]
	v_mfma_f32_16x16x32_bf16 v[2:5], v[154:157], v[202:205], v[2:5]
	v_mfma_f32_16x16x32_bf16 v[54:57], v[150:153], v[166:169], v[54:57]
	v_mfma_f32_16x16x32_bf16 v[46:49], v[158:161], v[166:169], v[46:49]
	v_mfma_f32_16x16x32_bf16 v[38:41], v[150:153], v[174:177], v[38:41]
	v_mfma_f32_16x16x32_bf16 v[34:37], v[158:161], v[174:177], v[34:37]
	v_mfma_f32_16x16x32_bf16 v[22:25], v[150:153], v[198:201], v[22:25]
	v_mfma_f32_16x16x32_bf16 v[14:17], v[158:161], v[198:201], v[14:17]
	v_mfma_f32_16x16x32_bf16 v[6:9], v[150:153], v[206:209], v[6:9]
	v_mfma_f32_16x16x32_bf16 v[2:5], v[158:161], v[206:209], v[2:5]
	s_barrier
	s_add_i32 s84, s84, 2
	s_add_u32 s12, s12, 0x100
	s_addc_u32 s13, s13, 0
	s_add_u32 s82, s82, 0x100
	s_addc_u32 s83, s83, 0
	s_cmp_gt_u32 s84, 41
	s_cbranch_scc0 .LBB0_228
	s_and_b64 vcc, exec, s[50:51]
	s_cbranch_vccz .LBB0_231
	s_barrier

; #define PG8_STAGE(bufoff, gbase, voff) do { _Pragma("unroll") for (int _i = 0; _i < 2; ++_i) \
;         __builtin_amdgcn_global_load_lds((const unsigned*)((const char*)(gbase) + (voff)[_i]), (PG8_LAS unsigned*)(lds + (bufoff) + ldsw + _i * 8192), 16, 0, 0); } while (0)
; #define PG8_LDA(dst, b, h) do { _Pragma("unroll") for (int m = 0; m < 4; ++m) _Pragma("unroll") for (int k = 0; k < 2; ++k) dst[m][k] = *(const PG8_LAS bf16x8*)(lds + PG8_SA(b, h) + aoff + m * 2048 + k * 1024); } while (0)
; #define PG8_LDB(dst, b, h) do { _Pragma("unroll") for (int n = 0; n < 2; ++n) _Pragma("unroll") for (int k = 0; k < 2; ++k) dst[n][k] = *(const PG8_LAS bf16x8*)(lds + PG8_SB(b, h) + boff + n * 2048 + k * 1024); } while (0)
; #define PG8_MMA(ai, bj, At, Bt) do { __builtin_amdgcn_s_setprio(1); _Pragma("unroll") for (int m = 0; m < 4; ++m) _Pragma("unroll") for (int n = 0; n < 2; ++n) _Pragma("unroll") for (int k = 0; k < 2; ++k) \
;         acc[ai][bj][m][n] = __builtin_amdgcn_mfma_f32_16x16x32_bf16(Bt[n][k], At[m][k], acc[ai][bj][m][n], 0, 0, 0); __builtin_amdgcn_s_setprio(0); } while (0)
; #define PG8_WAIT_V(n) asm volatile("s_waitcnt vmcnt(" #n ")" ::: "memory")
; #define PG8_BAR __builtin_amdgcn_s_barrier()
; template <class Epi, class Sched, bool ALIGN_EPI = false, bool SP2 = false>
; __device__ __forceinline__ void gemm_phase(PG8_LAS unsigned char* lds, const Gemm g, const Sched& S, const Epi& E) {
;     ...
;         for (int t = 0; t < nt; t += 2) {
;             const bool last = (t == nt - 2);
;             const char* a1 = cA + (size_t)(t + 1) * kstep;
;             const char* a2 = last ? nA : cA + (size_t)(t + 2) * kstep; const char* b2 = last ? nB : cB + (size_t)(t + 2) * kstep;
;             const char* a3 = a2 + kstep; const char* b3 = b2 + kstep;
;             if (last && has_next) S.a_ready(nxt);
;             if constexpr (SP2) {
;             PG8_LDB(B0, 0, 0); PG8_LDB(B1, 0, 1); PG8_SCHED; PG8_LDA(At, 0, 0); PG8_STAGE(PG8_SA(1, 1), a1 + hstep, voffA);
;             PG8_WAIT_V(8); PG8_WAIT_L(0); PG8_BAR; PG8_MMA(0, 0, At, B0); PG8_MMA(0, 1, At, B1); PG8_BAR; PG8_SCHED;
;             PG8_LDA(At, 0, 1); PG8_STAGE(PG8_SB(0, 0), b2, voffB); PG8_STAGE(PG8_SB(0, 1), b2 + hstep, voffB); PG8_STAGE(PG8_SA(0, 0), a2, voffA);
;             PG8_WAIT_V(8); PG8_WAIT_L(0); PG8_BAR; PG8_MMA(1, 0, At, B0); PG8_MMA(1, 1, At, B1); PG8_BAR; PG8_SCHED;
.LBB0_370:
	ds_read_b128 v[142:145], v148
	ds_read_b128 v[152:155], v148 offset:1024
	ds_read_b128 v[156:159], v148 offset:2048
	ds_read_b128 v[160:163], v148 offset:3072
	ds_read_b128 v[164:167], v149
	ds_read_b128 v[168:171], v149 offset:1024
	ds_read_b128 v[172:175], v149 offset:2048
	ds_read_b128 v[176:179], v149 offset:3072
	s_add_u32 s34, s42, 0xfffc0080
	s_addc_u32 s35, s43, -1
	s_cmp_eq_u32 s66, 12
	s_cselect_b32 s47, s17, s35
	s_cselect_b32 s46, s62, s34
	s_cselect_b32 s45, s15, s65
	s_cselect_b32 s44, s63, s64
	v_lshl_add_u64 v[212:213], s[42:43], 0, v[134:135]
	s_add_i32 m0, s41, 0xc000
	ds_read_b128 v[180:183], v150
	ds_read_b128 v[184:187], v150 offset:1024
	ds_read_b128 v[188:191], v150 offset:2048
	ds_read_b128 v[192:195], v150 offset:3072
	ds_read_b128 v[196:199], v150 offset:4096
	ds_read_b128 v[200:203], v150 offset:5120
	ds_read_b128 v[204:207], v150 offset:6144
	ds_read_b128 v[208:211], v150 offset:7168
	global_load_lds_dwordx4 v[212:213], off
	v_lshl_add_u64 v[212:213], s[42:43], 0, v[136:137]
	s_add_i32 m0, s41, 0xe000
	s_nop 0
	global_load_lds_dwordx4 v[212:213], off
	s_waitcnt vmcnt(8)
	s_waitcnt lgkmcnt(0)
	s_barrier
	s_waitcnt lgkmcnt(0)
	v_mfma_f32_16x16x32_bf16 v[126:129], v[142:145], v[180:183], v[126:129]
	v_mfma_f32_16x16x32_bf16 v[122:125], v[156:159], v[180:183], v[122:125]
	v_mfma_f32_16x16x32_bf16 v[110:113], v[142:145], v[188:191], v[110:113]
	v_mfma_f32_16x16x32_bf16 v[106:109], v[156:159], v[188:191], v[106:109]
	v_mfma_f32_16x16x32_bf16 v[94:97], v[142:145], v[196:199], v[94:97]
	v_mfma_f32_16x16x32_bf16 v[90:93], v[156:159], v[196:199], v[90:93]
	v_mfma_f32_16x16x32_bf16 v[78:81], v[142:145], v[204:207], v[78:81]
	v_mfma_f32_16x16x32_bf16 v[74:77], v[156:159], v[204:207], v[74:77]
	v_mfma_f32_16x16x32_bf16 v[126:129], v[152:155], v[184:187], v[126:129]
	v_mfma_f32_16x16x32_bf16 v[122:125], v[160:163], v[184:187], v[122:125]
	v_mfma_f32_16x16x32_bf16 v[110:113], v[152:155], v[192:195], v[110:113]
	v_mfma_f32_16x16x32_bf16 v[106:109], v[160:163], v[192:195], v[106:109]
	v_mfma_f32_16x16x32_bf16 v[94:97], v[152:155], v[200:203], v[94:97]
	v_mfma_f32_16x16x32_bf16 v[90:93], v[160:163], v[200:203], v[90:93]
	v_mfma_f32_16x16x32_bf16 v[78:81], v[152:155], v[208:211], v[78:81]
	v_mfma_f32_16x16x32_bf16 v[74:77], v[160:163], v[208:211], v[74:77]
	v_mfma_f32_16x16x32_bf16 v[118:121], v[164:167], v[180:183], v[118:121]
	v_mfma_f32_16x16x32_bf16 v[114:117], v[172:175], v[180:183], v[114:117]
	v_mfma_f32_16x16x32_bf16 v[102:105], v[164:167], v[188:191], v[102:105]
	v_mfma_f32_16x16x32_bf16 v[98:101], v[172:175], v[188:191], v[98:101]
	v_mfma_f32_16x16x32_bf16 v[86:89], v[164:167], v[196:199], v[86:89]
	v_mfma_f32_16x16x32_bf16 v[82:85], v[172:175], v[196:199], v[82:85]
	v_mfma_f32_16x16x32_bf16 v[70:73], v[164:167], v[204:207], v[70:73]
	v_mfma_f32_16x16x32_bf16 v[66:69], v[172:175], v[204:207], v[66:69]
	v_mfma_f32_16x16x32_bf16 v[118:121], v[168:171], v[184:187], v[118:121]
	v_mfma_f32_16x16x32_bf16 v[114:117], v[176:179], v[184:187], v[114:117]
	v_mfma_f32_16x16x32_bf16 v[102:105], v[168:171], v[192:195], v[102:105]
	v_mfma_f32_16x16x32_bf16 v[98:101], v[176:179], v[192:195], v[98:101]
	v_mfma_f32_16x16x32_bf16 v[86:89], v[168:171], v[200:203], v[86:89]
	v_mfma_f32_16x16x32_bf16 v[82:85], v[176:179], v[200:203], v[82:85]
	v_mfma_f32_16x16x32_bf16 v[70:73], v[168:171], v[208:211], v[70:73]
	v_mfma_f32_16x16x32_bf16 v[66:69], v[176:179], v[208:211], v[66:69]
	s_barrier
	s_add_i32 s34, s58, s48
	v_lshl_add_u64 v[212:213], s[44:45], 0, v[132:133]
	s_mov_b32 m0, s34
	ds_read_b128 v[180:183], v150 offset:16384
	ds_read_b128 v[184:187], v150 offset:17408
	ds_read_b128 v[188:191], v150 offset:18432
	ds_read_b128 v[192:195], v150 offset:19456
	ds_read_b128 v[196:199], v150 offset:20480
	ds_read_b128 v[200:203], v150 offset:21504
	ds_read_b128 v[204:207], v150 offset:22528
	ds_read_b128 v[208:211], v150 offset:23552
	global_load_lds_dwordx4 v[212:213], off
	s_add_i32 m0, s34, 0x2000
	s_add_u32 s68, s44, 0x40000
	v_lshl_add_u64 v[214:215], s[44:45], 0, v[130:131]
	s_addc_u32 s69, s45, 0
	s_add_i32 s34, s59, s48
	global_load_lds_dwordx4 v[214:215], off
	v_lshl_add_u64 v[216:217], s[68:69], 0, v[132:133]
	s_mov_b32 m0, s34
	v_lshl_add_u64 v[218:219], s[46:47], 0, v[130:131]
	global_load_lds_dwordx4 v[216:217], off
	v_lshl_add_u64 v[216:217], s[68:69], 0, v[130:131]
	s_add_i32 m0, s34, 0x2000
	s_nop 0
	global_load_lds_dwordx4 v[216:217], off
	v_lshl_add_u64 v[216:217], s[46:47], 0, v[132:133]
	s_mov_b32 m0, s41
	s_nop 0
	global_load_lds_dwordx4 v[216:217], off
	s_mov_b32 m0, s51
	s_nop 0
	global_load_lds_dwordx4 v[218:219], off
	s_waitcnt vmcnt(8)
	s_waitcnt lgkmcnt(0)
	s_barrier
; #define PG8_STAGE(bufoff, gbase, voff) do { _Pragma("unroll") for (int _i = 0; _i < 2; ++_i) \
;         __builtin_amdgcn_global_load_lds((const unsigned*)((const char*)(gbase) + (voff)[_i]), (PG8_LAS unsigned*)(lds + (bufoff) + ldsw + _i * 8192), 16, 0, 0); } while (0)
; #define PG8_LDA(dst, b, h) do { _Pragma("unroll") for (int m = 0; m < 4; ++m) _Pragma("unroll") for (int k = 0; k < 2; ++k) dst[m][k] = *(const PG8_LAS bf16x8*)(lds + PG8_SA(b, h) + aoff + m * 2048 + k * 1024); } while (0)
; #define PG8_LDB(dst, b, h) do { _Pragma("unroll") for (int n = 0; n < 2; ++n) _Pragma("unroll") for (int k = 0; k < 2; ++k) dst[n][k] = *(const PG8_LAS bf16x8*)(lds + PG8_SB(b, h) + boff + n * 2048 + k * 1024); } while (0)
; #define PG8_MMA(ai, bj, At, Bt) do { __builtin_amdgcn_s_setprio(1); _Pragma("unroll") for (int m = 0; m < 4; ++m) _Pragma("unroll") for (int n = 0; n < 2; ++n) _Pragma("unroll") for (int k = 0; k < 2; ++k) \
;         acc[ai][bj][m][n] = __builtin_amdgcn_mfma_f32_16x16x32_bf16(Bt[n][k], At[m][k], acc[ai][bj][m][n], 0, 0, 0); __builtin_amdgcn_s_setprio(0); } while (0)
; #define PG8_WAIT_V(n) asm volatile("s_waitcnt vmcnt(" #n ")" ::: "memory")
; #define PG8_WAIT_L(n) asm volatile("s_waitcnt lgkmcnt(" #n ")" ::: "memory")
; #define PG8_BAR __builtin_amdgcn_s_barrier()
; #define PG8_SCHED __builtin_amdgcn_sched_barrier(0)
; template <class Epi, class Sched, bool ALIGN_EPI = false, bool SP2 = false>
; __device__ __forceinline__ void gemm_phase(PG8_LAS unsigned char* lds, const Gemm g, const Sched& S, const Epi& E) {
;     ...
;             PG8_LDA(At, 0, 1); PG8_STAGE(PG8_SB(0, 0), b2, voffB); PG8_STAGE(PG8_SB(0, 1), b2 + hstep, voffB); PG8_STAGE(PG8_SA(0, 0), a2, voffA);
;             PG8_WAIT_V(8); PG8_WAIT_L(0); PG8_BAR; PG8_MMA(1, 0, At, B0); PG8_MMA(1, 1, At, B1); PG8_BAR; PG8_SCHED;
;             PG8_LDB(B0, 1, 0); PG8_LDB(B1, 1, 1); PG8_SCHED; PG8_LDA(At, 1, 0); PG8_STAGE(PG8_SA(0, 1), a2 + hstep, voffA);
;             PG8_WAIT_V(8); PG8_WAIT_L(0); PG8_BAR; PG8_MMA(0, 0, At, B0); PG8_MMA(0, 1, At, B1); PG8_BAR; PG8_SCHED;
;             PG8_LDA(At, 1, 1); PG8_STAGE(PG8_SB(1, 0), b3, voffB); PG8_STAGE(PG8_SB(1, 1), b3 + hstep, voffB); PG8_STAGE(PG8_SA(1, 0), a3, voffA);
	s_waitcnt lgkmcnt(0)
	v_mfma_f32_16x16x32_bf16 v[62:65], v[142:145], v[180:183], v[62:65]
	v_mfma_f32_16x16x32_bf16 v[58:61], v[156:159], v[180:183], v[58:61]
	v_mfma_f32_16x16x32_bf16 v[46:49], v[142:145], v[188:191], v[46:49]
	v_mfma_f32_16x16x32_bf16 v[42:45], v[156:159], v[188:191], v[42:45]
	v_mfma_f32_16x16x32_bf16 v[30:33], v[142:145], v[196:199], v[30:33]
	v_mfma_f32_16x16x32_bf16 v[26:29], v[156:159], v[196:199], v[26:29]
	v_mfma_f32_16x16x32_bf16 v[14:17], v[142:145], v[204:207], v[14:17]
	v_mfma_f32_16x16x32_bf16 v[10:13], v[156:159], v[204:207], v[10:13]
	v_mfma_f32_16x16x32_bf16 v[62:65], v[152:155], v[184:187], v[62:65]
	v_mfma_f32_16x16x32_bf16 v[58:61], v[160:163], v[184:187], v[58:61]
	v_mfma_f32_16x16x32_bf16 v[46:49], v[152:155], v[192:195], v[46:49]
	v_mfma_f32_16x16x32_bf16 v[42:45], v[160:163], v[192:195], v[42:45]
	v_mfma_f32_16x16x32_bf16 v[30:33], v[152:155], v[200:203], v[30:33]
	v_mfma_f32_16x16x32_bf16 v[26:29], v[160:163], v[200:203], v[26:29]
	v_mfma_f32_16x16x32_bf16 v[14:17], v[152:155], v[208:211], v[14:17]
	v_mfma_f32_16x16x32_bf16 v[10:13], v[160:163], v[208:211], v[10:13]
	v_mfma_f32_16x16x32_bf16 v[54:57], v[164:167], v[180:183], v[54:57]
	v_mfma_f32_16x16x32_bf16 v[50:53], v[172:175], v[180:183], v[50:53]
	v_mfma_f32_16x16x32_bf16 v[38:41], v[164:167], v[188:191], v[38:41]
	v_mfma_f32_16x16x32_bf16 v[34:37], v[172:175], v[188:191], v[34:37]
	v_mfma_f32_16x16x32_bf16 v[22:25], v[164:167], v[196:199], v[22:25]
	v_mfma_f32_16x16x32_bf16 v[18:21], v[172:175], v[196:199], v[18:21]
	v_mfma_f32_16x16x32_bf16 v[6:9], v[164:167], v[204:207], v[6:9]
	v_mfma_f32_16x16x32_bf16 v[2:5], v[172:175], v[204:207], v[2:5]
	v_mfma_f32_16x16x32_bf16 v[54:57], v[168:171], v[184:187], v[54:57]
	v_mfma_f32_16x16x32_bf16 v[50:53], v[176:179], v[184:187], v[50:53]
	v_mfma_f32_16x16x32_bf16 v[38:41], v[168:171], v[192:195], v[38:41]
	v_mfma_f32_16x16x32_bf16 v[34:37], v[176:179], v[192:195], v[34:37]
	v_mfma_f32_16x16x32_bf16 v[22:25], v[168:171], v[200:203], v[22:25]
	v_mfma_f32_16x16x32_bf16 v[18:21], v[176:179], v[200:203], v[18:21]
	v_mfma_f32_16x16x32_bf16 v[6:9], v[168:171], v[208:211], v[6:9]
	v_mfma_f32_16x16x32_bf16 v[2:5], v[176:179], v[208:211], v[2:5]
	s_barrier
	s_add_i32 s34, 0, 0x18000
	v_add_u32_e32 v151, s34, v146
	s_add_i32 s35, 0, 0x1c000
	ds_read_b128 v[142:145], v151
	ds_read_b128 v[152:155], v151 offset:1024
	ds_read_b128 v[156:159], v151 offset:2048
	ds_read_b128 v[160:163], v151 offset:3072
	v_add_u32_e32 v151, s35, v146
	ds_read_b128 v[164:167], v151
	ds_read_b128 v[168:171], v151 offset:1024
	ds_read_b128 v[172:175], v151 offset:2048
	ds_read_b128 v[176:179], v151 offset:3072
	s_add_u32 s46, s46, 0x40000
	s_addc_u32 s47, s47, 0
	s_mov_b32 m0, s52
	v_lshl_add_u64 v[220:221], s[46:47], 0, v[132:133]
	ds_read_b128 v[180:183], v150 offset:32768
	ds_read_b128 v[184:187], v150 offset:33792
	ds_read_b128 v[188:191], v150 offset:34816
	ds_read_b128 v[192:195], v150 offset:35840
	ds_read_b128 v[196:199], v150 offset:36864
	ds_read_b128 v[200:203], v150 offset:37888
	ds_read_b128 v[204:207], v150 offset:38912
	ds_read_b128 v[208:211], v150 offset:39936
	global_load_lds_dwordx4 v[220:221], off
	v_lshl_add_u64 v[220:221], s[46:47], 0, v[130:131]
	s_mov_b32 m0, s53
	s_nop 0
	global_load_lds_dwordx4 v[220:221], off
	s_waitcnt vmcnt(8)
	s_waitcnt lgkmcnt(0)
	s_barrier
	s_waitcnt lgkmcnt(0)
	v_mfma_f32_16x16x32_bf16 v[126:129], v[142:145], v[180:183], v[126:129]
	v_mfma_f32_16x16x32_bf16 v[122:125], v[156:159], v[180:183], v[122:125]
	v_mfma_f32_16x16x32_bf16 v[110:113], v[142:145], v[188:191], v[110:113]
	v_mfma_f32_16x16x32_bf16 v[106:109], v[156:159], v[188:191], v[106:109]
	v_mfma_f32_16x16x32_bf16 v[94:97], v[142:145], v[196:199], v[94:97]
	v_mfma_f32_16x16x32_bf16 v[90:93], v[156:159], v[196:199], v[90:93]
	v_mfma_f32_16x16x32_bf16 v[78:81], v[142:145], v[204:207], v[78:81]
	v_mfma_f32_16x16x32_bf16 v[74:77], v[156:159], v[204:207], v[74:77]
	v_mfma_f32_16x16x32_bf16 v[126:129], v[152:155], v[184:187], v[126:129]
	v_mfma_f32_16x16x32_bf16 v[122:125], v[160:163], v[184:187], v[122:125]
	v_mfma_f32_16x16x32_bf16 v[110:113], v[152:155], v[192:195], v[110:113]
	v_mfma_f32_16x16x32_bf16 v[106:109], v[160:163], v[192:195], v[106:109]
	v_mfma_f32_16x16x32_bf16 v[94:97], v[152:155], v[200:203], v[94:97]
	v_mfma_f32_16x16x32_bf16 v[90:93], v[160:163], v[200:203], v[90:93]
	v_mfma_f32_16x16x32_bf16 v[78:81], v[152:155], v[208:211], v[78:81]
	v_mfma_f32_16x16x32_bf16 v[74:77], v[160:163], v[208:211], v[74:77]
	v_mfma_f32_16x16x32_bf16 v[118:121], v[164:167], v[180:183], v[118:121]
	v_mfma_f32_16x16x32_bf16 v[114:117], v[172:175], v[180:183], v[114:117]
	v_mfma_f32_16x16x32_bf16 v[102:105], v[164:167], v[188:191], v[102:105]
	v_mfma_f32_16x16x32_bf16 v[98:101], v[172:175], v[188:191], v[98:101]
	v_mfma_f32_16x16x32_bf16 v[86:89], v[164:167], v[196:199], v[86:89]
	v_mfma_f32_16x16x32_bf16 v[82:85], v[172:175], v[196:199], v[82:85]
	v_mfma_f32_16x16x32_bf16 v[70:73], v[164:167], v[204:207], v[70:73]
	v_mfma_f32_16x16x32_bf16 v[66:69], v[172:175], v[204:207], v[66:69]
	v_mfma_f32_16x16x32_bf16 v[118:121], v[168:171], v[184:187], v[118:121]
	v_mfma_f32_16x16x32_bf16 v[114:117], v[176:179], v[184:187], v[114:117]
	v_mfma_f32_16x16x32_bf16 v[102:105], v[168:171], v[192:195], v[102:105]
	v_mfma_f32_16x16x32_bf16 v[98:101], v[176:179], v[192:195], v[98:101]
	v_mfma_f32_16x16x32_bf16 v[86:89], v[168:171], v[200:203], v[86:89]
	v_mfma_f32_16x16x32_bf16 v[82:85], v[176:179], v[200:203], v[82:85]
	v_mfma_f32_16x16x32_bf16 v[70:73], v[168:171], v[208:211], v[70:73]
	v_mfma_f32_16x16x32_bf16 v[66:69], v[176:179], v[208:211], v[66:69]
	s_barrier
; #define PG8_STAGE(bufoff, gbase, voff) do { _Pragma("unroll") for (int _i = 0; _i < 2; ++_i) \
;         __builtin_amdgcn_global_load_lds((const unsigned*)((const char*)(gbase) + (voff)[_i]), (PG8_LAS unsigned*)(lds + (bufoff) + ldsw + _i * 8192), 16, 0, 0); } while (0)
; #define PG8_LDA(dst, b, h) do { _Pragma("unroll") for (int m = 0; m < 4; ++m) _Pragma("unroll") for (int k = 0; k < 2; ++k) dst[m][k] = *(const PG8_LAS bf16x8*)(lds + PG8_SA(b, h) + aoff + m * 2048 + k * 1024); } while (0)
; #define PG8_MMA(ai, bj, At, Bt) do { __builtin_amdgcn_s_setprio(1); _Pragma("unroll") for (int m = 0; m < 4; ++m) _Pragma("unroll") for (int n = 0; n < 2; ++n) _Pragma("unroll") for (int k = 0; k < 2; ++k) \
;         acc[ai][bj][m][n] = __builtin_amdgcn_mfma_f32_16x16x32_bf16(Bt[n][k], At[m][k], acc[ai][bj][m][n], 0, 0, 0); __builtin_amdgcn_s_setprio(0); } while (0)
; #define PG8_WAIT_V(n) asm volatile("s_waitcnt vmcnt(" #n ")" ::: "memory")
; #define PG8_WAIT_L(n) asm volatile("s_waitcnt lgkmcnt(" #n ")" ::: "memory")
; #define PG8_BAR __builtin_amdgcn_s_barrier()
; #define PG8_SCHED __builtin_amdgcn_sched_barrier(0)
; template <class Epi, class Sched, bool ALIGN_EPI = false, bool SP2 = false>
; __device__ __forceinline__ void gemm_phase(PG8_LAS unsigned char* lds, const Gemm g, const Sched& S, const Epi& E) {
;     ...
;             PG8_LDA(At, 1, 1); PG8_STAGE(PG8_SB(1, 0), b3, voffB); PG8_STAGE(PG8_SB(1, 1), b3 + hstep, voffB); PG8_STAGE(PG8_SA(1, 0), a3, voffA);
;             PG8_WAIT_V(8); PG8_WAIT_L(0); PG8_BAR; PG8_MMA(1, 0, At, B0); PG8_MMA(1, 1, At, B1); PG8_BAR; PG8_SCHED;
	s_add_i32 s34, s34, s48
	v_lshl_add_u64 v[212:213], v[212:213], 0, s[10:11]
	s_mov_b32 m0, s34
	ds_read_b128 v[180:183], v150 offset:49152
	ds_read_b128 v[184:187], v150 offset:50176
	ds_read_b128 v[188:191], v150 offset:51200
	ds_read_b128 v[192:195], v150 offset:52224
	ds_read_b128 v[196:199], v150 offset:53248
	ds_read_b128 v[200:203], v150 offset:54272
	ds_read_b128 v[204:207], v150 offset:55296
	ds_read_b128 v[208:211], v150 offset:56320
	global_load_lds_dwordx4 v[212:213], off
	s_add_i32 m0, s34, 0x2000
	s_add_u32 s44, s44, 0x40080
	v_lshl_add_u64 v[212:213], v[214:215], 0, s[10:11]
	s_addc_u32 s45, s45, 0
	s_add_i32 s34, s35, s48
	global_load_lds_dwordx4 v[212:213], off
	v_lshl_add_u64 v[212:213], s[44:45], 0, v[132:133]
	s_mov_b32 m0, s34
	s_nop 0
	global_load_lds_dwordx4 v[212:213], off
	v_lshl_add_u64 v[212:213], s[44:45], 0, v[130:131]
	s_add_i32 m0, s34, 0x2000
	s_nop 0
	global_load_lds_dwordx4 v[212:213], off
	v_lshl_add_u64 v[212:213], v[216:217], 0, s[10:11]
	s_mov_b32 m0, s55
	s_nop 0
	global_load_lds_dwordx4 v[212:213], off
	v_lshl_add_u64 v[212:213], v[218:219], 0, s[10:11]
	s_mov_b32 m0, s56
	s_nop 0
	global_load_lds_dwordx4 v[212:213], off
	s_waitcnt vmcnt(8)
	s_waitcnt lgkmcnt(0)
	s_barrier
	s_waitcnt lgkmcnt(0)
	v_mfma_f32_16x16x32_bf16 v[62:65], v[142:145], v[180:183], v[62:65]
	v_mfma_f32_16x16x32_bf16 v[58:61], v[156:159], v[180:183], v[58:61]
	v_mfma_f32_16x16x32_bf16 v[46:49], v[142:145], v[188:191], v[46:49]
	v_mfma_f32_16x16x32_bf16 v[42:45], v[156:159], v[188:191], v[42:45]
	v_mfma_f32_16x16x32_bf16 v[30:33], v[142:145], v[196:199], v[30:33]
	v_mfma_f32_16x16x32_bf16 v[26:29], v[156:159], v[196:199], v[26:29]
	v_mfma_f32_16x16x32_bf16 v[14:17], v[142:145], v[204:207], v[14:17]
	v_mfma_f32_16x16x32_bf16 v[10:13], v[156:159], v[204:207], v[10:13]
	v_mfma_f32_16x16x32_bf16 v[62:65], v[152:155], v[184:187], v[62:65]
	v_mfma_f32_16x16x32_bf16 v[58:61], v[160:163], v[184:187], v[58:61]
	v_mfma_f32_16x16x32_bf16 v[46:49], v[152:155], v[192:195], v[46:49]
	v_mfma_f32_16x16x32_bf16 v[42:45], v[160:163], v[192:195], v[42:45]
	v_mfma_f32_16x16x32_bf16 v[30:33], v[152:155], v[200:203], v[30:33]
	v_mfma_f32_16x16x32_bf16 v[26:29], v[160:163], v[200:203], v[26:29]
	v_mfma_f32_16x16x32_bf16 v[14:17], v[152:155], v[208:211], v[14:17]
	v_mfma_f32_16x16x32_bf16 v[10:13], v[160:163], v[208:211], v[10:13]
	v_mfma_f32_16x16x32_bf16 v[54:57], v[164:167], v[180:183], v[54:57]
	v_mfma_f32_16x16x32_bf16 v[50:53], v[172:175], v[180:183], v[50:53]
	v_mfma_f32_16x16x32_bf16 v[38:41], v[164:167], v[188:191], v[38:41]
	v_mfma_f32_16x16x32_bf16 v[34:37], v[172:175], v[188:191], v[34:37]
	v_mfma_f32_16x16x32_bf16 v[22:25], v[164:167], v[196:199], v[22:25]
	v_mfma_f32_16x16x32_bf16 v[18:21], v[172:175], v[196:199], v[18:21]
	v_mfma_f32_16x16x32_bf16 v[6:9], v[164:167], v[204:207], v[6:9]
	v_mfma_f32_16x16x32_bf16 v[2:5], v[172:175], v[204:207], v[2:5]
	v_mfma_f32_16x16x32_bf16 v[54:57], v[168:171], v[184:187], v[54:57]
	v_mfma_f32_16x16x32_bf16 v[50:53], v[176:179], v[184:187], v[50:53]
	v_mfma_f32_16x16x32_bf16 v[38:41], v[168:171], v[192:195], v[38:41]
	v_mfma_f32_16x16x32_bf16 v[34:37], v[176:179], v[192:195], v[34:37]
	v_mfma_f32_16x16x32_bf16 v[22:25], v[168:171], v[200:203], v[22:25]
	v_mfma_f32_16x16x32_bf16 v[18:21], v[176:179], v[200:203], v[18:21]
	v_mfma_f32_16x16x32_bf16 v[6:9], v[168:171], v[208:211], v[6:9]
	v_mfma_f32_16x16x32_bf16 v[2:5], v[176:179], v[208:211], v[2:5]
	s_barrier
	s_add_i32 s66, s66, 2
	s_add_u32 s42, s42, 0x100
	s_addc_u32 s43, s43, 0
	s_add_u32 s64, s64, 0x100
	s_addc_u32 s65, s65, 0
	s_cmp_gt_u32 s66, 13
	s_cbranch_scc0 .LBB0_370
	s_and_b64 vcc, exec, s[12:13]
	s_cbranch_vccz .LBB0_373
	s_barrier

; #define PG8_STAGE(bufoff, gbase, voff) do { _Pragma("unroll") for (int _i = 0; _i < 2; ++_i) \
;         __builtin_amdgcn_global_load_lds((const unsigned*)((const char*)(gbase) + (voff)[_i]), (PG8_LAS unsigned*)(lds + (bufoff) + ldsw + _i * 8192), 16, 0, 0); } while (0)
; #define PG8_LDA(dst, b, h) do { _Pragma("unroll") for (int m = 0; m < 4; ++m) _Pragma("unroll") for (int k = 0; k < 2; ++k) dst[m][k] = *(const PG8_LAS bf16x8*)(lds + PG8_SA(b, h) + aoff + m * 2048 + k * 1024); } while (0)
; #define PG8_LDB(dst, b, h) do { _Pragma("unroll") for (int n = 0; n < 2; ++n) _Pragma("unroll") for (int k = 0; k < 2; ++k) dst[n][k] = *(const PG8_LAS bf16x8*)(lds + PG8_SB(b, h) + boff + n * 2048 + k * 1024); } while (0)
; #define PG8_MMA(ai, bj, At, Bt) do { __builtin_amdgcn_s_setprio(1); _Pragma("unroll") for (int m = 0; m < 4; ++m) _Pragma("unroll") for (int n = 0; n < 2; ++n) _Pragma("unroll") for (int k = 0; k < 2; ++k) \
;         acc[ai][bj][m][n] = __builtin_amdgcn_mfma_f32_16x16x32_bf16(Bt[n][k], At[m][k], acc[ai][bj][m][n], 0, 0, 0); __builtin_amdgcn_s_setprio(0); } while (0)
; #define PG8_WAIT_V(n) asm volatile("s_waitcnt vmcnt(" #n ")" ::: "memory")
; #define PG8_BAR __builtin_amdgcn_s_barrier()
; template <class Epi, class Sched, bool ALIGN_EPI = false, bool SP2 = false>
; __device__ __forceinline__ void gemm_phase(PG8_LAS unsigned char* lds, const Gemm g, const Sched& S, const Epi& E) {
;     ...
;         for (int t = 0; t < nt; t += 2) {
;             const bool last = (t == nt - 2);
;             const char* a1 = cA + (size_t)(t + 1) * kstep;
;             const char* a2 = last ? nA : cA + (size_t)(t + 2) * kstep; const char* b2 = last ? nB : cB + (size_t)(t + 2) * kstep;
;             const char* a3 = a2 + kstep; const char* b3 = b2 + kstep;
;             if (last && has_next) S.a_ready(nxt);
;             if constexpr (SP2) {
;             PG8_LDB(B0, 0, 0); PG8_LDB(B1, 0, 1); PG8_SCHED; PG8_LDA(At, 0, 0); PG8_STAGE(PG8_SA(1, 1), a1 + hstep, voffA);
;             PG8_WAIT_V(8); PG8_WAIT_L(0); PG8_BAR; PG8_MMA(0, 0, At, B0); PG8_MMA(0, 1, At, B1); PG8_BAR; PG8_SCHED;
;             PG8_LDA(At, 0, 1); PG8_STAGE(PG8_SB(0, 0), b2, voffB); PG8_STAGE(PG8_SB(0, 1), b2 + hstep, voffB); PG8_STAGE(PG8_SA(0, 0), a2, voffA);
;             PG8_WAIT_V(8); PG8_WAIT_L(0); PG8_BAR; PG8_MMA(1, 0, At, B0); PG8_MMA(1, 1, At, B1); PG8_BAR; PG8_SCHED;
.LBB0_579:
	ds_read_b128 v[130:133], v178
	ds_read_b128 v[148:151], v178 offset:1024
	ds_read_b128 v[152:155], v178 offset:2048
	ds_read_b128 v[156:159], v178 offset:3072
	ds_read_b128 v[160:163], v179
	ds_read_b128 v[164:167], v179 offset:1024
	ds_read_b128 v[168:171], v179 offset:2048
	ds_read_b128 v[184:187], v179 offset:3072
	s_add_u32 s12, s10, 0xfffc0080
	s_addc_u32 s13, s11, -1
	s_cmp_eq_u32 vcc_lo, 12
	s_cselect_b32 s15, s9, s13
	s_cselect_b32 s14, s67, s12
	s_cselect_b32 s13, s65, s97
	s_cselect_b32 s12, s72, s73
	v_lshl_add_u64 v[220:221], s[10:11], 0, v[140:141]
	s_add_i32 m0, s61, 0xc000
	ds_read_b128 v[188:191], v180
	ds_read_b128 v[192:195], v180 offset:1024
	ds_read_b128 v[196:199], v180 offset:2048
	ds_read_b128 v[200:203], v180 offset:3072
	ds_read_b128 v[204:207], v180 offset:4096
	ds_read_b128 v[208:211], v180 offset:5120
	ds_read_b128 v[212:215], v180 offset:6144
	ds_read_b128 v[216:219], v180 offset:7168
	global_load_lds_dwordx4 v[220:221], off
	v_lshl_add_u64 v[220:221], s[10:11], 0, v[142:143]
	s_add_i32 m0, s61, 0xe000
	s_nop 0
	global_load_lds_dwordx4 v[220:221], off
	s_waitcnt vmcnt(8)
	s_waitcnt lgkmcnt(0)
	s_barrier
	s_waitcnt lgkmcnt(0)
	v_mfma_f32_16x16x32_bf16 v[126:129], v[130:133], v[188:191], v[126:129]
	v_mfma_f32_16x16x32_bf16 v[122:125], v[152:155], v[188:191], v[122:125]
	v_mfma_f32_16x16x32_bf16 v[118:121], v[130:133], v[196:199], v[118:121]
	v_mfma_f32_16x16x32_bf16 v[114:117], v[152:155], v[196:199], v[114:117]
	v_mfma_f32_16x16x32_bf16 v[102:105], v[130:133], v[204:207], v[102:105]
	v_mfma_f32_16x16x32_bf16 v[98:101], v[152:155], v[204:207], v[98:101]
	v_mfma_f32_16x16x32_bf16 v[86:89], v[130:133], v[212:215], v[86:89]
	v_mfma_f32_16x16x32_bf16 v[82:85], v[152:155], v[212:215], v[82:85]
	v_mfma_f32_16x16x32_bf16 v[126:129], v[148:151], v[192:195], v[126:129]
	v_mfma_f32_16x16x32_bf16 v[122:125], v[156:159], v[192:195], v[122:125]
	v_mfma_f32_16x16x32_bf16 v[118:121], v[148:151], v[200:203], v[118:121]
	v_mfma_f32_16x16x32_bf16 v[114:117], v[156:159], v[200:203], v[114:117]
	v_mfma_f32_16x16x32_bf16 v[102:105], v[148:151], v[208:211], v[102:105]
	v_mfma_f32_16x16x32_bf16 v[98:101], v[156:159], v[208:211], v[98:101]
	v_mfma_f32_16x16x32_bf16 v[86:89], v[148:151], v[216:219], v[86:89]
	v_mfma_f32_16x16x32_bf16 v[82:85], v[156:159], v[216:219], v[82:85]
	v_mfma_f32_16x16x32_bf16 v[110:113], v[160:163], v[188:191], v[110:113]
	v_mfma_f32_16x16x32_bf16 v[106:109], v[168:171], v[188:191], v[106:109]
	v_mfma_f32_16x16x32_bf16 v[94:97], v[160:163], v[196:199], v[94:97]
	v_mfma_f32_16x16x32_bf16 v[90:93], v[168:171], v[196:199], v[90:93]
	v_mfma_f32_16x16x32_bf16 v[78:81], v[160:163], v[204:207], v[78:81]
	v_mfma_f32_16x16x32_bf16 v[74:77], v[168:171], v[204:207], v[74:77]
	v_mfma_f32_16x16x32_bf16 v[70:73], v[160:163], v[212:215], v[70:73]
	v_mfma_f32_16x16x32_bf16 v[66:69], v[168:171], v[212:215], v[66:69]
	v_mfma_f32_16x16x32_bf16 v[110:113], v[164:167], v[192:195], v[110:113]
	v_mfma_f32_16x16x32_bf16 v[106:109], v[184:187], v[192:195], v[106:109]
	v_mfma_f32_16x16x32_bf16 v[94:97], v[164:167], v[200:203], v[94:97]
	v_mfma_f32_16x16x32_bf16 v[90:93], v[184:187], v[200:203], v[90:93]
	v_mfma_f32_16x16x32_bf16 v[78:81], v[164:167], v[208:211], v[78:81]
	v_mfma_f32_16x16x32_bf16 v[74:77], v[184:187], v[208:211], v[74:77]
	v_mfma_f32_16x16x32_bf16 v[70:73], v[164:167], v[216:219], v[70:73]
	v_mfma_f32_16x16x32_bf16 v[66:69], v[184:187], v[216:219], v[66:69]
	s_barrier
	s_add_i32 s34, s86, s77
	v_lshl_add_u64 v[220:221], s[12:13], 0, v[134:135]
	s_mov_b32 m0, s34
	ds_read_b128 v[188:191], v180 offset:16384
	ds_read_b128 v[192:195], v180 offset:17408
	ds_read_b128 v[196:199], v180 offset:18432
	ds_read_b128 v[200:203], v180 offset:19456
	ds_read_b128 v[204:207], v180 offset:20480
	ds_read_b128 v[208:211], v180 offset:21504
	ds_read_b128 v[212:215], v180 offset:22528
	ds_read_b128 v[216:219], v180 offset:23552
	global_load_lds_dwordx4 v[220:221], off
	s_add_i32 m0, s34, 0x2000
	s_add_u32 s34, s12, 0x40000
	v_lshl_add_u64 v[222:223], s[12:13], 0, v[136:137]
	s_addc_u32 s35, s13, 0
	s_add_i32 vcc_hi, s87, s77
	global_load_lds_dwordx4 v[222:223], off
	v_lshl_add_u64 v[224:225], s[34:35], 0, v[134:135]
	s_mov_b32 m0, vcc_hi
	v_lshl_add_u64 v[226:227], s[14:15], 0, v[136:137]
	global_load_lds_dwordx4 v[224:225], off
	v_lshl_add_u64 v[224:225], s[34:35], 0, v[136:137]
	s_add_i32 m0, vcc_hi, 0x2000
	s_nop 0
	global_load_lds_dwordx4 v[224:225], off
	v_lshl_add_u64 v[224:225], s[14:15], 0, v[134:135]
	s_mov_b32 m0, s61
	s_nop 0
	global_load_lds_dwordx4 v[224:225], off
	s_mov_b32 m0, s78
	s_nop 0
	global_load_lds_dwordx4 v[226:227], off
	s_waitcnt vmcnt(8)
	s_waitcnt lgkmcnt(0)
	s_barrier
; #define PG8_STAGE(bufoff, gbase, voff) do { _Pragma("unroll") for (int _i = 0; _i < 2; ++_i) \
;         __builtin_amdgcn_global_load_lds((const unsigned*)((const char*)(gbase) + (voff)[_i]), (PG8_LAS unsigned*)(lds + (bufoff) + ldsw + _i * 8192), 16, 0, 0); } while (0)
; #define PG8_LDA(dst, b, h) do { _Pragma("unroll") for (int m = 0; m < 4; ++m) _Pragma("unroll") for (int k = 0; k < 2; ++k) dst[m][k] = *(const PG8_LAS bf16x8*)(lds + PG8_SA(b, h) + aoff + m * 2048 + k * 1024); } while (0)
; #define PG8_LDB(dst, b, h) do { _Pragma("unroll") for (int n = 0; n < 2; ++n) _Pragma("unroll") for (int k = 0; k < 2; ++k) dst[n][k] = *(const PG8_LAS bf16x8*)(lds + PG8_SB(b, h) + boff + n * 2048 + k * 1024); } while (0)
; #define PG8_MMA(ai, bj, At, Bt) do { __builtin_amdgcn_s_setprio(1); _Pragma("unroll") for (int m = 0; m < 4; ++m) _Pragma("unroll") for (int n = 0; n < 2; ++n) _Pragma("unroll") for (int k = 0; k < 2; ++k) \
;         acc[ai][bj][m][n] = __builtin_amdgcn_mfma_f32_16x16x32_bf16(Bt[n][k], At[m][k], acc[ai][bj][m][n], 0, 0, 0); __builtin_amdgcn_s_setprio(0); } while (0)
; #define PG8_WAIT_V(n) asm volatile("s_waitcnt vmcnt(" #n ")" ::: "memory")
; #define PG8_WAIT_L(n) asm volatile("s_waitcnt lgkmcnt(" #n ")" ::: "memory")
; #define PG8_BAR __builtin_amdgcn_s_barrier()
; #define PG8_SCHED __builtin_amdgcn_sched_barrier(0)
; template <class Epi, class Sched, bool ALIGN_EPI = false, bool SP2 = false>
; __device__ __forceinline__ void gemm_phase(PG8_LAS unsigned char* lds, const Gemm g, const Sched& S, const Epi& E) {
;     ...
;             PG8_LDA(At, 0, 1); PG8_STAGE(PG8_SB(0, 0), b2, voffB); PG8_STAGE(PG8_SB(0, 1), b2 + hstep, voffB); PG8_STAGE(PG8_SA(0, 0), a2, voffA);
;             PG8_WAIT_V(8); PG8_WAIT_L(0); PG8_BAR; PG8_MMA(1, 0, At, B0); PG8_MMA(1, 1, At, B1); PG8_BAR; PG8_SCHED;
;             PG8_LDB(B0, 1, 0); PG8_LDB(B1, 1, 1); PG8_SCHED; PG8_LDA(At, 1, 0); PG8_STAGE(PG8_SA(0, 1), a2 + hstep, voffA);
;             PG8_WAIT_V(8); PG8_WAIT_L(0); PG8_BAR; PG8_MMA(0, 0, At, B0); PG8_MMA(0, 1, At, B1); PG8_BAR; PG8_SCHED;
;             PG8_LDA(At, 1, 1); PG8_STAGE(PG8_SB(1, 0), b3, voffB); PG8_STAGE(PG8_SB(1, 1), b3 + hstep, voffB); PG8_STAGE(PG8_SA(1, 0), a3, voffA);
	s_waitcnt lgkmcnt(0)
	v_mfma_f32_16x16x32_bf16 v[62:65], v[130:133], v[188:191], v[62:65]
	v_mfma_f32_16x16x32_bf16 v[58:61], v[152:155], v[188:191], v[58:61]
	v_mfma_f32_16x16x32_bf16 v[54:57], v[130:133], v[196:199], v[54:57]
	v_mfma_f32_16x16x32_bf16 v[50:53], v[152:155], v[196:199], v[50:53]
	v_mfma_f32_16x16x32_bf16 v[38:41], v[130:133], v[204:207], v[38:41]
	v_mfma_f32_16x16x32_bf16 v[34:37], v[152:155], v[204:207], v[34:37]
	v_mfma_f32_16x16x32_bf16 v[22:25], v[130:133], v[212:215], v[22:25]
	v_mfma_f32_16x16x32_bf16 v[18:21], v[152:155], v[212:215], v[18:21]
	v_mfma_f32_16x16x32_bf16 v[62:65], v[148:151], v[192:195], v[62:65]
	v_mfma_f32_16x16x32_bf16 v[58:61], v[156:159], v[192:195], v[58:61]
	v_mfma_f32_16x16x32_bf16 v[54:57], v[148:151], v[200:203], v[54:57]
	v_mfma_f32_16x16x32_bf16 v[50:53], v[156:159], v[200:203], v[50:53]
	v_mfma_f32_16x16x32_bf16 v[38:41], v[148:151], v[208:211], v[38:41]
	v_mfma_f32_16x16x32_bf16 v[34:37], v[156:159], v[208:211], v[34:37]
	v_mfma_f32_16x16x32_bf16 v[22:25], v[148:151], v[216:219], v[22:25]
	v_mfma_f32_16x16x32_bf16 v[18:21], v[156:159], v[216:219], v[18:21]
	v_mfma_f32_16x16x32_bf16 v[46:49], v[160:163], v[188:191], v[46:49]
	v_mfma_f32_16x16x32_bf16 v[42:45], v[168:171], v[188:191], v[42:45]
	v_mfma_f32_16x16x32_bf16 v[30:33], v[160:163], v[196:199], v[30:33]
	v_mfma_f32_16x16x32_bf16 v[26:29], v[168:171], v[196:199], v[26:29]
	v_mfma_f32_16x16x32_bf16 v[14:17], v[160:163], v[204:207], v[14:17]
	v_mfma_f32_16x16x32_bf16 v[10:13], v[168:171], v[204:207], v[10:13]
	v_mfma_f32_16x16x32_bf16 v[6:9], v[160:163], v[212:215], v[6:9]
	v_mfma_f32_16x16x32_bf16 v[2:5], v[168:171], v[212:215], v[2:5]
	v_mfma_f32_16x16x32_bf16 v[46:49], v[164:167], v[192:195], v[46:49]
	v_mfma_f32_16x16x32_bf16 v[42:45], v[184:187], v[192:195], v[42:45]
	v_mfma_f32_16x16x32_bf16 v[30:33], v[164:167], v[200:203], v[30:33]
	v_mfma_f32_16x16x32_bf16 v[26:29], v[184:187], v[200:203], v[26:29]
	v_mfma_f32_16x16x32_bf16 v[14:17], v[164:167], v[208:211], v[14:17]
	v_mfma_f32_16x16x32_bf16 v[10:13], v[184:187], v[208:211], v[10:13]
	v_mfma_f32_16x16x32_bf16 v[6:9], v[164:167], v[216:219], v[6:9]
	v_mfma_f32_16x16x32_bf16 v[2:5], v[184:187], v[216:219], v[2:5]
	s_barrier
	s_add_i32 s34, 0, 0x18000
	v_add_u32_e32 v138, s34, v173
	s_add_i32 s35, 0, 0x1c000
	ds_read_b128 v[130:133], v138
	ds_read_b128 v[148:151], v138 offset:1024
	ds_read_b128 v[152:155], v138 offset:2048
	ds_read_b128 v[156:159], v138 offset:3072
	v_add_u32_e32 v138, s35, v173
	ds_read_b128 v[160:163], v138
	ds_read_b128 v[164:167], v138 offset:1024
	ds_read_b128 v[168:171], v138 offset:2048
	ds_read_b128 v[184:187], v138 offset:3072
	s_add_u32 s14, s14, 0x40000
	s_addc_u32 s15, s15, 0
	s_mov_b32 m0, s79
	v_lshl_add_u64 v[228:229], s[14:15], 0, v[134:135]
	ds_read_b128 v[188:191], v180 offset:32768
	ds_read_b128 v[192:195], v180 offset:33792
	ds_read_b128 v[196:199], v180 offset:34816
	ds_read_b128 v[200:203], v180 offset:35840
	ds_read_b128 v[204:207], v180 offset:36864
	ds_read_b128 v[208:211], v180 offset:37888
	ds_read_b128 v[212:215], v180 offset:38912
	ds_read_b128 v[216:219], v180 offset:39936
	global_load_lds_dwordx4 v[228:229], off
	v_lshl_add_u64 v[228:229], s[14:15], 0, v[136:137]
	s_mov_b32 m0, s80
	s_nop 0
	global_load_lds_dwordx4 v[228:229], off
	s_waitcnt vmcnt(8)
	s_waitcnt lgkmcnt(0)
	s_barrier
	s_waitcnt lgkmcnt(0)
	v_mfma_f32_16x16x32_bf16 v[126:129], v[130:133], v[188:191], v[126:129]
	v_mfma_f32_16x16x32_bf16 v[122:125], v[152:155], v[188:191], v[122:125]
	v_mfma_f32_16x16x32_bf16 v[118:121], v[130:133], v[196:199], v[118:121]
	v_mfma_f32_16x16x32_bf16 v[114:117], v[152:155], v[196:199], v[114:117]
	v_mfma_f32_16x16x32_bf16 v[102:105], v[130:133], v[204:207], v[102:105]
	v_mfma_f32_16x16x32_bf16 v[98:101], v[152:155], v[204:207], v[98:101]
	v_mfma_f32_16x16x32_bf16 v[86:89], v[130:133], v[212:215], v[86:89]
	v_mfma_f32_16x16x32_bf16 v[82:85], v[152:155], v[212:215], v[82:85]
	v_mfma_f32_16x16x32_bf16 v[126:129], v[148:151], v[192:195], v[126:129]
	v_mfma_f32_16x16x32_bf16 v[122:125], v[156:159], v[192:195], v[122:125]
	v_mfma_f32_16x16x32_bf16 v[118:121], v[148:151], v[200:203], v[118:121]
	v_mfma_f32_16x16x32_bf16 v[114:117], v[156:159], v[200:203], v[114:117]
	v_mfma_f32_16x16x32_bf16 v[102:105], v[148:151], v[208:211], v[102:105]
	v_mfma_f32_16x16x32_bf16 v[98:101], v[156:159], v[208:211], v[98:101]
	v_mfma_f32_16x16x32_bf16 v[86:89], v[148:151], v[216:219], v[86:89]
	v_mfma_f32_16x16x32_bf16 v[82:85], v[156:159], v[216:219], v[82:85]
	v_mfma_f32_16x16x32_bf16 v[110:113], v[160:163], v[188:191], v[110:113]
	v_mfma_f32_16x16x32_bf16 v[106:109], v[168:171], v[188:191], v[106:109]
	v_mfma_f32_16x16x32_bf16 v[94:97], v[160:163], v[196:199], v[94:97]
	v_mfma_f32_16x16x32_bf16 v[90:93], v[168:171], v[196:199], v[90:93]
	v_mfma_f32_16x16x32_bf16 v[78:81], v[160:163], v[204:207], v[78:81]
	v_mfma_f32_16x16x32_bf16 v[74:77], v[168:171], v[204:207], v[74:77]
	v_mfma_f32_16x16x32_bf16 v[70:73], v[160:163], v[212:215], v[70:73]
	v_mfma_f32_16x16x32_bf16 v[66:69], v[168:171], v[212:215], v[66:69]
	v_mfma_f32_16x16x32_bf16 v[110:113], v[164:167], v[192:195], v[110:113]
	v_mfma_f32_16x16x32_bf16 v[106:109], v[184:187], v[192:195], v[106:109]
	v_mfma_f32_16x16x32_bf16 v[94:97], v[164:167], v[200:203], v[94:97]
	v_mfma_f32_16x16x32_bf16 v[90:93], v[184:187], v[200:203], v[90:93]
	v_mfma_f32_16x16x32_bf16 v[78:81], v[164:167], v[208:211], v[78:81]
	v_mfma_f32_16x16x32_bf16 v[74:77], v[184:187], v[208:211], v[74:77]
	v_mfma_f32_16x16x32_bf16 v[70:73], v[164:167], v[216:219], v[70:73]
	v_mfma_f32_16x16x32_bf16 v[66:69], v[184:187], v[216:219], v[66:69]
	s_barrier
; #define PG8_STAGE(bufoff, gbase, voff) do { _Pragma("unroll") for (int _i = 0; _i < 2; ++_i) \
;         __builtin_amdgcn_global_load_lds((const unsigned*)((const char*)(gbase) + (voff)[_i]), (PG8_LAS unsigned*)(lds + (bufoff) + ldsw + _i * 8192), 16, 0, 0); } while (0)
; #define PG8_LDA(dst, b, h) do { _Pragma("unroll") for (int m = 0; m < 4; ++m) _Pragma("unroll") for (int k = 0; k < 2; ++k) dst[m][k] = *(const PG8_LAS bf16x8*)(lds + PG8_SA(b, h) + aoff + m * 2048 + k * 1024); } while (0)
; #define PG8_MMA(ai, bj, At, Bt) do { __builtin_amdgcn_s_setprio(1); _Pragma("unroll") for (int m = 0; m < 4; ++m) _Pragma("unroll") for (int n = 0; n < 2; ++n) _Pragma("unroll") for (int k = 0; k < 2; ++k) \
;         acc[ai][bj][m][n] = __builtin_amdgcn_mfma_f32_16x16x32_bf16(Bt[n][k], At[m][k], acc[ai][bj][m][n], 0, 0, 0); __builtin_amdgcn_s_setprio(0); } while (0)
; #define PG8_WAIT_V(n) asm volatile("s_waitcnt vmcnt(" #n ")" ::: "memory")
; #define PG8_WAIT_L(n) asm volatile("s_waitcnt lgkmcnt(" #n ")" ::: "memory")
; #define PG8_BAR __builtin_amdgcn_s_barrier()
; #define PG8_SCHED __builtin_amdgcn_sched_barrier(0)
; template <class Epi, class Sched, bool ALIGN_EPI = false, bool SP2 = false>
; __device__ __forceinline__ void gemm_phase(PG8_LAS unsigned char* lds, const Gemm g, const Sched& S, const Epi& E) {
;     ...
;             PG8_LDA(At, 1, 1); PG8_STAGE(PG8_SB(1, 0), b3, voffB); PG8_STAGE(PG8_SB(1, 1), b3 + hstep, voffB); PG8_STAGE(PG8_SA(1, 0), a3, voffA);
;             PG8_WAIT_V(8); PG8_WAIT_L(0); PG8_BAR; PG8_MMA(1, 0, At, B0); PG8_MMA(1, 1, At, B1); PG8_BAR; PG8_SCHED;
	s_add_i32 s14, s34, s77
	v_lshl_add_u64 v[220:221], v[220:221], 0, s[56:57]
	s_mov_b32 m0, s14
	ds_read_b128 v[188:191], v180 offset:49152
	ds_read_b128 v[192:195], v180 offset:50176
	ds_read_b128 v[196:199], v180 offset:51200
	ds_read_b128 v[200:203], v180 offset:52224
	ds_read_b128 v[204:207], v180 offset:53248
	ds_read_b128 v[208:211], v180 offset:54272
	ds_read_b128 v[212:215], v180 offset:55296
	ds_read_b128 v[216:219], v180 offset:56320
	global_load_lds_dwordx4 v[220:221], off
	s_add_i32 m0, s14, 0x2000
	s_add_u32 s12, s12, 0x40080
	v_lshl_add_u64 v[220:221], v[222:223], 0, s[56:57]
	s_addc_u32 s13, s13, 0
	s_add_i32 s14, s35, s77
	global_load_lds_dwordx4 v[220:221], off
	v_lshl_add_u64 v[220:221], s[12:13], 0, v[134:135]
	s_mov_b32 m0, s14
	s_nop 0
	global_load_lds_dwordx4 v[220:221], off
	v_lshl_add_u64 v[220:221], s[12:13], 0, v[136:137]
	s_add_i32 m0, s14, 0x2000
	s_nop 0
	global_load_lds_dwordx4 v[220:221], off
	v_lshl_add_u64 v[220:221], v[224:225], 0, s[56:57]
	s_mov_b32 m0, s82
	s_nop 0
	global_load_lds_dwordx4 v[220:221], off
	v_lshl_add_u64 v[220:221], v[226:227], 0, s[56:57]
	s_mov_b32 m0, s83
	s_nop 0
	global_load_lds_dwordx4 v[220:221], off
	s_waitcnt vmcnt(8)
	s_waitcnt lgkmcnt(0)
	s_barrier
	s_waitcnt lgkmcnt(0)
	v_mfma_f32_16x16x32_bf16 v[62:65], v[130:133], v[188:191], v[62:65]
	v_mfma_f32_16x16x32_bf16 v[58:61], v[152:155], v[188:191], v[58:61]
	v_mfma_f32_16x16x32_bf16 v[54:57], v[130:133], v[196:199], v[54:57]
	v_mfma_f32_16x16x32_bf16 v[50:53], v[152:155], v[196:199], v[50:53]
	v_mfma_f32_16x16x32_bf16 v[38:41], v[130:133], v[204:207], v[38:41]
	v_mfma_f32_16x16x32_bf16 v[34:37], v[152:155], v[204:207], v[34:37]
	v_mfma_f32_16x16x32_bf16 v[22:25], v[130:133], v[212:215], v[22:25]
	v_mfma_f32_16x16x32_bf16 v[18:21], v[152:155], v[212:215], v[18:21]
	v_mfma_f32_16x16x32_bf16 v[62:65], v[148:151], v[192:195], v[62:65]
	v_mfma_f32_16x16x32_bf16 v[58:61], v[156:159], v[192:195], v[58:61]
	v_mfma_f32_16x16x32_bf16 v[54:57], v[148:151], v[200:203], v[54:57]
	v_mfma_f32_16x16x32_bf16 v[50:53], v[156:159], v[200:203], v[50:53]
	v_mfma_f32_16x16x32_bf16 v[38:41], v[148:151], v[208:211], v[38:41]
	v_mfma_f32_16x16x32_bf16 v[34:37], v[156:159], v[208:211], v[34:37]
	v_mfma_f32_16x16x32_bf16 v[22:25], v[148:151], v[216:219], v[22:25]
	v_mfma_f32_16x16x32_bf16 v[18:21], v[156:159], v[216:219], v[18:21]
	v_mfma_f32_16x16x32_bf16 v[46:49], v[160:163], v[188:191], v[46:49]
	v_mfma_f32_16x16x32_bf16 v[42:45], v[168:171], v[188:191], v[42:45]
	v_mfma_f32_16x16x32_bf16 v[30:33], v[160:163], v[196:199], v[30:33]
	v_mfma_f32_16x16x32_bf16 v[26:29], v[168:171], v[196:199], v[26:29]
	v_mfma_f32_16x16x32_bf16 v[14:17], v[160:163], v[204:207], v[14:17]
	v_mfma_f32_16x16x32_bf16 v[10:13], v[168:171], v[204:207], v[10:13]
	v_mfma_f32_16x16x32_bf16 v[6:9], v[160:163], v[212:215], v[6:9]
	v_mfma_f32_16x16x32_bf16 v[2:5], v[168:171], v[212:215], v[2:5]
	v_mfma_f32_16x16x32_bf16 v[46:49], v[164:167], v[192:195], v[46:49]
	v_mfma_f32_16x16x32_bf16 v[42:45], v[184:187], v[192:195], v[42:45]
	v_mfma_f32_16x16x32_bf16 v[30:33], v[164:167], v[200:203], v[30:33]
	v_mfma_f32_16x16x32_bf16 v[26:29], v[184:187], v[200:203], v[26:29]
	v_mfma_f32_16x16x32_bf16 v[14:17], v[164:167], v[208:211], v[14:17]
	v_mfma_f32_16x16x32_bf16 v[10:13], v[184:187], v[208:211], v[10:13]
	v_mfma_f32_16x16x32_bf16 v[6:9], v[164:167], v[216:219], v[6:9]
	v_mfma_f32_16x16x32_bf16 v[2:5], v[184:187], v[216:219], v[2:5]
	s_barrier
	s_add_i32 vcc_lo, vcc_lo, 2
	s_add_u32 s10, s10, 0x100
	s_addc_u32 s11, s11, 0
	s_add_u32 s73, s73, 0x100
	s_addc_u32 s97, s97, 0
	s_cmp_gt_u32 vcc_lo, 13
	s_cbranch_scc0 .LBB0_579
	s_and_b64 vcc, exec, s[58:59]
	s_cbranch_vccz .LBB0_582
	s_barrier

; #define PG8_STAGE(bufoff, gbase, voff) do { _Pragma("unroll") for (int _i = 0; _i < 2; ++_i) \
;         __builtin_amdgcn_global_load_lds((const unsigned*)((const char*)(gbase) + (voff)[_i]), (PG8_LAS unsigned*)(lds + (bufoff) + ldsw + _i * 8192), 16, 0, 0); } while (0)
; #define PG8_LDA(dst, b, h) do { _Pragma("unroll") for (int m = 0; m < 4; ++m) _Pragma("unroll") for (int k = 0; k < 2; ++k) dst[m][k] = *(const PG8_LAS bf16x8*)(lds + PG8_SA(b, h) + aoff + m * 2048 + k * 1024); } while (0)
; #define PG8_LDB(dst, b, h) do { _Pragma("unroll") for (int n = 0; n < 2; ++n) _Pragma("unroll") for (int k = 0; k < 2; ++k) dst[n][k] = *(const PG8_LAS bf16x8*)(lds + PG8_SB(b, h) + boff + n * 2048 + k * 1024); } while (0)
; #define PG8_MMA(ai, bj, At, Bt) do { __builtin_amdgcn_s_setprio(1); _Pragma("unroll") for (int m = 0; m < 4; ++m) _Pragma("unroll") for (int n = 0; n < 2; ++n) _Pragma("unroll") for (int k = 0; k < 2; ++k) \
;         acc[ai][bj][m][n] = __builtin_amdgcn_mfma_f32_16x16x32_bf16(Bt[n][k], At[m][k], acc[ai][bj][m][n], 0, 0, 0); __builtin_amdgcn_s_setprio(0); } while (0)
; #define PG8_WAIT_V(n) asm volatile("s_waitcnt vmcnt(" #n ")" ::: "memory")
; #define PG8_BAR __builtin_amdgcn_s_barrier()
; template <class Epi, class Sched, bool ALIGN_EPI = false, bool SP2 = false>
; __device__ __forceinline__ void gemm_phase(PG8_LAS unsigned char* lds, const Gemm g, const Sched& S, const Epi& E) {
;     ...
;         for (int t = 0; t < nt; t += 2) {
;             const bool last = (t == nt - 2);
;             const char* a1 = cA + (size_t)(t + 1) * kstep;
;             const char* a2 = last ? nA : cA + (size_t)(t + 2) * kstep; const char* b2 = last ? nB : cB + (size_t)(t + 2) * kstep;
;             const char* a3 = a2 + kstep; const char* b3 = b2 + kstep;
;             if (last && has_next) S.a_ready(nxt);
;             if constexpr (SP2) {
;             PG8_LDB(B0, 0, 0); PG8_LDB(B1, 0, 1); PG8_SCHED; PG8_LDA(At, 0, 0); PG8_STAGE(PG8_SA(1, 1), a1 + hstep, voffA);
;             PG8_WAIT_V(8); PG8_WAIT_L(0); PG8_BAR; PG8_MMA(0, 0, At, B0); PG8_MMA(0, 1, At, B1); PG8_BAR; PG8_SCHED;
;             PG8_LDA(At, 0, 1); PG8_STAGE(PG8_SB(0, 0), b2, voffB); PG8_STAGE(PG8_SB(0, 1), b2 + hstep, voffB); PG8_STAGE(PG8_SA(0, 0), a2, voffA);
;             PG8_WAIT_V(8); PG8_WAIT_L(0); PG8_BAR; PG8_MMA(1, 0, At, B0); PG8_MMA(1, 1, At, B1); PG8_BAR; PG8_SCHED;
.LBB0_1331:
	ds_read_b128 v[74:77], v220
	ds_read_b128 v[82:85], v220 offset:1024
	ds_read_b128 v[86:89], v220 offset:2048
	ds_read_b128 v[90:93], v220 offset:3072
	ds_read_b128 v[146:149], v221
	ds_read_b128 v[150:153], v221 offset:1024
	ds_read_b128 v[154:157], v221 offset:2048
	ds_read_b128 v[158:161], v221 offset:3072
	s_add_u32 s34, s12, 0xfffc0080
	s_addc_u32 s35, s13, -1
	s_cmp_eq_u32 s80, 12
	s_cselect_b32 s65, s43, s35
	s_cselect_b32 s64, s55, s34
	s_cselect_b32 s63, s53, s79
	s_cselect_b32 s62, s61, s78
	v_lshl_add_u64 v[182:183], s[12:13], 0, v[190:191]
	s_add_i32 m0, s19, 0xc000
	ds_read_b128 v[162:165], v222
	ds_read_b128 v[166:169], v222 offset:1024
	ds_read_b128 v[170:173], v222 offset:2048
	ds_read_b128 v[174:177], v222 offset:3072
	ds_read_b128 v[178:181], v222 offset:4096
	ds_read_b128 v[198:201], v222 offset:5120
	ds_read_b128 v[202:205], v222 offset:6144
	ds_read_b128 v[206:209], v222 offset:7168
	global_load_lds_dwordx4 v[182:183], off
	v_lshl_add_u64 v[182:183], s[12:13], 0, v[192:193]
	s_add_i32 m0, s19, 0xe000
	s_nop 0
	global_load_lds_dwordx4 v[182:183], off
	s_waitcnt vmcnt(8)
	s_waitcnt lgkmcnt(0)
	s_barrier
	s_waitcnt lgkmcnt(0)
	v_mfma_f32_16x16x32_bf16 v[142:145], v[74:77], v[162:165], v[142:145]
	v_mfma_f32_16x16x32_bf16 v[138:141], v[86:89], v[162:165], v[138:141]
	v_mfma_f32_16x16x32_bf16 v[134:137], v[74:77], v[170:173], v[134:137]
	v_mfma_f32_16x16x32_bf16 v[122:125], v[86:89], v[170:173], v[122:125]
	v_mfma_f32_16x16x32_bf16 v[110:113], v[74:77], v[178:181], v[110:113]
	v_mfma_f32_16x16x32_bf16 v[106:109], v[86:89], v[178:181], v[106:109]
	v_mfma_f32_16x16x32_bf16 v[102:105], v[74:77], v[202:205], v[102:105]
	v_mfma_f32_16x16x32_bf16 v[78:81], v[86:89], v[202:205], v[78:81]
	v_mfma_f32_16x16x32_bf16 v[142:145], v[82:85], v[166:169], v[142:145]
	v_mfma_f32_16x16x32_bf16 v[138:141], v[90:93], v[166:169], v[138:141]
	v_mfma_f32_16x16x32_bf16 v[134:137], v[82:85], v[174:177], v[134:137]
	v_mfma_f32_16x16x32_bf16 v[122:125], v[90:93], v[174:177], v[122:125]
	v_mfma_f32_16x16x32_bf16 v[110:113], v[82:85], v[198:201], v[110:113]
	v_mfma_f32_16x16x32_bf16 v[106:109], v[90:93], v[198:201], v[106:109]
	v_mfma_f32_16x16x32_bf16 v[102:105], v[82:85], v[206:209], v[102:105]
	v_mfma_f32_16x16x32_bf16 v[78:81], v[90:93], v[206:209], v[78:81]
	v_mfma_f32_16x16x32_bf16 v[130:133], v[146:149], v[162:165], v[130:133]
	v_mfma_f32_16x16x32_bf16 v[126:129], v[154:157], v[162:165], v[126:129]
	v_mfma_f32_16x16x32_bf16 v[118:121], v[146:149], v[170:173], v[118:121]
	v_mfma_f32_16x16x32_bf16 v[114:117], v[154:157], v[170:173], v[114:117]
	v_mfma_f32_16x16x32_bf16 v[98:101], v[146:149], v[178:181], v[98:101]
	v_mfma_f32_16x16x32_bf16 v[94:97], v[154:157], v[178:181], v[94:97]
	v_mfma_f32_16x16x32_bf16 v[70:73], v[146:149], v[202:205], v[70:73]
	v_mfma_f32_16x16x32_bf16 v[66:69], v[154:157], v[202:205], v[66:69]
	v_mfma_f32_16x16x32_bf16 v[130:133], v[150:153], v[166:169], v[130:133]
	v_mfma_f32_16x16x32_bf16 v[126:129], v[158:161], v[166:169], v[126:129]
	v_mfma_f32_16x16x32_bf16 v[118:121], v[150:153], v[174:177], v[118:121]
	v_mfma_f32_16x16x32_bf16 v[114:117], v[158:161], v[174:177], v[114:117]
	v_mfma_f32_16x16x32_bf16 v[98:101], v[150:153], v[198:201], v[98:101]
	v_mfma_f32_16x16x32_bf16 v[94:97], v[158:161], v[198:201], v[94:97]
	v_mfma_f32_16x16x32_bf16 v[70:73], v[150:153], v[206:209], v[70:73]
	v_mfma_f32_16x16x32_bf16 v[66:69], v[158:161], v[206:209], v[66:69]
	s_barrier
	s_add_i32 s34, s76, s3
	v_lshl_add_u64 v[182:183], s[62:63], 0, v[184:185]
	s_mov_b32 m0, s34
	ds_read_b128 v[162:165], v222 offset:16384
	ds_read_b128 v[166:169], v222 offset:17408
	ds_read_b128 v[170:173], v222 offset:18432
	ds_read_b128 v[174:177], v222 offset:19456
	ds_read_b128 v[178:181], v222 offset:20480
	ds_read_b128 v[198:201], v222 offset:21504
	ds_read_b128 v[202:205], v222 offset:22528
	ds_read_b128 v[206:209], v222 offset:23552
	global_load_lds_dwordx4 v[182:183], off
	s_add_i32 m0, s34, 0x2000
	s_add_u32 s34, s62, 0x40000
	v_lshl_add_u64 v[210:211], s[62:63], 0, v[186:187]
	s_addc_u32 s35, s63, 0
	s_add_i32 s81, s77, s3
	global_load_lds_dwordx4 v[210:211], off
	v_lshl_add_u64 v[212:213], s[34:35], 0, v[184:185]
	s_mov_b32 m0, s81
	v_lshl_add_u64 v[214:215], s[64:65], 0, v[186:187]
	global_load_lds_dwordx4 v[212:213], off
	v_lshl_add_u64 v[212:213], s[34:35], 0, v[186:187]
	s_add_i32 m0, s81, 0x2000
	s_nop 0
	global_load_lds_dwordx4 v[212:213], off
	v_lshl_add_u64 v[212:213], s[64:65], 0, v[184:185]
	s_mov_b32 m0, s19
	s_nop 0
	global_load_lds_dwordx4 v[212:213], off
	s_mov_b32 m0, s66
	s_nop 0
	global_load_lds_dwordx4 v[214:215], off
	s_waitcnt vmcnt(8)
	s_waitcnt lgkmcnt(0)
	s_barrier
; #define PG8_STAGE(bufoff, gbase, voff) do { _Pragma("unroll") for (int _i = 0; _i < 2; ++_i) \
;         __builtin_amdgcn_global_load_lds((const unsigned*)((const char*)(gbase) + (voff)[_i]), (PG8_LAS unsigned*)(lds + (bufoff) + ldsw + _i * 8192), 16, 0, 0); } while (0)
; #define PG8_LDA(dst, b, h) do { _Pragma("unroll") for (int m = 0; m < 4; ++m) _Pragma("unroll") for (int k = 0; k < 2; ++k) dst[m][k] = *(const PG8_LAS bf16x8*)(lds + PG8_SA(b, h) + aoff + m * 2048 + k * 1024); } while (0)
; #define PG8_LDB(dst, b, h) do { _Pragma("unroll") for (int n = 0; n < 2; ++n) _Pragma("unroll") for (int k = 0; k < 2; ++k) dst[n][k] = *(const PG8_LAS bf16x8*)(lds + PG8_SB(b, h) + boff + n * 2048 + k * 1024); } while (0)
; #define PG8_MMA(ai, bj, At, Bt) do { __builtin_amdgcn_s_setprio(1); _Pragma("unroll") for (int m = 0; m < 4; ++m) _Pragma("unroll") for (int n = 0; n < 2; ++n) _Pragma("unroll") for (int k = 0; k < 2; ++k) \
;         acc[ai][bj][m][n] = __builtin_amdgcn_mfma_f32_16x16x32_bf16(Bt[n][k], At[m][k], acc[ai][bj][m][n], 0, 0, 0); __builtin_amdgcn_s_setprio(0); } while (0)
; #define PG8_WAIT_V(n) asm volatile("s_waitcnt vmcnt(" #n ")" ::: "memory")
; #define PG8_WAIT_L(n) asm volatile("s_waitcnt lgkmcnt(" #n ")" ::: "memory")
; #define PG8_BAR __builtin_amdgcn_s_barrier()
; #define PG8_SCHED __builtin_amdgcn_sched_barrier(0)
; template <class Epi, class Sched, bool ALIGN_EPI = false, bool SP2 = false>
; __device__ __forceinline__ void gemm_phase(PG8_LAS unsigned char* lds, const Gemm g, const Sched& S, const Epi& E) {
;     ...
;             PG8_LDA(At, 0, 1); PG8_STAGE(PG8_SB(0, 0), b2, voffB); PG8_STAGE(PG8_SB(0, 1), b2 + hstep, voffB); PG8_STAGE(PG8_SA(0, 0), a2, voffA);
;             PG8_WAIT_V(8); PG8_WAIT_L(0); PG8_BAR; PG8_MMA(1, 0, At, B0); PG8_MMA(1, 1, At, B1); PG8_BAR; PG8_SCHED;
;             PG8_LDB(B0, 1, 0); PG8_LDB(B1, 1, 1); PG8_SCHED; PG8_LDA(At, 1, 0); PG8_STAGE(PG8_SA(0, 1), a2 + hstep, voffA);
;             PG8_WAIT_V(8); PG8_WAIT_L(0); PG8_BAR; PG8_MMA(0, 0, At, B0); PG8_MMA(0, 1, At, B1); PG8_BAR; PG8_SCHED;
;             PG8_LDA(At, 1, 1); PG8_STAGE(PG8_SB(1, 0), b3, voffB); PG8_STAGE(PG8_SB(1, 1), b3 + hstep, voffB); PG8_STAGE(PG8_SA(1, 0), a3, voffA);
	s_waitcnt lgkmcnt(0)
	v_mfma_f32_16x16x32_bf16 v[62:65], v[74:77], v[162:165], v[62:65]
	v_mfma_f32_16x16x32_bf16 v[58:61], v[86:89], v[162:165], v[58:61]
	v_mfma_f32_16x16x32_bf16 v[54:57], v[74:77], v[170:173], v[54:57]
	v_mfma_f32_16x16x32_bf16 v[42:45], v[86:89], v[170:173], v[42:45]
	v_mfma_f32_16x16x32_bf16 v[30:33], v[74:77], v[178:181], v[30:33]
	v_mfma_f32_16x16x32_bf16 v[26:29], v[86:89], v[178:181], v[26:29]
	v_mfma_f32_16x16x32_bf16 v[22:25], v[74:77], v[202:205], v[22:25]
	v_mfma_f32_16x16x32_bf16 v[10:13], v[86:89], v[202:205], v[10:13]
	v_mfma_f32_16x16x32_bf16 v[62:65], v[82:85], v[166:169], v[62:65]
	v_mfma_f32_16x16x32_bf16 v[58:61], v[90:93], v[166:169], v[58:61]
	v_mfma_f32_16x16x32_bf16 v[54:57], v[82:85], v[174:177], v[54:57]
	v_mfma_f32_16x16x32_bf16 v[42:45], v[90:93], v[174:177], v[42:45]
	v_mfma_f32_16x16x32_bf16 v[30:33], v[82:85], v[198:201], v[30:33]
	v_mfma_f32_16x16x32_bf16 v[26:29], v[90:93], v[198:201], v[26:29]
	v_mfma_f32_16x16x32_bf16 v[22:25], v[82:85], v[206:209], v[22:25]
	v_mfma_f32_16x16x32_bf16 v[10:13], v[90:93], v[206:209], v[10:13]
	v_mfma_f32_16x16x32_bf16 v[50:53], v[146:149], v[162:165], v[50:53]
	v_mfma_f32_16x16x32_bf16 v[46:49], v[154:157], v[162:165], v[46:49]
	v_mfma_f32_16x16x32_bf16 v[38:41], v[146:149], v[170:173], v[38:41]
	v_mfma_f32_16x16x32_bf16 v[34:37], v[154:157], v[170:173], v[34:37]
	v_mfma_f32_16x16x32_bf16 v[18:21], v[146:149], v[178:181], v[18:21]
	v_mfma_f32_16x16x32_bf16 v[14:17], v[154:157], v[178:181], v[14:17]
	v_mfma_f32_16x16x32_bf16 v[6:9], v[146:149], v[202:205], v[6:9]
	v_mfma_f32_16x16x32_bf16 v[2:5], v[154:157], v[202:205], v[2:5]
	v_mfma_f32_16x16x32_bf16 v[50:53], v[150:153], v[166:169], v[50:53]
	v_mfma_f32_16x16x32_bf16 v[46:49], v[158:161], v[166:169], v[46:49]
	v_mfma_f32_16x16x32_bf16 v[38:41], v[150:153], v[174:177], v[38:41]
	v_mfma_f32_16x16x32_bf16 v[34:37], v[158:161], v[174:177], v[34:37]
	v_mfma_f32_16x16x32_bf16 v[18:21], v[150:153], v[198:201], v[18:21]
	v_mfma_f32_16x16x32_bf16 v[14:17], v[158:161], v[198:201], v[14:17]
	v_mfma_f32_16x16x32_bf16 v[6:9], v[150:153], v[206:209], v[6:9]
	v_mfma_f32_16x16x32_bf16 v[2:5], v[158:161], v[206:209], v[2:5]
	s_barrier
	s_add_i32 s81, 0, 0x18000
	s_add_i32 s82, 0, 0x1c000
	v_add_u32_e32 v90, s81, v216
	v_add_u32_e32 v158, s82, v216
	ds_read_b128 v[74:77], v90
	ds_read_b128 v[82:85], v90 offset:1024
	ds_read_b128 v[86:89], v90 offset:2048
	ds_read_b128 v[90:93], v90 offset:3072
	ds_read_b128 v[146:149], v158
	ds_read_b128 v[150:153], v158 offset:1024
	ds_read_b128 v[154:157], v158 offset:2048
	ds_read_b128 v[158:161], v158 offset:3072
	s_add_u32 s34, s64, 0x40000
	s_addc_u32 s35, s65, 0
	s_mov_b32 m0, s67
	v_lshl_add_u64 v[224:225], s[34:35], 0, v[184:185]
	ds_read_b128 v[162:165], v222 offset:32768
	ds_read_b128 v[166:169], v222 offset:33792
	ds_read_b128 v[170:173], v222 offset:34816
	ds_read_b128 v[174:177], v222 offset:35840
	ds_read_b128 v[178:181], v222 offset:36864
	ds_read_b128 v[198:201], v222 offset:37888
	ds_read_b128 v[202:205], v222 offset:38912
	ds_read_b128 v[206:209], v222 offset:39936
	global_load_lds_dwordx4 v[224:225], off
	v_lshl_add_u64 v[224:225], s[34:35], 0, v[186:187]
	s_mov_b32 m0, s68
	s_nop 0
	global_load_lds_dwordx4 v[224:225], off
	s_waitcnt vmcnt(8)
	s_waitcnt lgkmcnt(0)
	s_barrier
	s_waitcnt lgkmcnt(0)
	v_mfma_f32_16x16x32_bf16 v[142:145], v[74:77], v[162:165], v[142:145]
	v_mfma_f32_16x16x32_bf16 v[138:141], v[86:89], v[162:165], v[138:141]
	v_mfma_f32_16x16x32_bf16 v[134:137], v[74:77], v[170:173], v[134:137]
	v_mfma_f32_16x16x32_bf16 v[122:125], v[86:89], v[170:173], v[122:125]
	v_mfma_f32_16x16x32_bf16 v[110:113], v[74:77], v[178:181], v[110:113]
	v_mfma_f32_16x16x32_bf16 v[106:109], v[86:89], v[178:181], v[106:109]
	v_mfma_f32_16x16x32_bf16 v[102:105], v[74:77], v[202:205], v[102:105]
	v_mfma_f32_16x16x32_bf16 v[78:81], v[86:89], v[202:205], v[78:81]
	v_mfma_f32_16x16x32_bf16 v[142:145], v[82:85], v[166:169], v[142:145]
	v_mfma_f32_16x16x32_bf16 v[138:141], v[90:93], v[166:169], v[138:141]
	v_mfma_f32_16x16x32_bf16 v[134:137], v[82:85], v[174:177], v[134:137]
	v_mfma_f32_16x16x32_bf16 v[122:125], v[90:93], v[174:177], v[122:125]
	v_mfma_f32_16x16x32_bf16 v[110:113], v[82:85], v[198:201], v[110:113]
	v_mfma_f32_16x16x32_bf16 v[106:109], v[90:93], v[198:201], v[106:109]
	v_mfma_f32_16x16x32_bf16 v[102:105], v[82:85], v[206:209], v[102:105]
	v_mfma_f32_16x16x32_bf16 v[78:81], v[90:93], v[206:209], v[78:81]
	v_mfma_f32_16x16x32_bf16 v[130:133], v[146:149], v[162:165], v[130:133]
	v_mfma_f32_16x16x32_bf16 v[126:129], v[154:157], v[162:165], v[126:129]
	v_mfma_f32_16x16x32_bf16 v[118:121], v[146:149], v[170:173], v[118:121]
	v_mfma_f32_16x16x32_bf16 v[114:117], v[154:157], v[170:173], v[114:117]
	v_mfma_f32_16x16x32_bf16 v[98:101], v[146:149], v[178:181], v[98:101]
	v_mfma_f32_16x16x32_bf16 v[94:97], v[154:157], v[178:181], v[94:97]
	v_mfma_f32_16x16x32_bf16 v[70:73], v[146:149], v[202:205], v[70:73]
	v_mfma_f32_16x16x32_bf16 v[66:69], v[154:157], v[202:205], v[66:69]
	v_mfma_f32_16x16x32_bf16 v[130:133], v[150:153], v[166:169], v[130:133]
	v_mfma_f32_16x16x32_bf16 v[126:129], v[158:161], v[166:169], v[126:129]
	v_mfma_f32_16x16x32_bf16 v[118:121], v[150:153], v[174:177], v[118:121]
	v_mfma_f32_16x16x32_bf16 v[114:117], v[158:161], v[174:177], v[114:117]
	v_mfma_f32_16x16x32_bf16 v[98:101], v[150:153], v[198:201], v[98:101]
	v_mfma_f32_16x16x32_bf16 v[94:97], v[158:161], v[198:201], v[94:97]
	v_mfma_f32_16x16x32_bf16 v[70:73], v[150:153], v[206:209], v[70:73]
	v_mfma_f32_16x16x32_bf16 v[66:69], v[158:161], v[206:209], v[66:69]
	s_barrier
; #define PG8_STAGE(bufoff, gbase, voff) do { _Pragma("unroll") for (int _i = 0; _i < 2; ++_i) \
;         __builtin_amdgcn_global_load_lds((const unsigned*)((const char*)(gbase) + (voff)[_i]), (PG8_LAS unsigned*)(lds + (bufoff) + ldsw + _i * 8192), 16, 0, 0); } while (0)
; #define PG8_LDA(dst, b, h) do { _Pragma("unroll") for (int m = 0; m < 4; ++m) _Pragma("unroll") for (int k = 0; k < 2; ++k) dst[m][k] = *(const PG8_LAS bf16x8*)(lds + PG8_SA(b, h) + aoff + m * 2048 + k * 1024); } while (0)
; #define PG8_MMA(ai, bj, At, Bt) do { __builtin_amdgcn_s_setprio(1); _Pragma("unroll") for (int m = 0; m < 4; ++m) _Pragma("unroll") for (int n = 0; n < 2; ++n) _Pragma("unroll") for (int k = 0; k < 2; ++k) \
;         acc[ai][bj][m][n] = __builtin_amdgcn_mfma_f32_16x16x32_bf16(Bt[n][k], At[m][k], acc[ai][bj][m][n], 0, 0, 0); __builtin_amdgcn_s_setprio(0); } while (0)
; #define PG8_WAIT_V(n) asm volatile("s_waitcnt vmcnt(" #n ")" ::: "memory")
; #define PG8_WAIT_L(n) asm volatile("s_waitcnt lgkmcnt(" #n ")" ::: "memory")
; #define PG8_BAR __builtin_amdgcn_s_barrier()
; #define PG8_SCHED __builtin_amdgcn_sched_barrier(0)
; template <class Epi, class Sched, bool ALIGN_EPI = false, bool SP2 = false>
; __device__ __forceinline__ void gemm_phase(PG8_LAS unsigned char* lds, const Gemm g, const Sched& S, const Epi& E) {
;     ...
;             PG8_LDA(At, 1, 1); PG8_STAGE(PG8_SB(1, 0), b3, voffB); PG8_STAGE(PG8_SB(1, 1), b3 + hstep, voffB); PG8_STAGE(PG8_SA(1, 0), a3, voffA);
;             PG8_WAIT_V(8); PG8_WAIT_L(0); PG8_BAR; PG8_MMA(1, 0, At, B0); PG8_MMA(1, 1, At, B1); PG8_BAR; PG8_SCHED;
	s_add_i32 s34, s81, s3
	v_lshl_add_u64 v[182:183], v[182:183], 0, s[46:47]
	s_mov_b32 m0, s34
	ds_read_b128 v[162:165], v222 offset:49152
	ds_read_b128 v[166:169], v222 offset:50176
	ds_read_b128 v[170:173], v222 offset:51200
	ds_read_b128 v[174:177], v222 offset:52224
	ds_read_b128 v[178:181], v222 offset:53248
	ds_read_b128 v[198:201], v222 offset:54272
	ds_read_b128 v[202:205], v222 offset:55296
	ds_read_b128 v[206:209], v222 offset:56320
	global_load_lds_dwordx4 v[182:183], off
	s_add_i32 m0, s34, 0x2000
	s_add_u32 s34, s62, 0x40080
	v_lshl_add_u64 v[182:183], v[210:211], 0, s[46:47]
	s_addc_u32 s35, s63, 0
	s_add_i32 s62, s82, s3
	global_load_lds_dwordx4 v[182:183], off
	v_lshl_add_u64 v[182:183], s[34:35], 0, v[184:185]
	s_mov_b32 m0, s62
	s_nop 0
	global_load_lds_dwordx4 v[182:183], off
	v_lshl_add_u64 v[182:183], s[34:35], 0, v[186:187]
	s_add_i32 m0, s62, 0x2000
	s_nop 0
	global_load_lds_dwordx4 v[182:183], off
	v_lshl_add_u64 v[182:183], v[212:213], 0, s[46:47]
	s_mov_b32 m0, s70
	s_nop 0
	global_load_lds_dwordx4 v[182:183], off
	v_lshl_add_u64 v[182:183], v[214:215], 0, s[46:47]
	s_mov_b32 m0, s71
	s_nop 0
	global_load_lds_dwordx4 v[182:183], off
	s_waitcnt vmcnt(8)
	s_waitcnt lgkmcnt(0)
	s_barrier
	s_waitcnt lgkmcnt(0)
	v_mfma_f32_16x16x32_bf16 v[62:65], v[74:77], v[162:165], v[62:65]
	v_mfma_f32_16x16x32_bf16 v[58:61], v[86:89], v[162:165], v[58:61]
	v_mfma_f32_16x16x32_bf16 v[54:57], v[74:77], v[170:173], v[54:57]
	v_mfma_f32_16x16x32_bf16 v[42:45], v[86:89], v[170:173], v[42:45]
	v_mfma_f32_16x16x32_bf16 v[30:33], v[74:77], v[178:181], v[30:33]
	v_mfma_f32_16x16x32_bf16 v[26:29], v[86:89], v[178:181], v[26:29]
	v_mfma_f32_16x16x32_bf16 v[22:25], v[74:77], v[202:205], v[22:25]
	v_mfma_f32_16x16x32_bf16 v[10:13], v[86:89], v[202:205], v[10:13]
	v_mfma_f32_16x16x32_bf16 v[62:65], v[82:85], v[166:169], v[62:65]
	v_mfma_f32_16x16x32_bf16 v[58:61], v[90:93], v[166:169], v[58:61]
	v_mfma_f32_16x16x32_bf16 v[54:57], v[82:85], v[174:177], v[54:57]
	v_mfma_f32_16x16x32_bf16 v[42:45], v[90:93], v[174:177], v[42:45]
	v_mfma_f32_16x16x32_bf16 v[30:33], v[82:85], v[198:201], v[30:33]
	v_mfma_f32_16x16x32_bf16 v[26:29], v[90:93], v[198:201], v[26:29]
	v_mfma_f32_16x16x32_bf16 v[22:25], v[82:85], v[206:209], v[22:25]
	v_mfma_f32_16x16x32_bf16 v[10:13], v[90:93], v[206:209], v[10:13]
	v_mfma_f32_16x16x32_bf16 v[50:53], v[146:149], v[162:165], v[50:53]
	v_mfma_f32_16x16x32_bf16 v[46:49], v[154:157], v[162:165], v[46:49]
	v_mfma_f32_16x16x32_bf16 v[38:41], v[146:149], v[170:173], v[38:41]
	v_mfma_f32_16x16x32_bf16 v[34:37], v[154:157], v[170:173], v[34:37]
	v_mfma_f32_16x16x32_bf16 v[18:21], v[146:149], v[178:181], v[18:21]
	v_mfma_f32_16x16x32_bf16 v[14:17], v[154:157], v[178:181], v[14:17]
	v_mfma_f32_16x16x32_bf16 v[6:9], v[146:149], v[202:205], v[6:9]
	v_mfma_f32_16x16x32_bf16 v[2:5], v[154:157], v[202:205], v[2:5]
	v_mfma_f32_16x16x32_bf16 v[50:53], v[150:153], v[166:169], v[50:53]
	v_mfma_f32_16x16x32_bf16 v[46:49], v[158:161], v[166:169], v[46:49]
	v_mfma_f32_16x16x32_bf16 v[38:41], v[150:153], v[174:177], v[38:41]
	v_mfma_f32_16x16x32_bf16 v[34:37], v[158:161], v[174:177], v[34:37]
	v_mfma_f32_16x16x32_bf16 v[18:21], v[150:153], v[198:201], v[18:21]
	v_mfma_f32_16x16x32_bf16 v[14:17], v[158:161], v[198:201], v[14:17]
	v_mfma_f32_16x16x32_bf16 v[6:9], v[150:153], v[206:209], v[6:9]
	v_mfma_f32_16x16x32_bf16 v[2:5], v[158:161], v[206:209], v[2:5]
	s_barrier
	s_add_i32 s80, s80, 2
	s_add_u32 s12, s12, 0x100
	s_addc_u32 s13, s13, 0
	s_add_u32 s78, s78, 0x100
	s_addc_u32 s79, s79, 0
	s_cmp_gt_u32 s80, 13
	s_cbranch_scc0 .LBB0_1331
	s_and_b64 vcc, exec, s[48:49]
	s_cbranch_vccz .LBB0_1334
	s_barrier

; #define PG8_STAGE(bufoff, gbase, voff) do { _Pragma("unroll") for (int _i = 0; _i < 2; ++_i) \
;         __builtin_amdgcn_global_load_lds((const unsigned*)((const char*)(gbase) + (voff)[_i]), (PG8_LAS unsigned*)(lds + (bufoff) + ldsw + _i * 8192), 16, 0, 0); } while (0)
; #define PG8_LDA(dst, b, h) do { _Pragma("unroll") for (int m = 0; m < 4; ++m) _Pragma("unroll") for (int k = 0; k < 2; ++k) dst[m][k] = *(const PG8_LAS bf16x8*)(lds + PG8_SA(b, h) + aoff + m * 2048 + k * 1024); } while (0)
; #define PG8_LDB(dst, b, h) do { _Pragma("unroll") for (int n = 0; n < 2; ++n) _Pragma("unroll") for (int k = 0; k < 2; ++k) dst[n][k] = *(const PG8_LAS bf16x8*)(lds + PG8_SB(b, h) + boff + n * 2048 + k * 1024); } while (0)
; #define PG8_MMA(ai, bj, At, Bt) do { __builtin_amdgcn_s_setprio(1); _Pragma("unroll") for (int m = 0; m < 4; ++m) _Pragma("unroll") for (int n = 0; n < 2; ++n) _Pragma("unroll") for (int k = 0; k < 2; ++k) \
;         acc[ai][bj][m][n] = __builtin_amdgcn_mfma_f32_16x16x32_bf16(Bt[n][k], At[m][k], acc[ai][bj][m][n], 0, 0, 0); __builtin_amdgcn_s_setprio(0); } while (0)
; #define PG8_WAIT_V(n) asm volatile("s_waitcnt vmcnt(" #n ")" ::: "memory")
; #define PG8_BAR __builtin_amdgcn_s_barrier()
; template <class Epi, class Sched, bool ALIGN_EPI = false, bool SP2 = false>
; __device__ __forceinline__ void gemm_phase(PG8_LAS unsigned char* lds, const Gemm g, const Sched& S, const Epi& E) {
;     ...
;         for (int t = 0; t < nt; t += 2) {
;             const bool last = (t == nt - 2);
;             const char* a1 = cA + (size_t)(t + 1) * kstep;
;             const char* a2 = last ? nA : cA + (size_t)(t + 2) * kstep; const char* b2 = last ? nB : cB + (size_t)(t + 2) * kstep;
;             const char* a3 = a2 + kstep; const char* b3 = b2 + kstep;
;             if (last && has_next) S.a_ready(nxt);
;             if constexpr (SP2) {
;             PG8_LDB(B0, 0, 0); PG8_LDB(B1, 0, 1); PG8_SCHED; PG8_LDA(At, 0, 0); PG8_STAGE(PG8_SA(1, 1), a1 + hstep, voffA);
;             PG8_WAIT_V(8); PG8_WAIT_L(0); PG8_BAR; PG8_MMA(0, 0, At, B0); PG8_MMA(0, 1, At, B1); PG8_BAR; PG8_SCHED;
;             PG8_LDA(At, 0, 1); PG8_STAGE(PG8_SB(0, 0), b2, voffB); PG8_STAGE(PG8_SB(0, 1), b2 + hstep, voffB); PG8_STAGE(PG8_SA(0, 0), a2, voffA);
;             PG8_WAIT_V(8); PG8_WAIT_L(0); PG8_BAR; PG8_MMA(1, 0, At, B0); PG8_MMA(1, 1, At, B1); PG8_BAR; PG8_SCHED;
.LBB0_1577:
	ds_read_b128 v[142:145], v160
	ds_read_b128 v[146:149], v160 offset:1024
	ds_read_b128 v[164:167], v160 offset:2048
	ds_read_b128 v[168:171], v160 offset:3072
	ds_read_b128 v[172:175], v161
	ds_read_b128 v[176:179], v161 offset:1024
	ds_read_b128 v[180:183], v161 offset:2048
	ds_read_b128 v[184:187], v161 offset:3072
	s_add_u32 s34, s60, 0xfffe0080
	s_addc_u32 s35, s61, -1
	s_cmp_eq_u32 s82, 4
	s_cselect_b32 s65, s53, s35
	s_cselect_b32 s64, s78, s34
	s_cselect_b32 s63, s51, s81
	s_cselect_b32 s62, s79, s80
	v_lshl_add_u64 v[220:221], s[60:61], 0, v[134:135]
	s_add_i32 m0, s59, 0xc000
	ds_read_b128 v[188:191], v162
	ds_read_b128 v[192:195], v162 offset:1024
	ds_read_b128 v[196:199], v162 offset:2048
	ds_read_b128 v[200:203], v162 offset:3072
	ds_read_b128 v[204:207], v162 offset:4096
	ds_read_b128 v[208:211], v162 offset:5120
	ds_read_b128 v[212:215], v162 offset:6144
	ds_read_b128 v[216:219], v162 offset:7168
	global_load_lds_dwordx4 v[220:221], off
	v_lshl_add_u64 v[220:221], s[60:61], 0, v[136:137]
	s_add_i32 m0, s59, 0xe000
	s_nop 0
	global_load_lds_dwordx4 v[220:221], off
	s_waitcnt vmcnt(8)
	s_waitcnt lgkmcnt(0)
	s_barrier
	s_waitcnt lgkmcnt(0)
	v_mfma_f32_16x16x32_bf16 v[126:129], v[142:145], v[188:191], v[126:129]
	v_mfma_f32_16x16x32_bf16 v[122:125], v[164:167], v[188:191], v[122:125]
	v_mfma_f32_16x16x32_bf16 v[118:121], v[142:145], v[196:199], v[118:121]
	v_mfma_f32_16x16x32_bf16 v[106:109], v[164:167], v[196:199], v[106:109]
	v_mfma_f32_16x16x32_bf16 v[98:101], v[142:145], v[204:207], v[98:101]
	v_mfma_f32_16x16x32_bf16 v[90:93], v[164:167], v[204:207], v[90:93]
	v_mfma_f32_16x16x32_bf16 v[86:89], v[142:145], v[212:215], v[86:89]
	v_mfma_f32_16x16x32_bf16 v[74:77], v[164:167], v[212:215], v[74:77]
	v_mfma_f32_16x16x32_bf16 v[126:129], v[146:149], v[192:195], v[126:129]
	v_mfma_f32_16x16x32_bf16 v[122:125], v[168:171], v[192:195], v[122:125]
	v_mfma_f32_16x16x32_bf16 v[118:121], v[146:149], v[200:203], v[118:121]
	v_mfma_f32_16x16x32_bf16 v[106:109], v[168:171], v[200:203], v[106:109]
	v_mfma_f32_16x16x32_bf16 v[98:101], v[146:149], v[208:211], v[98:101]
	v_mfma_f32_16x16x32_bf16 v[90:93], v[168:171], v[208:211], v[90:93]
	v_mfma_f32_16x16x32_bf16 v[86:89], v[146:149], v[216:219], v[86:89]
	v_mfma_f32_16x16x32_bf16 v[74:77], v[168:171], v[216:219], v[74:77]
	v_mfma_f32_16x16x32_bf16 v[114:117], v[172:175], v[188:191], v[114:117]
	v_mfma_f32_16x16x32_bf16 v[110:113], v[180:183], v[188:191], v[110:113]
	v_mfma_f32_16x16x32_bf16 v[102:105], v[172:175], v[196:199], v[102:105]
	v_mfma_f32_16x16x32_bf16 v[94:97], v[180:183], v[196:199], v[94:97]
	v_mfma_f32_16x16x32_bf16 v[82:85], v[172:175], v[204:207], v[82:85]
	v_mfma_f32_16x16x32_bf16 v[78:81], v[180:183], v[204:207], v[78:81]
	v_mfma_f32_16x16x32_bf16 v[70:73], v[172:175], v[212:215], v[70:73]
	v_mfma_f32_16x16x32_bf16 v[66:69], v[180:183], v[212:215], v[66:69]
	v_mfma_f32_16x16x32_bf16 v[114:117], v[176:179], v[192:195], v[114:117]
	v_mfma_f32_16x16x32_bf16 v[110:113], v[184:187], v[192:195], v[110:113]
	v_mfma_f32_16x16x32_bf16 v[102:105], v[176:179], v[200:203], v[102:105]
	v_mfma_f32_16x16x32_bf16 v[94:97], v[184:187], v[200:203], v[94:97]
	v_mfma_f32_16x16x32_bf16 v[82:85], v[176:179], v[208:211], v[82:85]
	v_mfma_f32_16x16x32_bf16 v[78:81], v[184:187], v[208:211], v[78:81]
	v_mfma_f32_16x16x32_bf16 v[70:73], v[176:179], v[216:219], v[70:73]
	v_mfma_f32_16x16x32_bf16 v[66:69], v[184:187], v[216:219], v[66:69]
	s_barrier
	s_add_i32 s34, s73, s19
	v_lshl_add_u64 v[220:221], s[62:63], 0, v[130:131]
	s_mov_b32 m0, s34
	ds_read_b128 v[188:191], v162 offset:16384
	ds_read_b128 v[192:195], v162 offset:17408
	ds_read_b128 v[196:199], v162 offset:18432
	ds_read_b128 v[200:203], v162 offset:19456
	ds_read_b128 v[204:207], v162 offset:20480
	ds_read_b128 v[208:211], v162 offset:21504
	ds_read_b128 v[212:215], v162 offset:22528
	ds_read_b128 v[216:219], v162 offset:23552
	global_load_lds_dwordx4 v[220:221], off
	s_add_i32 m0, s34, 0x2000
	s_add_u32 s34, s62, 0x20000
	v_lshl_add_u64 v[222:223], s[62:63], 0, v[132:133]
	s_addc_u32 s35, s63, 0
	s_add_i32 s83, s76, s19
	global_load_lds_dwordx4 v[222:223], off
	v_lshl_add_u64 v[224:225], s[34:35], 0, v[130:131]
	s_mov_b32 m0, s83
	v_lshl_add_u64 v[226:227], s[64:65], 0, v[132:133]
	global_load_lds_dwordx4 v[224:225], off
	v_lshl_add_u64 v[224:225], s[34:35], 0, v[132:133]
	s_add_i32 m0, s83, 0x2000
	s_nop 0
	global_load_lds_dwordx4 v[224:225], off
	v_lshl_add_u64 v[224:225], s[64:65], 0, v[130:131]
	s_mov_b32 m0, s59
	s_nop 0
	global_load_lds_dwordx4 v[224:225], off
	s_mov_b32 m0, s66
	s_nop 0
	global_load_lds_dwordx4 v[226:227], off
	s_waitcnt vmcnt(8)
	s_waitcnt lgkmcnt(0)
	s_barrier
; #define PG8_STAGE(bufoff, gbase, voff) do { _Pragma("unroll") for (int _i = 0; _i < 2; ++_i) \
;         __builtin_amdgcn_global_load_lds((const unsigned*)((const char*)(gbase) + (voff)[_i]), (PG8_LAS unsigned*)(lds + (bufoff) + ldsw + _i * 8192), 16, 0, 0); } while (0)
; #define PG8_LDA(dst, b, h) do { _Pragma("unroll") for (int m = 0; m < 4; ++m) _Pragma("unroll") for (int k = 0; k < 2; ++k) dst[m][k] = *(const PG8_LAS bf16x8*)(lds + PG8_SA(b, h) + aoff + m * 2048 + k * 1024); } while (0)
; #define PG8_LDB(dst, b, h) do { _Pragma("unroll") for (int n = 0; n < 2; ++n) _Pragma("unroll") for (int k = 0; k < 2; ++k) dst[n][k] = *(const PG8_LAS bf16x8*)(lds + PG8_SB(b, h) + boff + n * 2048 + k * 1024); } while (0)
; #define PG8_MMA(ai, bj, At, Bt) do { __builtin_amdgcn_s_setprio(1); _Pragma("unroll") for (int m = 0; m < 4; ++m) _Pragma("unroll") for (int n = 0; n < 2; ++n) _Pragma("unroll") for (int k = 0; k < 2; ++k) \
;         acc[ai][bj][m][n] = __builtin_amdgcn_mfma_f32_16x16x32_bf16(Bt[n][k], At[m][k], acc[ai][bj][m][n], 0, 0, 0); __builtin_amdgcn_s_setprio(0); } while (0)
; #define PG8_WAIT_V(n) asm volatile("s_waitcnt vmcnt(" #n ")" ::: "memory")
; #define PG8_WAIT_L(n) asm volatile("s_waitcnt lgkmcnt(" #n ")" ::: "memory")
; #define PG8_BAR __builtin_amdgcn_s_barrier()
; #define PG8_SCHED __builtin_amdgcn_sched_barrier(0)
; template <class Epi, class Sched, bool ALIGN_EPI = false, bool SP2 = false>
; __device__ __forceinline__ void gemm_phase(PG8_LAS unsigned char* lds, const Gemm g, const Sched& S, const Epi& E) {
;     ...
;             PG8_LDA(At, 0, 1); PG8_STAGE(PG8_SB(0, 0), b2, voffB); PG8_STAGE(PG8_SB(0, 1), b2 + hstep, voffB); PG8_STAGE(PG8_SA(0, 0), a2, voffA);
;             PG8_WAIT_V(8); PG8_WAIT_L(0); PG8_BAR; PG8_MMA(1, 0, At, B0); PG8_MMA(1, 1, At, B1); PG8_BAR; PG8_SCHED;
;             PG8_LDB(B0, 1, 0); PG8_LDB(B1, 1, 1); PG8_SCHED; PG8_LDA(At, 1, 0); PG8_STAGE(PG8_SA(0, 1), a2 + hstep, voffA);
;             PG8_WAIT_V(8); PG8_WAIT_L(0); PG8_BAR; PG8_MMA(0, 0, At, B0); PG8_MMA(0, 1, At, B1); PG8_BAR; PG8_SCHED;
;             PG8_LDA(At, 1, 1); PG8_STAGE(PG8_SB(1, 0), b3, voffB); PG8_STAGE(PG8_SB(1, 1), b3 + hstep, voffB); PG8_STAGE(PG8_SA(1, 0), a3, voffA);
	s_waitcnt lgkmcnt(0)
	v_mfma_f32_16x16x32_bf16 v[62:65], v[142:145], v[188:191], v[62:65]
	v_mfma_f32_16x16x32_bf16 v[58:61], v[164:167], v[188:191], v[58:61]
	v_mfma_f32_16x16x32_bf16 v[54:57], v[142:145], v[196:199], v[54:57]
	v_mfma_f32_16x16x32_bf16 v[42:45], v[164:167], v[196:199], v[42:45]
	v_mfma_f32_16x16x32_bf16 v[34:37], v[142:145], v[204:207], v[34:37]
	v_mfma_f32_16x16x32_bf16 v[26:29], v[164:167], v[204:207], v[26:29]
	v_mfma_f32_16x16x32_bf16 v[18:21], v[142:145], v[212:215], v[18:21]
	v_mfma_f32_16x16x32_bf16 v[10:13], v[164:167], v[212:215], v[10:13]
	v_mfma_f32_16x16x32_bf16 v[62:65], v[146:149], v[192:195], v[62:65]
	v_mfma_f32_16x16x32_bf16 v[58:61], v[168:171], v[192:195], v[58:61]
	v_mfma_f32_16x16x32_bf16 v[54:57], v[146:149], v[200:203], v[54:57]
	v_mfma_f32_16x16x32_bf16 v[42:45], v[168:171], v[200:203], v[42:45]
	v_mfma_f32_16x16x32_bf16 v[34:37], v[146:149], v[208:211], v[34:37]
	v_mfma_f32_16x16x32_bf16 v[26:29], v[168:171], v[208:211], v[26:29]
	v_mfma_f32_16x16x32_bf16 v[18:21], v[146:149], v[216:219], v[18:21]
	v_mfma_f32_16x16x32_bf16 v[10:13], v[168:171], v[216:219], v[10:13]
	v_mfma_f32_16x16x32_bf16 v[50:53], v[172:175], v[188:191], v[50:53]
	v_mfma_f32_16x16x32_bf16 v[46:49], v[180:183], v[188:191], v[46:49]
	v_mfma_f32_16x16x32_bf16 v[38:41], v[172:175], v[196:199], v[38:41]
	v_mfma_f32_16x16x32_bf16 v[30:33], v[180:183], v[196:199], v[30:33]
	v_mfma_f32_16x16x32_bf16 v[22:25], v[172:175], v[204:207], v[22:25]
	v_mfma_f32_16x16x32_bf16 v[14:17], v[180:183], v[204:207], v[14:17]
	v_mfma_f32_16x16x32_bf16 v[6:9], v[172:175], v[212:215], v[6:9]
	v_mfma_f32_16x16x32_bf16 v[2:5], v[180:183], v[212:215], v[2:5]
	v_mfma_f32_16x16x32_bf16 v[50:53], v[176:179], v[192:195], v[50:53]
	v_mfma_f32_16x16x32_bf16 v[46:49], v[184:187], v[192:195], v[46:49]
	v_mfma_f32_16x16x32_bf16 v[38:41], v[176:179], v[200:203], v[38:41]
	v_mfma_f32_16x16x32_bf16 v[30:33], v[184:187], v[200:203], v[30:33]
	v_mfma_f32_16x16x32_bf16 v[22:25], v[176:179], v[208:211], v[22:25]
	v_mfma_f32_16x16x32_bf16 v[14:17], v[184:187], v[208:211], v[14:17]
	v_mfma_f32_16x16x32_bf16 v[6:9], v[176:179], v[216:219], v[6:9]
	v_mfma_f32_16x16x32_bf16 v[2:5], v[184:187], v[216:219], v[2:5]
	s_barrier
	s_add_i32 s83, 0, 0x18000
	v_add_u32_e32 v163, s83, v158
	s_add_i32 s84, 0, 0x1c000
	ds_read_b128 v[142:145], v163
	ds_read_b128 v[146:149], v163 offset:1024
	ds_read_b128 v[164:167], v163 offset:2048
	ds_read_b128 v[168:171], v163 offset:3072
	v_add_u32_e32 v163, s84, v158
	ds_read_b128 v[172:175], v163
	ds_read_b128 v[176:179], v163 offset:1024
	ds_read_b128 v[180:183], v163 offset:2048
	ds_read_b128 v[184:187], v163 offset:3072
	s_add_u32 s34, s64, 0x20000
	s_addc_u32 s35, s65, 0
	s_mov_b32 m0, s67
	v_lshl_add_u64 v[228:229], s[34:35], 0, v[130:131]
	ds_read_b128 v[188:191], v162 offset:32768
	ds_read_b128 v[192:195], v162 offset:33792
	ds_read_b128 v[196:199], v162 offset:34816
	ds_read_b128 v[200:203], v162 offset:35840
	ds_read_b128 v[204:207], v162 offset:36864
	ds_read_b128 v[208:211], v162 offset:37888
	ds_read_b128 v[212:215], v162 offset:38912
	ds_read_b128 v[216:219], v162 offset:39936
	global_load_lds_dwordx4 v[228:229], off
	v_lshl_add_u64 v[228:229], s[34:35], 0, v[132:133]
	s_mov_b32 m0, s68
	s_nop 0
	global_load_lds_dwordx4 v[228:229], off
	s_waitcnt vmcnt(8)
	s_waitcnt lgkmcnt(0)
	s_barrier
	s_waitcnt lgkmcnt(0)
	v_mfma_f32_16x16x32_bf16 v[126:129], v[142:145], v[188:191], v[126:129]
	v_mfma_f32_16x16x32_bf16 v[122:125], v[164:167], v[188:191], v[122:125]
	v_mfma_f32_16x16x32_bf16 v[118:121], v[142:145], v[196:199], v[118:121]
	v_mfma_f32_16x16x32_bf16 v[106:109], v[164:167], v[196:199], v[106:109]
	v_mfma_f32_16x16x32_bf16 v[98:101], v[142:145], v[204:207], v[98:101]
	v_mfma_f32_16x16x32_bf16 v[90:93], v[164:167], v[204:207], v[90:93]
	v_mfma_f32_16x16x32_bf16 v[86:89], v[142:145], v[212:215], v[86:89]
	v_mfma_f32_16x16x32_bf16 v[74:77], v[164:167], v[212:215], v[74:77]
	v_mfma_f32_16x16x32_bf16 v[126:129], v[146:149], v[192:195], v[126:129]
	v_mfma_f32_16x16x32_bf16 v[122:125], v[168:171], v[192:195], v[122:125]
	v_mfma_f32_16x16x32_bf16 v[118:121], v[146:149], v[200:203], v[118:121]
	v_mfma_f32_16x16x32_bf16 v[106:109], v[168:171], v[200:203], v[106:109]
	v_mfma_f32_16x16x32_bf16 v[98:101], v[146:149], v[208:211], v[98:101]
	v_mfma_f32_16x16x32_bf16 v[90:93], v[168:171], v[208:211], v[90:93]
	v_mfma_f32_16x16x32_bf16 v[86:89], v[146:149], v[216:219], v[86:89]
	v_mfma_f32_16x16x32_bf16 v[74:77], v[168:171], v[216:219], v[74:77]
	v_mfma_f32_16x16x32_bf16 v[114:117], v[172:175], v[188:191], v[114:117]
	v_mfma_f32_16x16x32_bf16 v[110:113], v[180:183], v[188:191], v[110:113]
	v_mfma_f32_16x16x32_bf16 v[102:105], v[172:175], v[196:199], v[102:105]
	v_mfma_f32_16x16x32_bf16 v[94:97], v[180:183], v[196:199], v[94:97]
	v_mfma_f32_16x16x32_bf16 v[82:85], v[172:175], v[204:207], v[82:85]
	v_mfma_f32_16x16x32_bf16 v[78:81], v[180:183], v[204:207], v[78:81]
	v_mfma_f32_16x16x32_bf16 v[70:73], v[172:175], v[212:215], v[70:73]
	v_mfma_f32_16x16x32_bf16 v[66:69], v[180:183], v[212:215], v[66:69]
	v_mfma_f32_16x16x32_bf16 v[114:117], v[176:179], v[192:195], v[114:117]
	v_mfma_f32_16x16x32_bf16 v[110:113], v[184:187], v[192:195], v[110:113]
	v_mfma_f32_16x16x32_bf16 v[102:105], v[176:179], v[200:203], v[102:105]
	v_mfma_f32_16x16x32_bf16 v[94:97], v[184:187], v[200:203], v[94:97]
	v_mfma_f32_16x16x32_bf16 v[82:85], v[176:179], v[208:211], v[82:85]
	v_mfma_f32_16x16x32_bf16 v[78:81], v[184:187], v[208:211], v[78:81]
	v_mfma_f32_16x16x32_bf16 v[70:73], v[176:179], v[216:219], v[70:73]
	v_mfma_f32_16x16x32_bf16 v[66:69], v[184:187], v[216:219], v[66:69]
	s_barrier
; #define PG8_STAGE(bufoff, gbase, voff) do { _Pragma("unroll") for (int _i = 0; _i < 2; ++_i) \
;         __builtin_amdgcn_global_load_lds((const unsigned*)((const char*)(gbase) + (voff)[_i]), (PG8_LAS unsigned*)(lds + (bufoff) + ldsw + _i * 8192), 16, 0, 0); } while (0)
; #define PG8_LDA(dst, b, h) do { _Pragma("unroll") for (int m = 0; m < 4; ++m) _Pragma("unroll") for (int k = 0; k < 2; ++k) dst[m][k] = *(const PG8_LAS bf16x8*)(lds + PG8_SA(b, h) + aoff + m * 2048 + k * 1024); } while (0)
; #define PG8_MMA(ai, bj, At, Bt) do { __builtin_amdgcn_s_setprio(1); _Pragma("unroll") for (int m = 0; m < 4; ++m) _Pragma("unroll") for (int n = 0; n < 2; ++n) _Pragma("unroll") for (int k = 0; k < 2; ++k) \
;         acc[ai][bj][m][n] = __builtin_amdgcn_mfma_f32_16x16x32_bf16(Bt[n][k], At[m][k], acc[ai][bj][m][n], 0, 0, 0); __builtin_amdgcn_s_setprio(0); } while (0)
; #define PG8_WAIT_V(n) asm volatile("s_waitcnt vmcnt(" #n ")" ::: "memory")
; #define PG8_WAIT_L(n) asm volatile("s_waitcnt lgkmcnt(" #n ")" ::: "memory")
; #define PG8_BAR __builtin_amdgcn_s_barrier()
; #define PG8_SCHED __builtin_amdgcn_sched_barrier(0)
; template <class Epi, class Sched, bool ALIGN_EPI = false, bool SP2 = false>
; __device__ __forceinline__ void gemm_phase(PG8_LAS unsigned char* lds, const Gemm g, const Sched& S, const Epi& E) {
;     ...
;             PG8_LDA(At, 1, 1); PG8_STAGE(PG8_SB(1, 0), b3, voffB); PG8_STAGE(PG8_SB(1, 1), b3 + hstep, voffB); PG8_STAGE(PG8_SA(1, 0), a3, voffA);
;             PG8_WAIT_V(8); PG8_WAIT_L(0); PG8_BAR; PG8_MMA(1, 0, At, B0); PG8_MMA(1, 1, At, B1); PG8_BAR; PG8_SCHED;
	s_add_i32 s34, s83, s19
	v_lshl_add_u64 v[220:221], v[220:221], 0, s[36:37]
	s_mov_b32 m0, s34
	ds_read_b128 v[188:191], v162 offset:49152
	ds_read_b128 v[192:195], v162 offset:50176
	ds_read_b128 v[196:199], v162 offset:51200
	ds_read_b128 v[200:203], v162 offset:52224
	ds_read_b128 v[204:207], v162 offset:53248
	ds_read_b128 v[208:211], v162 offset:54272
	ds_read_b128 v[212:215], v162 offset:55296
	ds_read_b128 v[216:219], v162 offset:56320
	global_load_lds_dwordx4 v[220:221], off
	s_add_i32 m0, s34, 0x2000
	s_add_u32 s34, s62, 0x20080
	v_lshl_add_u64 v[220:221], v[222:223], 0, s[36:37]
	s_addc_u32 s35, s63, 0
	s_add_i32 s62, s84, s19
	global_load_lds_dwordx4 v[220:221], off
	v_lshl_add_u64 v[220:221], s[34:35], 0, v[130:131]
	s_mov_b32 m0, s62
	s_nop 0
	global_load_lds_dwordx4 v[220:221], off
	v_lshl_add_u64 v[220:221], s[34:35], 0, v[132:133]
	s_add_i32 m0, s62, 0x2000
	s_nop 0
	global_load_lds_dwordx4 v[220:221], off
	v_lshl_add_u64 v[220:221], v[224:225], 0, s[36:37]
	s_mov_b32 m0, s70
	s_nop 0
	global_load_lds_dwordx4 v[220:221], off
	v_lshl_add_u64 v[220:221], v[226:227], 0, s[36:37]
	s_mov_b32 m0, s71
	s_nop 0
	global_load_lds_dwordx4 v[220:221], off
	s_waitcnt vmcnt(8)
	s_waitcnt lgkmcnt(0)
	s_barrier
	s_waitcnt lgkmcnt(0)
	v_mfma_f32_16x16x32_bf16 v[62:65], v[142:145], v[188:191], v[62:65]
	v_mfma_f32_16x16x32_bf16 v[58:61], v[164:167], v[188:191], v[58:61]
	v_mfma_f32_16x16x32_bf16 v[54:57], v[142:145], v[196:199], v[54:57]
	v_mfma_f32_16x16x32_bf16 v[42:45], v[164:167], v[196:199], v[42:45]
	v_mfma_f32_16x16x32_bf16 v[34:37], v[142:145], v[204:207], v[34:37]
	v_mfma_f32_16x16x32_bf16 v[26:29], v[164:167], v[204:207], v[26:29]
	v_mfma_f32_16x16x32_bf16 v[18:21], v[142:145], v[212:215], v[18:21]
	v_mfma_f32_16x16x32_bf16 v[10:13], v[164:167], v[212:215], v[10:13]
	v_mfma_f32_16x16x32_bf16 v[62:65], v[146:149], v[192:195], v[62:65]
	v_mfma_f32_16x16x32_bf16 v[58:61], v[168:171], v[192:195], v[58:61]
	v_mfma_f32_16x16x32_bf16 v[54:57], v[146:149], v[200:203], v[54:57]
	v_mfma_f32_16x16x32_bf16 v[42:45], v[168:171], v[200:203], v[42:45]
	v_mfma_f32_16x16x32_bf16 v[34:37], v[146:149], v[208:211], v[34:37]
	v_mfma_f32_16x16x32_bf16 v[26:29], v[168:171], v[208:211], v[26:29]
	v_mfma_f32_16x16x32_bf16 v[18:21], v[146:149], v[216:219], v[18:21]
	v_mfma_f32_16x16x32_bf16 v[10:13], v[168:171], v[216:219], v[10:13]
	v_mfma_f32_16x16x32_bf16 v[50:53], v[172:175], v[188:191], v[50:53]
	v_mfma_f32_16x16x32_bf16 v[46:49], v[180:183], v[188:191], v[46:49]
	v_mfma_f32_16x16x32_bf16 v[38:41], v[172:175], v[196:199], v[38:41]
	v_mfma_f32_16x16x32_bf16 v[30:33], v[180:183], v[196:199], v[30:33]
	v_mfma_f32_16x16x32_bf16 v[22:25], v[172:175], v[204:207], v[22:25]
	v_mfma_f32_16x16x32_bf16 v[14:17], v[180:183], v[204:207], v[14:17]
	v_mfma_f32_16x16x32_bf16 v[6:9], v[172:175], v[212:215], v[6:9]
	v_mfma_f32_16x16x32_bf16 v[2:5], v[180:183], v[212:215], v[2:5]
	v_mfma_f32_16x16x32_bf16 v[50:53], v[176:179], v[192:195], v[50:53]
	v_mfma_f32_16x16x32_bf16 v[46:49], v[184:187], v[192:195], v[46:49]
	v_mfma_f32_16x16x32_bf16 v[38:41], v[176:179], v[200:203], v[38:41]
	v_mfma_f32_16x16x32_bf16 v[30:33], v[184:187], v[200:203], v[30:33]
	v_mfma_f32_16x16x32_bf16 v[22:25], v[176:179], v[208:211], v[22:25]
	v_mfma_f32_16x16x32_bf16 v[14:17], v[184:187], v[208:211], v[14:17]
	v_mfma_f32_16x16x32_bf16 v[6:9], v[176:179], v[216:219], v[6:9]
	v_mfma_f32_16x16x32_bf16 v[2:5], v[184:187], v[216:219], v[2:5]
	s_barrier
	s_add_i32 s82, s82, 2
	s_add_u32 s60, s60, 0x100
	s_addc_u32 s61, s61, 0
	s_add_u32 s80, s80, 0x100
	s_addc_u32 s81, s81, 0
	s_cmp_gt_u32 s82, 5
	s_cbranch_scc0 .LBB0_1577
	s_and_b64 vcc, exec, s[38:39]
	s_cbranch_vccz .LBB0_1580
	s_barrier

; #define PG8_STAGE(bufoff, gbase, voff) do { _Pragma("unroll") for (int _i = 0; _i < 2; ++_i) \
;         __builtin_amdgcn_global_load_lds((const unsigned*)((const char*)(gbase) + (voff)[_i]), (PG8_LAS unsigned*)(lds + (bufoff) + ldsw + _i * 8192), 16, 0, 0); } while (0)
; #define PG8_LDA(dst, b, h) do { _Pragma("unroll") for (int m = 0; m < 4; ++m) _Pragma("unroll") for (int k = 0; k < 2; ++k) dst[m][k] = *(const PG8_LAS bf16x8*)(lds + PG8_SA(b, h) + aoff + m * 2048 + k * 1024); } while (0)
; #define PG8_LDB(dst, b, h) do { _Pragma("unroll") for (int n = 0; n < 2; ++n) _Pragma("unroll") for (int k = 0; k < 2; ++k) dst[n][k] = *(const PG8_LAS bf16x8*)(lds + PG8_SB(b, h) + boff + n * 2048 + k * 1024); } while (0)
; #define PG8_MMA(ai, bj, At, Bt) do { __builtin_amdgcn_s_setprio(1); _Pragma("unroll") for (int m = 0; m < 4; ++m) _Pragma("unroll") for (int n = 0; n < 2; ++n) _Pragma("unroll") for (int k = 0; k < 2; ++k) \
;         acc[ai][bj][m][n] = __builtin_amdgcn_mfma_f32_16x16x32_bf16(Bt[n][k], At[m][k], acc[ai][bj][m][n], 0, 0, 0); __builtin_amdgcn_s_setprio(0); } while (0)
; #define PG8_WAIT_V(n) asm volatile("s_waitcnt vmcnt(" #n ")" ::: "memory")
; #define PG8_BAR __builtin_amdgcn_s_barrier()
; template <class Epi, class Sched, bool ALIGN_EPI = false, bool SP2 = false>
; __device__ __forceinline__ void gemm_phase(PG8_LAS unsigned char* lds, const Gemm g, const Sched& S, const Epi& E) {
;     ...
;         for (int t = 0; t < nt; t += 2) {
;             const bool last = (t == nt - 2);
;             const char* a1 = cA + (size_t)(t + 1) * kstep;
;             const char* a2 = last ? nA : cA + (size_t)(t + 2) * kstep; const char* b2 = last ? nB : cB + (size_t)(t + 2) * kstep;
;             const char* a3 = a2 + kstep; const char* b3 = b2 + kstep;
;             if (last && has_next) S.a_ready(nxt);
;             if constexpr (SP2) {
;             PG8_LDB(B0, 0, 0); PG8_LDB(B1, 0, 1); PG8_SCHED; PG8_LDA(At, 0, 0); PG8_STAGE(PG8_SA(1, 1), a1 + hstep, voffA);
;             PG8_WAIT_V(8); PG8_WAIT_L(0); PG8_BAR; PG8_MMA(0, 0, At, B0); PG8_MMA(0, 1, At, B1); PG8_BAR; PG8_SCHED;
;             PG8_LDA(At, 0, 1); PG8_STAGE(PG8_SB(0, 0), b2, voffB); PG8_STAGE(PG8_SB(0, 1), b2 + hstep, voffB); PG8_STAGE(PG8_SA(0, 0), a2, voffA);
;             PG8_WAIT_V(8); PG8_WAIT_L(0); PG8_BAR; PG8_MMA(1, 0, At, B0); PG8_MMA(1, 1, At, B1); PG8_BAR; PG8_SCHED;
.LBB0_1601:
	ds_read_b128 v[142:145], v1
	ds_read_b128 v[146:149], v1 offset:1024
	ds_read_b128 v[150:153], v1 offset:2048
	ds_read_b128 v[160:163], v1 offset:3072
	ds_read_b128 v[164:167], v156
	ds_read_b128 v[168:171], v156 offset:1024
	ds_read_b128 v[172:175], v156 offset:2048
	ds_read_b128 v[176:179], v156 offset:3072
	s_add_u32 s34, s56, 0xfffe0080
	s_addc_u32 s35, s57, -1
	s_cmp_eq_u32 s78, 4
	s_cselect_b32 s61, s49, s35
	s_cselect_b32 s60, s72, s34
	s_cselect_b32 s59, s47, s77
	s_cselect_b32 s58, s73, s76
	v_lshl_add_u64 v[212:213], s[56:57], 0, v[134:135]
	s_add_i32 m0, s55, 0xc000
	ds_read_b128 v[180:183], v158
	ds_read_b128 v[184:187], v158 offset:1024
	ds_read_b128 v[188:191], v158 offset:2048
	ds_read_b128 v[192:195], v158 offset:3072
	ds_read_b128 v[196:199], v158 offset:4096
	ds_read_b128 v[200:203], v158 offset:5120
	ds_read_b128 v[204:207], v158 offset:6144
	ds_read_b128 v[208:211], v158 offset:7168
	global_load_lds_dwordx4 v[212:213], off
	v_lshl_add_u64 v[212:213], s[56:57], 0, v[136:137]
	s_add_i32 m0, s55, 0xe000
	s_nop 0
	global_load_lds_dwordx4 v[212:213], off
	s_waitcnt vmcnt(8)
	s_waitcnt lgkmcnt(0)
	s_barrier
	s_waitcnt lgkmcnt(0)
	v_mfma_f32_16x16x32_bf16 v[126:129], v[142:145], v[180:183], v[126:129]
	v_mfma_f32_16x16x32_bf16 v[122:125], v[150:153], v[180:183], v[122:125]
	v_mfma_f32_16x16x32_bf16 v[114:117], v[142:145], v[188:191], v[114:117]
	v_mfma_f32_16x16x32_bf16 v[106:109], v[150:153], v[188:191], v[106:109]
	v_mfma_f32_16x16x32_bf16 v[94:97], v[142:145], v[196:199], v[94:97]
	v_mfma_f32_16x16x32_bf16 v[90:93], v[150:153], v[196:199], v[90:93]
	v_mfma_f32_16x16x32_bf16 v[82:85], v[142:145], v[204:207], v[82:85]
	v_mfma_f32_16x16x32_bf16 v[74:77], v[150:153], v[204:207], v[74:77]
	v_mfma_f32_16x16x32_bf16 v[126:129], v[146:149], v[184:187], v[126:129]
	v_mfma_f32_16x16x32_bf16 v[122:125], v[160:163], v[184:187], v[122:125]
	v_mfma_f32_16x16x32_bf16 v[114:117], v[146:149], v[192:195], v[114:117]
	v_mfma_f32_16x16x32_bf16 v[106:109], v[160:163], v[192:195], v[106:109]
	v_mfma_f32_16x16x32_bf16 v[94:97], v[146:149], v[200:203], v[94:97]
	v_mfma_f32_16x16x32_bf16 v[90:93], v[160:163], v[200:203], v[90:93]
	v_mfma_f32_16x16x32_bf16 v[82:85], v[146:149], v[208:211], v[82:85]
	v_mfma_f32_16x16x32_bf16 v[74:77], v[160:163], v[208:211], v[74:77]
	v_mfma_f32_16x16x32_bf16 v[118:121], v[164:167], v[180:183], v[118:121]
	v_mfma_f32_16x16x32_bf16 v[110:113], v[172:175], v[180:183], v[110:113]
	v_mfma_f32_16x16x32_bf16 v[102:105], v[164:167], v[188:191], v[102:105]
	v_mfma_f32_16x16x32_bf16 v[98:101], v[172:175], v[188:191], v[98:101]
	v_mfma_f32_16x16x32_bf16 v[86:89], v[164:167], v[196:199], v[86:89]
	v_mfma_f32_16x16x32_bf16 v[78:81], v[172:175], v[196:199], v[78:81]
	v_mfma_f32_16x16x32_bf16 v[70:73], v[164:167], v[204:207], v[70:73]
	v_mfma_f32_16x16x32_bf16 v[66:69], v[172:175], v[204:207], v[66:69]
	v_mfma_f32_16x16x32_bf16 v[118:121], v[168:171], v[184:187], v[118:121]
	v_mfma_f32_16x16x32_bf16 v[110:113], v[176:179], v[184:187], v[110:113]
	v_mfma_f32_16x16x32_bf16 v[102:105], v[168:171], v[192:195], v[102:105]
	v_mfma_f32_16x16x32_bf16 v[98:101], v[176:179], v[192:195], v[98:101]
	v_mfma_f32_16x16x32_bf16 v[86:89], v[168:171], v[200:203], v[86:89]
	v_mfma_f32_16x16x32_bf16 v[78:81], v[176:179], v[200:203], v[78:81]
	v_mfma_f32_16x16x32_bf16 v[70:73], v[168:171], v[208:211], v[70:73]
	v_mfma_f32_16x16x32_bf16 v[66:69], v[176:179], v[208:211], v[66:69]
	s_barrier
	s_add_i32 s34, s69, s19
	v_lshl_add_u64 v[212:213], s[58:59], 0, v[130:131]
	s_mov_b32 m0, s34
	ds_read_b128 v[180:183], v158 offset:16384
	ds_read_b128 v[184:187], v158 offset:17408
	ds_read_b128 v[188:191], v158 offset:18432
	ds_read_b128 v[192:195], v158 offset:19456
	ds_read_b128 v[196:199], v158 offset:20480
	ds_read_b128 v[200:203], v158 offset:21504
	ds_read_b128 v[204:207], v158 offset:22528
	ds_read_b128 v[208:211], v158 offset:23552
	global_load_lds_dwordx4 v[212:213], off
	s_add_i32 m0, s34, 0x2000
	s_add_u32 s34, s58, 0x20000
	v_lshl_add_u64 v[214:215], s[58:59], 0, v[132:133]
	s_addc_u32 s35, s59, 0
	s_add_i32 s79, s70, s19
	global_load_lds_dwordx4 v[214:215], off
	v_lshl_add_u64 v[216:217], s[34:35], 0, v[130:131]
	s_mov_b32 m0, s79
	v_lshl_add_u64 v[218:219], s[60:61], 0, v[132:133]
	global_load_lds_dwordx4 v[216:217], off
	v_lshl_add_u64 v[216:217], s[34:35], 0, v[132:133]
	s_add_i32 m0, s79, 0x2000
	s_nop 0
	global_load_lds_dwordx4 v[216:217], off
	v_lshl_add_u64 v[216:217], s[60:61], 0, v[130:131]
	s_mov_b32 m0, s55
	s_nop 0
	global_load_lds_dwordx4 v[216:217], off
	s_mov_b32 m0, s62
	s_nop 0
	global_load_lds_dwordx4 v[218:219], off
	s_waitcnt vmcnt(8)
	s_waitcnt lgkmcnt(0)
	s_barrier
; #define PG8_STAGE(bufoff, gbase, voff) do { _Pragma("unroll") for (int _i = 0; _i < 2; ++_i) \
;         __builtin_amdgcn_global_load_lds((const unsigned*)((const char*)(gbase) + (voff)[_i]), (PG8_LAS unsigned*)(lds + (bufoff) + ldsw + _i * 8192), 16, 0, 0); } while (0)
; #define PG8_LDA(dst, b, h) do { _Pragma("unroll") for (int m = 0; m < 4; ++m) _Pragma("unroll") for (int k = 0; k < 2; ++k) dst[m][k] = *(const PG8_LAS bf16x8*)(lds + PG8_SA(b, h) + aoff + m * 2048 + k * 1024); } while (0)
; #define PG8_LDB(dst, b, h) do { _Pragma("unroll") for (int n = 0; n < 2; ++n) _Pragma("unroll") for (int k = 0; k < 2; ++k) dst[n][k] = *(const PG8_LAS bf16x8*)(lds + PG8_SB(b, h) + boff + n * 2048 + k * 1024); } while (0)
; #define PG8_MMA(ai, bj, At, Bt) do { __builtin_amdgcn_s_setprio(1); _Pragma("unroll") for (int m = 0; m < 4; ++m) _Pragma("unroll") for (int n = 0; n < 2; ++n) _Pragma("unroll") for (int k = 0; k < 2; ++k) \
;         acc[ai][bj][m][n] = __builtin_amdgcn_mfma_f32_16x16x32_bf16(Bt[n][k], At[m][k], acc[ai][bj][m][n], 0, 0, 0); __builtin_amdgcn_s_setprio(0); } while (0)
; #define PG8_WAIT_V(n) asm volatile("s_waitcnt vmcnt(" #n ")" ::: "memory")
; #define PG8_WAIT_L(n) asm volatile("s_waitcnt lgkmcnt(" #n ")" ::: "memory")
; #define PG8_BAR __builtin_amdgcn_s_barrier()
; #define PG8_SCHED __builtin_amdgcn_sched_barrier(0)
; template <class Epi, class Sched, bool ALIGN_EPI = false, bool SP2 = false>
; __device__ __forceinline__ void gemm_phase(PG8_LAS unsigned char* lds, const Gemm g, const Sched& S, const Epi& E) {
;     ...
;             PG8_WAIT_V(8); PG8_WAIT_L(0); PG8_BAR; PG8_MMA(1, 0, At, B0); PG8_MMA(1, 1, At, B1); PG8_BAR; PG8_SCHED;
;             PG8_LDB(B0, 1, 0); PG8_LDB(B1, 1, 1); PG8_SCHED; PG8_LDA(At, 1, 0); PG8_STAGE(PG8_SA(0, 1), a2 + hstep, voffA);
;             PG8_WAIT_V(8); PG8_WAIT_L(0); PG8_BAR; PG8_MMA(0, 0, At, B0); PG8_MMA(0, 1, At, B1); PG8_BAR; PG8_SCHED;
	s_waitcnt lgkmcnt(0)
	v_mfma_f32_16x16x32_bf16 v[62:65], v[142:145], v[180:183], v[62:65]
	v_mfma_f32_16x16x32_bf16 v[58:61], v[150:153], v[180:183], v[58:61]
	v_mfma_f32_16x16x32_bf16 v[50:53], v[142:145], v[188:191], v[50:53]
	v_mfma_f32_16x16x32_bf16 v[42:45], v[150:153], v[188:191], v[42:45]
	v_mfma_f32_16x16x32_bf16 v[30:33], v[142:145], v[196:199], v[30:33]
	v_mfma_f32_16x16x32_bf16 v[26:29], v[150:153], v[196:199], v[26:29]
	v_mfma_f32_16x16x32_bf16 v[18:21], v[142:145], v[204:207], v[18:21]
	v_mfma_f32_16x16x32_bf16 v[10:13], v[150:153], v[204:207], v[10:13]
	v_mfma_f32_16x16x32_bf16 v[62:65], v[146:149], v[184:187], v[62:65]
	v_mfma_f32_16x16x32_bf16 v[58:61], v[160:163], v[184:187], v[58:61]
	v_mfma_f32_16x16x32_bf16 v[50:53], v[146:149], v[192:195], v[50:53]
	v_mfma_f32_16x16x32_bf16 v[42:45], v[160:163], v[192:195], v[42:45]
	v_mfma_f32_16x16x32_bf16 v[30:33], v[146:149], v[200:203], v[30:33]
	v_mfma_f32_16x16x32_bf16 v[26:29], v[160:163], v[200:203], v[26:29]
	v_mfma_f32_16x16x32_bf16 v[18:21], v[146:149], v[208:211], v[18:21]
	v_mfma_f32_16x16x32_bf16 v[10:13], v[160:163], v[208:211], v[10:13]
	v_mfma_f32_16x16x32_bf16 v[54:57], v[164:167], v[180:183], v[54:57]
	v_mfma_f32_16x16x32_bf16 v[46:49], v[172:175], v[180:183], v[46:49]
	v_mfma_f32_16x16x32_bf16 v[38:41], v[164:167], v[188:191], v[38:41]
	v_mfma_f32_16x16x32_bf16 v[34:37], v[172:175], v[188:191], v[34:37]
	v_mfma_f32_16x16x32_bf16 v[22:25], v[164:167], v[196:199], v[22:25]
	v_mfma_f32_16x16x32_bf16 v[14:17], v[172:175], v[196:199], v[14:17]
	v_mfma_f32_16x16x32_bf16 v[6:9], v[164:167], v[204:207], v[6:9]
	v_mfma_f32_16x16x32_bf16 v[2:5], v[172:175], v[204:207], v[2:5]
	v_mfma_f32_16x16x32_bf16 v[54:57], v[168:171], v[184:187], v[54:57]
	v_mfma_f32_16x16x32_bf16 v[46:49], v[176:179], v[184:187], v[46:49]
	v_mfma_f32_16x16x32_bf16 v[38:41], v[168:171], v[192:195], v[38:41]
	v_mfma_f32_16x16x32_bf16 v[34:37], v[176:179], v[192:195], v[34:37]
	v_mfma_f32_16x16x32_bf16 v[22:25], v[168:171], v[200:203], v[22:25]
	v_mfma_f32_16x16x32_bf16 v[14:17], v[176:179], v[200:203], v[14:17]
	v_mfma_f32_16x16x32_bf16 v[6:9], v[168:171], v[208:211], v[6:9]
	v_mfma_f32_16x16x32_bf16 v[2:5], v[176:179], v[208:211], v[2:5]
	s_barrier
	s_add_i32 s79, 0, 0x18000
	v_add_u32_e32 v159, s79, v154
	s_add_i32 s80, 0, 0x1c000
	ds_read_b128 v[142:145], v159
	ds_read_b128 v[146:149], v159 offset:1024
	ds_read_b128 v[150:153], v159 offset:2048
	ds_read_b128 v[160:163], v159 offset:3072
	v_add_u32_e32 v159, s80, v154
	ds_read_b128 v[164:167], v159
	ds_read_b128 v[168:171], v159 offset:1024
	ds_read_b128 v[172:175], v159 offset:2048
	ds_read_b128 v[176:179], v159 offset:3072
	s_add_u32 s34, s60, 0x20000
	s_addc_u32 s35, s61, 0
	s_mov_b32 m0, s63
	v_lshl_add_u64 v[220:221], s[34:35], 0, v[130:131]
	ds_read_b128 v[180:183], v158 offset:32768
	ds_read_b128 v[184:187], v158 offset:33792
	ds_read_b128 v[188:191], v158 offset:34816
	ds_read_b128 v[192:195], v158 offset:35840
	ds_read_b128 v[196:199], v158 offset:36864
	ds_read_b128 v[200:203], v158 offset:37888
	ds_read_b128 v[204:207], v158 offset:38912
	ds_read_b128 v[208:211], v158 offset:39936
	global_load_lds_dwordx4 v[220:221], off
	v_lshl_add_u64 v[220:221], s[34:35], 0, v[132:133]
	s_mov_b32 m0, s64
	s_nop 0
	global_load_lds_dwordx4 v[220:221], off
	s_waitcnt vmcnt(8)
	s_waitcnt lgkmcnt(0)
	s_barrier
	s_waitcnt lgkmcnt(0)
	v_mfma_f32_16x16x32_bf16 v[126:129], v[142:145], v[180:183], v[126:129]
	v_mfma_f32_16x16x32_bf16 v[122:125], v[150:153], v[180:183], v[122:125]
	v_mfma_f32_16x16x32_bf16 v[114:117], v[142:145], v[188:191], v[114:117]
	v_mfma_f32_16x16x32_bf16 v[106:109], v[150:153], v[188:191], v[106:109]
	v_mfma_f32_16x16x32_bf16 v[94:97], v[142:145], v[196:199], v[94:97]
	v_mfma_f32_16x16x32_bf16 v[90:93], v[150:153], v[196:199], v[90:93]
	v_mfma_f32_16x16x32_bf16 v[82:85], v[142:145], v[204:207], v[82:85]
	v_mfma_f32_16x16x32_bf16 v[74:77], v[150:153], v[204:207], v[74:77]
	v_mfma_f32_16x16x32_bf16 v[126:129], v[146:149], v[184:187], v[126:129]
	v_mfma_f32_16x16x32_bf16 v[122:125], v[160:163], v[184:187], v[122:125]
	v_mfma_f32_16x16x32_bf16 v[114:117], v[146:149], v[192:195], v[114:117]
	v_mfma_f32_16x16x32_bf16 v[106:109], v[160:163], v[192:195], v[106:109]
	v_mfma_f32_16x16x32_bf16 v[94:97], v[146:149], v[200:203], v[94:97]
	v_mfma_f32_16x16x32_bf16 v[90:93], v[160:163], v[200:203], v[90:93]
	v_mfma_f32_16x16x32_bf16 v[82:85], v[146:149], v[208:211], v[82:85]
	v_mfma_f32_16x16x32_bf16 v[74:77], v[160:163], v[208:211], v[74:77]
	v_mfma_f32_16x16x32_bf16 v[118:121], v[164:167], v[180:183], v[118:121]
	v_mfma_f32_16x16x32_bf16 v[110:113], v[172:175], v[180:183], v[110:113]
	v_mfma_f32_16x16x32_bf16 v[102:105], v[164:167], v[188:191], v[102:105]
	v_mfma_f32_16x16x32_bf16 v[98:101], v[172:175], v[188:191], v[98:101]
	v_mfma_f32_16x16x32_bf16 v[86:89], v[164:167], v[196:199], v[86:89]
	v_mfma_f32_16x16x32_bf16 v[78:81], v[172:175], v[196:199], v[78:81]
	v_mfma_f32_16x16x32_bf16 v[70:73], v[164:167], v[204:207], v[70:73]
	v_mfma_f32_16x16x32_bf16 v[66:69], v[172:175], v[204:207], v[66:69]
	v_mfma_f32_16x16x32_bf16 v[118:121], v[168:171], v[184:187], v[118:121]
	v_mfma_f32_16x16x32_bf16 v[110:113], v[176:179], v[184:187], v[110:113]
	v_mfma_f32_16x16x32_bf16 v[102:105], v[168:171], v[192:195], v[102:105]
	v_mfma_f32_16x16x32_bf16 v[98:101], v[176:179], v[192:195], v[98:101]
	v_mfma_f32_16x16x32_bf16 v[86:89], v[168:171], v[200:203], v[86:89]
	v_mfma_f32_16x16x32_bf16 v[78:81], v[176:179], v[200:203], v[78:81]
	v_mfma_f32_16x16x32_bf16 v[70:73], v[168:171], v[208:211], v[70:73]
	v_mfma_f32_16x16x32_bf16 v[66:69], v[176:179], v[208:211], v[66:69]
	s_barrier
; #define PG8_STAGE(bufoff, gbase, voff) do { _Pragma("unroll") for (int _i = 0; _i < 2; ++_i) \
;         __builtin_amdgcn_global_load_lds((const unsigned*)((const char*)(gbase) + (voff)[_i]), (PG8_LAS unsigned*)(lds + (bufoff) + ldsw + _i * 8192), 16, 0, 0); } while (0)
; #define PG8_LDA(dst, b, h) do { _Pragma("unroll") for (int m = 0; m < 4; ++m) _Pragma("unroll") for (int k = 0; k < 2; ++k) dst[m][k] = *(const PG8_LAS bf16x8*)(lds + PG8_SA(b, h) + aoff + m * 2048 + k * 1024); } while (0)
; #define PG8_MMA(ai, bj, At, Bt) do { __builtin_amdgcn_s_setprio(1); _Pragma("unroll") for (int m = 0; m < 4; ++m) _Pragma("unroll") for (int n = 0; n < 2; ++n) _Pragma("unroll") for (int k = 0; k < 2; ++k) \
;         acc[ai][bj][m][n] = __builtin_amdgcn_mfma_f32_16x16x32_bf16(Bt[n][k], At[m][k], acc[ai][bj][m][n], 0, 0, 0); __builtin_amdgcn_s_setprio(0); } while (0)
; #define PG8_WAIT_V(n) asm volatile("s_waitcnt vmcnt(" #n ")" ::: "memory")
; #define PG8_WAIT_L(n) asm volatile("s_waitcnt lgkmcnt(" #n ")" ::: "memory")
; #define PG8_BAR __builtin_amdgcn_s_barrier()
; #define PG8_SCHED __builtin_amdgcn_sched_barrier(0)
; template <class Epi, class Sched, bool ALIGN_EPI = false, bool SP2 = false>
; __device__ __forceinline__ void gemm_phase(PG8_LAS unsigned char* lds, const Gemm g, const Sched& S, const Epi& E) {
;     ...
;         for (int t = 0; t < nt; t += 2) {
;             const bool last = (t == nt - 2);
;             const char* a1 = cA + (size_t)(t + 1) * kstep;
;             const char* a2 = last ? nA : cA + (size_t)(t + 2) * kstep; const char* b2 = last ? nB : cB + (size_t)(t + 2) * kstep;
;     ...
;             PG8_LDA(At, 1, 1); PG8_STAGE(PG8_SB(1, 0), b3, voffB); PG8_STAGE(PG8_SB(1, 1), b3 + hstep, voffB); PG8_STAGE(PG8_SA(1, 0), a3, voffA);
;             PG8_WAIT_V(8); PG8_WAIT_L(0); PG8_BAR; PG8_MMA(1, 0, At, B0); PG8_MMA(1, 1, At, B1); PG8_BAR; PG8_SCHED;
	s_add_i32 s34, s79, s19
	v_lshl_add_u64 v[212:213], v[212:213], 0, s[42:43]
	s_mov_b32 m0, s34
	ds_read_b128 v[180:183], v158 offset:49152
	ds_read_b128 v[184:187], v158 offset:50176
	ds_read_b128 v[188:191], v158 offset:51200
	ds_read_b128 v[192:195], v158 offset:52224
	ds_read_b128 v[196:199], v158 offset:53248
	ds_read_b128 v[200:203], v158 offset:54272
	ds_read_b128 v[204:207], v158 offset:55296
	ds_read_b128 v[208:211], v158 offset:56320
	global_load_lds_dwordx4 v[212:213], off
	s_add_i32 m0, s34, 0x2000
	s_add_u32 s34, s58, 0x20080
	v_lshl_add_u64 v[212:213], v[214:215], 0, s[42:43]
	s_addc_u32 s35, s59, 0
	s_add_i32 s58, s80, s19
	global_load_lds_dwordx4 v[212:213], off
	v_lshl_add_u64 v[212:213], s[34:35], 0, v[130:131]
	s_mov_b32 m0, s58
	s_nop 0
	global_load_lds_dwordx4 v[212:213], off
	v_lshl_add_u64 v[212:213], s[34:35], 0, v[132:133]
	s_add_i32 m0, s58, 0x2000
	s_nop 0
	global_load_lds_dwordx4 v[212:213], off
	v_lshl_add_u64 v[212:213], v[216:217], 0, s[42:43]
	s_mov_b32 m0, s66
	s_nop 0
	global_load_lds_dwordx4 v[212:213], off
	v_lshl_add_u64 v[212:213], v[218:219], 0, s[42:43]
	s_mov_b32 m0, s67
	s_nop 0
	global_load_lds_dwordx4 v[212:213], off
	s_waitcnt vmcnt(8)
	s_waitcnt lgkmcnt(0)
	s_barrier
	s_waitcnt lgkmcnt(0)
	v_mfma_f32_16x16x32_bf16 v[62:65], v[142:145], v[180:183], v[62:65]
	v_mfma_f32_16x16x32_bf16 v[58:61], v[150:153], v[180:183], v[58:61]
	v_mfma_f32_16x16x32_bf16 v[50:53], v[142:145], v[188:191], v[50:53]
	v_mfma_f32_16x16x32_bf16 v[42:45], v[150:153], v[188:191], v[42:45]
	v_mfma_f32_16x16x32_bf16 v[30:33], v[142:145], v[196:199], v[30:33]
	v_mfma_f32_16x16x32_bf16 v[26:29], v[150:153], v[196:199], v[26:29]
	v_mfma_f32_16x16x32_bf16 v[18:21], v[142:145], v[204:207], v[18:21]
	v_mfma_f32_16x16x32_bf16 v[10:13], v[150:153], v[204:207], v[10:13]
	v_mfma_f32_16x16x32_bf16 v[62:65], v[146:149], v[184:187], v[62:65]
	v_mfma_f32_16x16x32_bf16 v[58:61], v[160:163], v[184:187], v[58:61]
	v_mfma_f32_16x16x32_bf16 v[50:53], v[146:149], v[192:195], v[50:53]
	v_mfma_f32_16x16x32_bf16 v[42:45], v[160:163], v[192:195], v[42:45]
	v_mfma_f32_16x16x32_bf16 v[30:33], v[146:149], v[200:203], v[30:33]
	v_mfma_f32_16x16x32_bf16 v[26:29], v[160:163], v[200:203], v[26:29]
	v_mfma_f32_16x16x32_bf16 v[18:21], v[146:149], v[208:211], v[18:21]
	v_mfma_f32_16x16x32_bf16 v[10:13], v[160:163], v[208:211], v[10:13]
	v_mfma_f32_16x16x32_bf16 v[54:57], v[164:167], v[180:183], v[54:57]
	v_mfma_f32_16x16x32_bf16 v[46:49], v[172:175], v[180:183], v[46:49]
	v_mfma_f32_16x16x32_bf16 v[38:41], v[164:167], v[188:191], v[38:41]
	v_mfma_f32_16x16x32_bf16 v[34:37], v[172:175], v[188:191], v[34:37]
	v_mfma_f32_16x16x32_bf16 v[22:25], v[164:167], v[196:199], v[22:25]
	v_mfma_f32_16x16x32_bf16 v[14:17], v[172:175], v[196:199], v[14:17]
	v_mfma_f32_16x16x32_bf16 v[6:9], v[164:167], v[204:207], v[6:9]
	v_mfma_f32_16x16x32_bf16 v[2:5], v[172:175], v[204:207], v[2:5]
	v_mfma_f32_16x16x32_bf16 v[54:57], v[168:171], v[184:187], v[54:57]
	v_mfma_f32_16x16x32_bf16 v[46:49], v[176:179], v[184:187], v[46:49]
	v_mfma_f32_16x16x32_bf16 v[38:41], v[168:171], v[192:195], v[38:41]
	v_mfma_f32_16x16x32_bf16 v[34:37], v[176:179], v[192:195], v[34:37]
	v_mfma_f32_16x16x32_bf16 v[22:25], v[168:171], v[200:203], v[22:25]
	v_mfma_f32_16x16x32_bf16 v[14:17], v[176:179], v[200:203], v[14:17]
	v_mfma_f32_16x16x32_bf16 v[6:9], v[168:171], v[208:211], v[6:9]
	v_mfma_f32_16x16x32_bf16 v[2:5], v[176:179], v[208:211], v[2:5]
	s_barrier
	s_add_i32 s78, s78, 2
	s_add_u32 s56, s56, 0x100
	s_addc_u32 s57, s57, 0
	s_add_u32 s76, s76, 0x100
	s_addc_u32 s77, s77, 0
	s_cmp_gt_u32 s78, 5
	s_cbranch_scc0 .LBB0_1601
	s_and_b64 vcc, exec, s[44:45]
	s_cbranch_vccz .LBB0_1604
	s_barrier

; #define PG8_STAGE(bufoff, gbase, voff) do { _Pragma("unroll") for (int _i = 0; _i < 2; ++_i) \
;         __builtin_amdgcn_global_load_lds((const unsigned*)((const char*)(gbase) + (voff)[_i]), (PG8_LAS unsigned*)(lds + (bufoff) + ldsw + _i * 8192), 16, 0, 0); } while (0)
; #define PG8_LDA(dst, b, h) do { _Pragma("unroll") for (int m = 0; m < 4; ++m) _Pragma("unroll") for (int k = 0; k < 2; ++k) dst[m][k] = *(const PG8_LAS bf16x8*)(lds + PG8_SA(b, h) + aoff + m * 2048 + k * 1024); } while (0)
; #define PG8_LDB(dst, b, h) do { _Pragma("unroll") for (int n = 0; n < 2; ++n) _Pragma("unroll") for (int k = 0; k < 2; ++k) dst[n][k] = *(const PG8_LAS bf16x8*)(lds + PG8_SB(b, h) + boff + n * 2048 + k * 1024); } while (0)
; #define PG8_MMA(ai, bj, At, Bt) do { __builtin_amdgcn_s_setprio(1); _Pragma("unroll") for (int m = 0; m < 4; ++m) _Pragma("unroll") for (int n = 0; n < 2; ++n) _Pragma("unroll") for (int k = 0; k < 2; ++k) \
;         acc[ai][bj][m][n] = __builtin_amdgcn_mfma_f32_16x16x32_bf16(Bt[n][k], At[m][k], acc[ai][bj][m][n], 0, 0, 0); __builtin_amdgcn_s_setprio(0); } while (0)
; #define PG8_WAIT_V(n) asm volatile("s_waitcnt vmcnt(" #n ")" ::: "memory")
; #define PG8_BAR __builtin_amdgcn_s_barrier()
; template <class Epi, class Sched, bool ALIGN_EPI = false, bool SP2 = false>
; __device__ __forceinline__ void gemm_phase(PG8_LAS unsigned char* lds, const Gemm g, const Sched& S, const Epi& E) {
;     ...
;         for (int t = 0; t < nt; t += 2) {
;             const bool last = (t == nt - 2);
;             const char* a1 = cA + (size_t)(t + 1) * kstep;
;             const char* a2 = last ? nA : cA + (size_t)(t + 2) * kstep; const char* b2 = last ? nB : cB + (size_t)(t + 2) * kstep;
;             const char* a3 = a2 + kstep; const char* b3 = b2 + kstep;
;             if (last && has_next) S.a_ready(nxt);
;             if constexpr (SP2) {
;             PG8_LDB(B0, 0, 0); PG8_LDB(B1, 0, 1); PG8_SCHED; PG8_LDA(At, 0, 0); PG8_STAGE(PG8_SA(1, 1), a1 + hstep, voffA);
;             PG8_WAIT_V(8); PG8_WAIT_L(0); PG8_BAR; PG8_MMA(0, 0, At, B0); PG8_MMA(0, 1, At, B1); PG8_BAR; PG8_SCHED;
;             PG8_LDA(At, 0, 1); PG8_STAGE(PG8_SB(0, 0), b2, voffB); PG8_STAGE(PG8_SB(0, 1), b2 + hstep, voffB); PG8_STAGE(PG8_SA(0, 0), a2, voffA);
;             PG8_WAIT_V(8); PG8_WAIT_L(0); PG8_BAR; PG8_MMA(1, 0, At, B0); PG8_MMA(1, 1, At, B1); PG8_BAR; PG8_SCHED;
.LBB0_1746:
	ds_read_b128 v[130:133], v173
	ds_read_b128 v[148:151], v173 offset:1024
	ds_read_b128 v[178:181], v173 offset:2048
	ds_read_b128 v[182:185], v173 offset:3072
	ds_read_b128 v[186:189], v174
	ds_read_b128 v[190:193], v174 offset:1024
	ds_read_b128 v[194:197], v174 offset:2048
	ds_read_b128 v[198:201], v174 offset:3072
	s_add_u32 s50, s10, 0xfffc0080
	s_addc_u32 s51, s11, -1
	s_cmp_eq_u32 s80, 12
	s_cselect_b32 s53, s9, s51
	s_cselect_b32 s52, s43, s50
	s_cselect_b32 s51, s41, s79
	s_cselect_b32 s50, s77, s78
	v_lshl_add_u64 v[166:167], s[10:11], 0, v[140:141]
	s_add_i32 m0, s49, 0xc000
	ds_read_b128 v[202:205], v175
	ds_read_b128 v[206:209], v175 offset:1024
	ds_read_b128 v[210:213], v175 offset:2048
	ds_read_b128 v[214:217], v175 offset:3072
	ds_read_b128 v[218:221], v175 offset:4096
	ds_read_b128 v[222:225], v175 offset:5120
	ds_read_b128 v[226:229], v175 offset:6144
	ds_read_b128 v[230:233], v175 offset:7168
	global_load_lds_dwordx4 v[166:167], off
	v_lshl_add_u64 v[166:167], s[10:11], 0, v[142:143]
	s_add_i32 m0, s49, 0xe000
	s_nop 0
	global_load_lds_dwordx4 v[166:167], off
	s_waitcnt vmcnt(8)
	s_waitcnt lgkmcnt(0)
	s_barrier
	s_waitcnt lgkmcnt(0)
	v_mfma_f32_16x16x32_bf16 v[126:129], v[130:133], v[202:205], v[126:129]
	v_mfma_f32_16x16x32_bf16 v[122:125], v[178:181], v[202:205], v[122:125]
	v_mfma_f32_16x16x32_bf16 v[110:113], v[130:133], v[210:213], v[110:113]
	v_mfma_f32_16x16x32_bf16 v[106:109], v[178:181], v[210:213], v[106:109]
	v_mfma_f32_16x16x32_bf16 v[94:97], v[130:133], v[218:221], v[94:97]
	v_mfma_f32_16x16x32_bf16 v[90:93], v[178:181], v[218:221], v[90:93]
	v_mfma_f32_16x16x32_bf16 v[78:81], v[130:133], v[226:229], v[78:81]
	v_mfma_f32_16x16x32_bf16 v[74:77], v[178:181], v[226:229], v[74:77]
	v_mfma_f32_16x16x32_bf16 v[126:129], v[148:151], v[206:209], v[126:129]
	v_mfma_f32_16x16x32_bf16 v[122:125], v[182:185], v[206:209], v[122:125]
	v_mfma_f32_16x16x32_bf16 v[110:113], v[148:151], v[214:217], v[110:113]
	v_mfma_f32_16x16x32_bf16 v[106:109], v[182:185], v[214:217], v[106:109]
	v_mfma_f32_16x16x32_bf16 v[94:97], v[148:151], v[222:225], v[94:97]
	v_mfma_f32_16x16x32_bf16 v[90:93], v[182:185], v[222:225], v[90:93]
	v_mfma_f32_16x16x32_bf16 v[78:81], v[148:151], v[230:233], v[78:81]
	v_mfma_f32_16x16x32_bf16 v[74:77], v[182:185], v[230:233], v[74:77]
	v_mfma_f32_16x16x32_bf16 v[118:121], v[186:189], v[202:205], v[118:121]
	v_mfma_f32_16x16x32_bf16 v[114:117], v[194:197], v[202:205], v[114:117]
	v_mfma_f32_16x16x32_bf16 v[102:105], v[186:189], v[210:213], v[102:105]
	v_mfma_f32_16x16x32_bf16 v[98:101], v[194:197], v[210:213], v[98:101]
	v_mfma_f32_16x16x32_bf16 v[86:89], v[186:189], v[218:221], v[86:89]
	v_mfma_f32_16x16x32_bf16 v[82:85], v[194:197], v[218:221], v[82:85]
	v_mfma_f32_16x16x32_bf16 v[70:73], v[186:189], v[226:229], v[70:73]
	v_mfma_f32_16x16x32_bf16 v[66:69], v[194:197], v[226:229], v[66:69]
	v_mfma_f32_16x16x32_bf16 v[118:121], v[190:193], v[206:209], v[118:121]
	v_mfma_f32_16x16x32_bf16 v[114:117], v[198:201], v[206:209], v[114:117]
	v_mfma_f32_16x16x32_bf16 v[102:105], v[190:193], v[214:217], v[102:105]
	v_mfma_f32_16x16x32_bf16 v[98:101], v[198:201], v[214:217], v[98:101]
	v_mfma_f32_16x16x32_bf16 v[86:89], v[190:193], v[222:225], v[86:89]
	v_mfma_f32_16x16x32_bf16 v[82:85], v[198:201], v[222:225], v[82:85]
	v_mfma_f32_16x16x32_bf16 v[70:73], v[190:193], v[230:233], v[70:73]
	v_mfma_f32_16x16x32_bf16 v[66:69], v[198:201], v[230:233], v[66:69]
	s_barrier
	s_add_i32 s81, s64, s54
	v_lshl_add_u64 v[166:167], s[50:51], 0, v[134:135]
	s_mov_b32 m0, s81
	ds_read_b128 v[202:205], v175 offset:16384
	ds_read_b128 v[206:209], v175 offset:17408
	ds_read_b128 v[210:213], v175 offset:18432
	ds_read_b128 v[214:217], v175 offset:19456
	ds_read_b128 v[218:221], v175 offset:20480
	ds_read_b128 v[222:225], v175 offset:21504
	ds_read_b128 v[226:229], v175 offset:22528
	ds_read_b128 v[230:233], v175 offset:23552
	global_load_lds_dwordx4 v[166:167], off
	s_add_i32 m0, s81, 0x2000
	s_add_u32 s82, s50, 0x40000
	v_lshl_add_u64 v[234:235], s[50:51], 0, v[136:137]
	s_addc_u32 s83, s51, 0
	s_add_i32 s81, s65, s54
	global_load_lds_dwordx4 v[234:235], off
	v_lshl_add_u64 v[236:237], s[82:83], 0, v[134:135]
	s_mov_b32 m0, s81
	v_lshl_add_u64 v[238:239], s[52:53], 0, v[136:137]
	global_load_lds_dwordx4 v[236:237], off
	v_lshl_add_u64 v[236:237], s[82:83], 0, v[136:137]
	s_add_i32 m0, s81, 0x2000
	s_nop 0
	global_load_lds_dwordx4 v[236:237], off
	v_lshl_add_u64 v[236:237], s[52:53], 0, v[134:135]
	s_mov_b32 m0, s49
	s_nop 0
	global_load_lds_dwordx4 v[236:237], off
	s_mov_b32 m0, s55
	s_nop 0
	global_load_lds_dwordx4 v[238:239], off
	s_waitcnt vmcnt(8)
	s_waitcnt lgkmcnt(0)
	s_barrier
; #define PG8_STAGE(bufoff, gbase, voff) do { _Pragma("unroll") for (int _i = 0; _i < 2; ++_i) \
;         __builtin_amdgcn_global_load_lds((const unsigned*)((const char*)(gbase) + (voff)[_i]), (PG8_LAS unsigned*)(lds + (bufoff) + ldsw + _i * 8192), 16, 0, 0); } while (0)
; #define PG8_LDA(dst, b, h) do { _Pragma("unroll") for (int m = 0; m < 4; ++m) _Pragma("unroll") for (int k = 0; k < 2; ++k) dst[m][k] = *(const PG8_LAS bf16x8*)(lds + PG8_SA(b, h) + aoff + m * 2048 + k * 1024); } while (0)
; #define PG8_LDB(dst, b, h) do { _Pragma("unroll") for (int n = 0; n < 2; ++n) _Pragma("unroll") for (int k = 0; k < 2; ++k) dst[n][k] = *(const PG8_LAS bf16x8*)(lds + PG8_SB(b, h) + boff + n * 2048 + k * 1024); } while (0)
; #define PG8_MMA(ai, bj, At, Bt) do { __builtin_amdgcn_s_setprio(1); _Pragma("unroll") for (int m = 0; m < 4; ++m) _Pragma("unroll") for (int n = 0; n < 2; ++n) _Pragma("unroll") for (int k = 0; k < 2; ++k) \
;         acc[ai][bj][m][n] = __builtin_amdgcn_mfma_f32_16x16x32_bf16(Bt[n][k], At[m][k], acc[ai][bj][m][n], 0, 0, 0); __builtin_amdgcn_s_setprio(0); } while (0)
; #define PG8_WAIT_V(n) asm volatile("s_waitcnt vmcnt(" #n ")" ::: "memory")
; #define PG8_WAIT_L(n) asm volatile("s_waitcnt lgkmcnt(" #n ")" ::: "memory")
; #define PG8_BAR __builtin_amdgcn_s_barrier()
; #define PG8_SCHED __builtin_amdgcn_sched_barrier(0)
; template <class Epi, class Sched, bool ALIGN_EPI = false, bool SP2 = false>
; __device__ __forceinline__ void gemm_phase(PG8_LAS unsigned char* lds, const Gemm g, const Sched& S, const Epi& E) {
;     ...
;             PG8_WAIT_V(8); PG8_WAIT_L(0); PG8_BAR; PG8_MMA(1, 0, At, B0); PG8_MMA(1, 1, At, B1); PG8_BAR; PG8_SCHED;
;             PG8_LDB(B0, 1, 0); PG8_LDB(B1, 1, 1); PG8_SCHED; PG8_LDA(At, 1, 0); PG8_STAGE(PG8_SA(0, 1), a2 + hstep, voffA);
;             PG8_WAIT_V(8); PG8_WAIT_L(0); PG8_BAR; PG8_MMA(0, 0, At, B0); PG8_MMA(0, 1, At, B1); PG8_BAR; PG8_SCHED;
	s_waitcnt lgkmcnt(0)
	v_mfma_f32_16x16x32_bf16 v[62:65], v[130:133], v[202:205], v[62:65]
	v_mfma_f32_16x16x32_bf16 v[58:61], v[178:181], v[202:205], v[58:61]
	v_mfma_f32_16x16x32_bf16 v[46:49], v[130:133], v[210:213], v[46:49]
	v_mfma_f32_16x16x32_bf16 v[42:45], v[178:181], v[210:213], v[42:45]
	v_mfma_f32_16x16x32_bf16 v[30:33], v[130:133], v[218:221], v[30:33]
	v_mfma_f32_16x16x32_bf16 v[26:29], v[178:181], v[218:221], v[26:29]
	v_mfma_f32_16x16x32_bf16 v[14:17], v[130:133], v[226:229], v[14:17]
	v_mfma_f32_16x16x32_bf16 v[10:13], v[178:181], v[226:229], v[10:13]
	v_mfma_f32_16x16x32_bf16 v[62:65], v[148:151], v[206:209], v[62:65]
	v_mfma_f32_16x16x32_bf16 v[58:61], v[182:185], v[206:209], v[58:61]
	v_mfma_f32_16x16x32_bf16 v[46:49], v[148:151], v[214:217], v[46:49]
	v_mfma_f32_16x16x32_bf16 v[42:45], v[182:185], v[214:217], v[42:45]
	v_mfma_f32_16x16x32_bf16 v[30:33], v[148:151], v[222:225], v[30:33]
	v_mfma_f32_16x16x32_bf16 v[26:29], v[182:185], v[222:225], v[26:29]
	v_mfma_f32_16x16x32_bf16 v[14:17], v[148:151], v[230:233], v[14:17]
	v_mfma_f32_16x16x32_bf16 v[10:13], v[182:185], v[230:233], v[10:13]
	v_mfma_f32_16x16x32_bf16 v[54:57], v[186:189], v[202:205], v[54:57]
	v_mfma_f32_16x16x32_bf16 v[50:53], v[194:197], v[202:205], v[50:53]
	v_mfma_f32_16x16x32_bf16 v[38:41], v[186:189], v[210:213], v[38:41]
	v_mfma_f32_16x16x32_bf16 v[34:37], v[194:197], v[210:213], v[34:37]
	v_mfma_f32_16x16x32_bf16 v[22:25], v[186:189], v[218:221], v[22:25]
	v_mfma_f32_16x16x32_bf16 v[18:21], v[194:197], v[218:221], v[18:21]
	v_mfma_f32_16x16x32_bf16 v[6:9], v[186:189], v[226:229], v[6:9]
	v_mfma_f32_16x16x32_bf16 v[2:5], v[194:197], v[226:229], v[2:5]
	v_mfma_f32_16x16x32_bf16 v[54:57], v[190:193], v[206:209], v[54:57]
	v_mfma_f32_16x16x32_bf16 v[50:53], v[198:201], v[206:209], v[50:53]
	v_mfma_f32_16x16x32_bf16 v[38:41], v[190:193], v[214:217], v[38:41]
	v_mfma_f32_16x16x32_bf16 v[34:37], v[198:201], v[214:217], v[34:37]
	v_mfma_f32_16x16x32_bf16 v[22:25], v[190:193], v[222:225], v[22:25]
	v_mfma_f32_16x16x32_bf16 v[18:21], v[198:201], v[222:225], v[18:21]
	v_mfma_f32_16x16x32_bf16 v[6:9], v[190:193], v[230:233], v[6:9]
	v_mfma_f32_16x16x32_bf16 v[2:5], v[198:201], v[230:233], v[2:5]
	s_barrier
	s_add_i32 s81, 0, 0x18000
	v_add_u32_e32 v138, s81, v170
	s_add_i32 s82, 0, 0x1c000
	ds_read_b128 v[130:133], v138
	ds_read_b128 v[148:151], v138 offset:1024
	ds_read_b128 v[178:181], v138 offset:2048
	ds_read_b128 v[182:185], v138 offset:3072
	v_add_u32_e32 v138, s82, v170
	ds_read_b128 v[186:189], v138
	ds_read_b128 v[190:193], v138 offset:1024
	ds_read_b128 v[194:197], v138 offset:2048
	ds_read_b128 v[198:201], v138 offset:3072
	s_add_u32 s52, s52, 0x40000
	s_addc_u32 s53, s53, 0
	s_mov_b32 m0, s56
	v_lshl_add_u64 v[240:241], s[52:53], 0, v[134:135]
	ds_read_b128 v[202:205], v175 offset:32768
	ds_read_b128 v[206:209], v175 offset:33792
	ds_read_b128 v[210:213], v175 offset:34816
	ds_read_b128 v[214:217], v175 offset:35840
	ds_read_b128 v[218:221], v175 offset:36864
	ds_read_b128 v[222:225], v175 offset:37888
	ds_read_b128 v[226:229], v175 offset:38912
	ds_read_b128 v[230:233], v175 offset:39936
	global_load_lds_dwordx4 v[240:241], off
	v_lshl_add_u64 v[240:241], s[52:53], 0, v[136:137]
	s_mov_b32 m0, s57
	s_nop 0
	global_load_lds_dwordx4 v[240:241], off
	s_waitcnt vmcnt(8)
	s_waitcnt lgkmcnt(0)
	s_barrier
	s_waitcnt lgkmcnt(0)
	v_mfma_f32_16x16x32_bf16 v[126:129], v[130:133], v[202:205], v[126:129]
	v_mfma_f32_16x16x32_bf16 v[122:125], v[178:181], v[202:205], v[122:125]
	v_mfma_f32_16x16x32_bf16 v[110:113], v[130:133], v[210:213], v[110:113]
	v_mfma_f32_16x16x32_bf16 v[106:109], v[178:181], v[210:213], v[106:109]
	v_mfma_f32_16x16x32_bf16 v[94:97], v[130:133], v[218:221], v[94:97]
	v_mfma_f32_16x16x32_bf16 v[90:93], v[178:181], v[218:221], v[90:93]
	v_mfma_f32_16x16x32_bf16 v[78:81], v[130:133], v[226:229], v[78:81]
	v_mfma_f32_16x16x32_bf16 v[74:77], v[178:181], v[226:229], v[74:77]
	v_mfma_f32_16x16x32_bf16 v[126:129], v[148:151], v[206:209], v[126:129]
	v_mfma_f32_16x16x32_bf16 v[122:125], v[182:185], v[206:209], v[122:125]
	v_mfma_f32_16x16x32_bf16 v[110:113], v[148:151], v[214:217], v[110:113]
	v_mfma_f32_16x16x32_bf16 v[106:109], v[182:185], v[214:217], v[106:109]
	v_mfma_f32_16x16x32_bf16 v[94:97], v[148:151], v[222:225], v[94:97]
	v_mfma_f32_16x16x32_bf16 v[90:93], v[182:185], v[222:225], v[90:93]
	v_mfma_f32_16x16x32_bf16 v[78:81], v[148:151], v[230:233], v[78:81]
	v_mfma_f32_16x16x32_bf16 v[74:77], v[182:185], v[230:233], v[74:77]
	v_mfma_f32_16x16x32_bf16 v[118:121], v[186:189], v[202:205], v[118:121]
	v_mfma_f32_16x16x32_bf16 v[114:117], v[194:197], v[202:205], v[114:117]
	v_mfma_f32_16x16x32_bf16 v[102:105], v[186:189], v[210:213], v[102:105]
	v_mfma_f32_16x16x32_bf16 v[98:101], v[194:197], v[210:213], v[98:101]
	v_mfma_f32_16x16x32_bf16 v[86:89], v[186:189], v[218:221], v[86:89]
	v_mfma_f32_16x16x32_bf16 v[82:85], v[194:197], v[218:221], v[82:85]
	v_mfma_f32_16x16x32_bf16 v[70:73], v[186:189], v[226:229], v[70:73]
	v_mfma_f32_16x16x32_bf16 v[66:69], v[194:197], v[226:229], v[66:69]
	v_mfma_f32_16x16x32_bf16 v[118:121], v[190:193], v[206:209], v[118:121]
	v_mfma_f32_16x16x32_bf16 v[114:117], v[198:201], v[206:209], v[114:117]
	v_mfma_f32_16x16x32_bf16 v[102:105], v[190:193], v[214:217], v[102:105]
	v_mfma_f32_16x16x32_bf16 v[98:101], v[198:201], v[214:217], v[98:101]
	v_mfma_f32_16x16x32_bf16 v[86:89], v[190:193], v[222:225], v[86:89]
	v_mfma_f32_16x16x32_bf16 v[82:85], v[198:201], v[222:225], v[82:85]
	v_mfma_f32_16x16x32_bf16 v[70:73], v[190:193], v[230:233], v[70:73]
	v_mfma_f32_16x16x32_bf16 v[66:69], v[198:201], v[230:233], v[66:69]
	s_barrier
; #define PG8_STAGE(bufoff, gbase, voff) do { _Pragma("unroll") for (int _i = 0; _i < 2; ++_i) \
;         __builtin_amdgcn_global_load_lds((const unsigned*)((const char*)(gbase) + (voff)[_i]), (PG8_LAS unsigned*)(lds + (bufoff) + ldsw + _i * 8192), 16, 0, 0); } while (0)
; #define PG8_LDA(dst, b, h) do { _Pragma("unroll") for (int m = 0; m < 4; ++m) _Pragma("unroll") for (int k = 0; k < 2; ++k) dst[m][k] = *(const PG8_LAS bf16x8*)(lds + PG8_SA(b, h) + aoff + m * 2048 + k * 1024); } while (0)
; #define PG8_MMA(ai, bj, At, Bt) do { __builtin_amdgcn_s_setprio(1); _Pragma("unroll") for (int m = 0; m < 4; ++m) _Pragma("unroll") for (int n = 0; n < 2; ++n) _Pragma("unroll") for (int k = 0; k < 2; ++k) \
;         acc[ai][bj][m][n] = __builtin_amdgcn_mfma_f32_16x16x32_bf16(Bt[n][k], At[m][k], acc[ai][bj][m][n], 0, 0, 0); __builtin_amdgcn_s_setprio(0); } while (0)
; #define PG8_WAIT_V(n) asm volatile("s_waitcnt vmcnt(" #n ")" ::: "memory")
; #define PG8_WAIT_L(n) asm volatile("s_waitcnt lgkmcnt(" #n ")" ::: "memory")
; #define PG8_BAR __builtin_amdgcn_s_barrier()
; #define PG8_SCHED __builtin_amdgcn_sched_barrier(0)
; template <class Epi, class Sched, bool ALIGN_EPI = false, bool SP2 = false>
; __device__ __forceinline__ void gemm_phase(PG8_LAS unsigned char* lds, const Gemm g, const Sched& S, const Epi& E) {
;     ...
;         for (int t = 0; t < nt; t += 2) {
;             const bool last = (t == nt - 2);
;             const char* a1 = cA + (size_t)(t + 1) * kstep;
;             const char* a2 = last ? nA : cA + (size_t)(t + 2) * kstep; const char* b2 = last ? nB : cB + (size_t)(t + 2) * kstep;
;     ...
;             PG8_LDA(At, 1, 1); PG8_STAGE(PG8_SB(1, 0), b3, voffB); PG8_STAGE(PG8_SB(1, 1), b3 + hstep, voffB); PG8_STAGE(PG8_SA(1, 0), a3, voffA);
;             PG8_WAIT_V(8); PG8_WAIT_L(0); PG8_BAR; PG8_MMA(1, 0, At, B0); PG8_MMA(1, 1, At, B1); PG8_BAR; PG8_SCHED;
	s_add_i32 s52, s81, s54
	v_lshl_add_u64 v[166:167], v[166:167], 0, s[34:35]
	s_mov_b32 m0, s52
	ds_read_b128 v[202:205], v175 offset:49152
	ds_read_b128 v[206:209], v175 offset:50176
	ds_read_b128 v[210:213], v175 offset:51200
	ds_read_b128 v[214:217], v175 offset:52224
	ds_read_b128 v[218:221], v175 offset:53248
	ds_read_b128 v[222:225], v175 offset:54272
	ds_read_b128 v[226:229], v175 offset:55296
	ds_read_b128 v[230:233], v175 offset:56320
	global_load_lds_dwordx4 v[166:167], off
	s_add_i32 m0, s52, 0x2000
	s_add_u32 s50, s50, 0x40080
	v_lshl_add_u64 v[166:167], v[234:235], 0, s[34:35]
	s_addc_u32 s51, s51, 0
	s_add_i32 s52, s82, s54
	global_load_lds_dwordx4 v[166:167], off
	v_lshl_add_u64 v[166:167], s[50:51], 0, v[134:135]
	s_mov_b32 m0, s52
	s_nop 0
	global_load_lds_dwordx4 v[166:167], off
	v_lshl_add_u64 v[166:167], s[50:51], 0, v[136:137]
	s_add_i32 m0, s52, 0x2000
	s_nop 0
	global_load_lds_dwordx4 v[166:167], off
	v_lshl_add_u64 v[166:167], v[236:237], 0, s[34:35]
	s_mov_b32 m0, s59
	s_nop 0
	global_load_lds_dwordx4 v[166:167], off
	v_lshl_add_u64 v[166:167], v[238:239], 0, s[34:35]
	s_mov_b32 m0, s60
	s_nop 0
	global_load_lds_dwordx4 v[166:167], off
	s_waitcnt vmcnt(8)
	s_waitcnt lgkmcnt(0)
	s_barrier
	s_waitcnt lgkmcnt(0)
	v_mfma_f32_16x16x32_bf16 v[62:65], v[130:133], v[202:205], v[62:65]
	v_mfma_f32_16x16x32_bf16 v[58:61], v[178:181], v[202:205], v[58:61]
	v_mfma_f32_16x16x32_bf16 v[46:49], v[130:133], v[210:213], v[46:49]
	v_mfma_f32_16x16x32_bf16 v[42:45], v[178:181], v[210:213], v[42:45]
	v_mfma_f32_16x16x32_bf16 v[30:33], v[130:133], v[218:221], v[30:33]
	v_mfma_f32_16x16x32_bf16 v[26:29], v[178:181], v[218:221], v[26:29]
	v_mfma_f32_16x16x32_bf16 v[14:17], v[130:133], v[226:229], v[14:17]
	v_mfma_f32_16x16x32_bf16 v[10:13], v[178:181], v[226:229], v[10:13]
	v_mfma_f32_16x16x32_bf16 v[62:65], v[148:151], v[206:209], v[62:65]
	v_mfma_f32_16x16x32_bf16 v[58:61], v[182:185], v[206:209], v[58:61]
	v_mfma_f32_16x16x32_bf16 v[46:49], v[148:151], v[214:217], v[46:49]
	v_mfma_f32_16x16x32_bf16 v[42:45], v[182:185], v[214:217], v[42:45]
	v_mfma_f32_16x16x32_bf16 v[30:33], v[148:151], v[222:225], v[30:33]
	v_mfma_f32_16x16x32_bf16 v[26:29], v[182:185], v[222:225], v[26:29]
	v_mfma_f32_16x16x32_bf16 v[14:17], v[148:151], v[230:233], v[14:17]
	v_mfma_f32_16x16x32_bf16 v[10:13], v[182:185], v[230:233], v[10:13]
	v_mfma_f32_16x16x32_bf16 v[54:57], v[186:189], v[202:205], v[54:57]
	v_mfma_f32_16x16x32_bf16 v[50:53], v[194:197], v[202:205], v[50:53]
	v_mfma_f32_16x16x32_bf16 v[38:41], v[186:189], v[210:213], v[38:41]
	v_mfma_f32_16x16x32_bf16 v[34:37], v[194:197], v[210:213], v[34:37]
	v_mfma_f32_16x16x32_bf16 v[22:25], v[186:189], v[218:221], v[22:25]
	v_mfma_f32_16x16x32_bf16 v[18:21], v[194:197], v[218:221], v[18:21]
	v_mfma_f32_16x16x32_bf16 v[6:9], v[186:189], v[226:229], v[6:9]
	v_mfma_f32_16x16x32_bf16 v[2:5], v[194:197], v[226:229], v[2:5]
	v_mfma_f32_16x16x32_bf16 v[54:57], v[190:193], v[206:209], v[54:57]
	v_mfma_f32_16x16x32_bf16 v[50:53], v[198:201], v[206:209], v[50:53]
	v_mfma_f32_16x16x32_bf16 v[38:41], v[190:193], v[214:217], v[38:41]
	v_mfma_f32_16x16x32_bf16 v[34:37], v[198:201], v[214:217], v[34:37]
	v_mfma_f32_16x16x32_bf16 v[22:25], v[190:193], v[222:225], v[22:25]
	v_mfma_f32_16x16x32_bf16 v[18:21], v[198:201], v[222:225], v[18:21]
	v_mfma_f32_16x16x32_bf16 v[6:9], v[190:193], v[230:233], v[6:9]
	v_mfma_f32_16x16x32_bf16 v[2:5], v[198:201], v[230:233], v[2:5]
	s_barrier
	s_add_i32 s80, s80, 2
	s_add_u32 s10, s10, 0x100
	s_addc_u32 s11, s11, 0
	s_add_u32 s78, s78, 0x100
	s_addc_u32 s79, s79, 0
	s_cmp_gt_u32 s80, 13
	s_cbranch_scc0 .LBB0_1746
	s_and_b64 vcc, exec, s[36:37]
	s_cbranch_vccz .LBB0_1749
	s_barrier

; #define PG8_STAGE(bufoff, gbase, voff) do { _Pragma("unroll") for (int _i = 0; _i < 2; ++_i) \
;         __builtin_amdgcn_global_load_lds((const unsigned*)((const char*)(gbase) + (voff)[_i]), (PG8_LAS unsigned*)(lds + (bufoff) + ldsw + _i * 8192), 16, 0, 0); } while (0)
; #define PG8_LDA(dst, b, h) do { _Pragma("unroll") for (int m = 0; m < 4; ++m) _Pragma("unroll") for (int k = 0; k < 2; ++k) dst[m][k] = *(const PG8_LAS bf16x8*)(lds + PG8_SA(b, h) + aoff + m * 2048 + k * 1024); } while (0)
; #define PG8_LDB(dst, b, h) do { _Pragma("unroll") for (int n = 0; n < 2; ++n) _Pragma("unroll") for (int k = 0; k < 2; ++k) dst[n][k] = *(const PG8_LAS bf16x8*)(lds + PG8_SB(b, h) + boff + n * 2048 + k * 1024); } while (0)
; #define PG8_MMA(ai, bj, At, Bt) do { __builtin_amdgcn_s_setprio(1); _Pragma("unroll") for (int m = 0; m < 4; ++m) _Pragma("unroll") for (int n = 0; n < 2; ++n) _Pragma("unroll") for (int k = 0; k < 2; ++k) \
;         acc[ai][bj][m][n] = __builtin_amdgcn_mfma_f32_16x16x32_bf16(Bt[n][k], At[m][k], acc[ai][bj][m][n], 0, 0, 0); __builtin_amdgcn_s_setprio(0); } while (0)
; #define PG8_WAIT_V(n) asm volatile("s_waitcnt vmcnt(" #n ")" ::: "memory")
; #define PG8_BAR __builtin_amdgcn_s_barrier()
; template <class Epi, class Sched, bool ALIGN_EPI = false, bool SP2 = false>
; __device__ __forceinline__ void gemm_phase(PG8_LAS unsigned char* lds, const Gemm g, const Sched& S, const Epi& E) {
;     ...
;         for (int t = 0; t < nt; t += 2) {
;             const bool last = (t == nt - 2);
;             const char* a1 = cA + (size_t)(t + 1) * kstep;
;             const char* a2 = last ? nA : cA + (size_t)(t + 2) * kstep; const char* b2 = last ? nB : cB + (size_t)(t + 2) * kstep;
;             const char* a3 = a2 + kstep; const char* b3 = b2 + kstep;
;             if (last && has_next) S.a_ready(nxt);
;             if constexpr (SP2) {
;             PG8_LDB(B0, 0, 0); PG8_LDB(B1, 0, 1); PG8_SCHED; PG8_LDA(At, 0, 0); PG8_STAGE(PG8_SA(1, 1), a1 + hstep, voffA);
;             PG8_WAIT_V(8); PG8_WAIT_L(0); PG8_BAR; PG8_MMA(0, 0, At, B0); PG8_MMA(0, 1, At, B1); PG8_BAR; PG8_SCHED;
;             PG8_LDA(At, 0, 1); PG8_STAGE(PG8_SB(0, 0), b2, voffB); PG8_STAGE(PG8_SB(0, 1), b2 + hstep, voffB); PG8_STAGE(PG8_SA(0, 0), a2, voffA);
;             PG8_WAIT_V(8); PG8_WAIT_L(0); PG8_BAR; PG8_MMA(1, 0, At, B0); PG8_MMA(1, 1, At, B1); PG8_BAR; PG8_SCHED;
.LBB0_1898:
	ds_read_b128 v[170:173], v147
	ds_read_b128 v[174:177], v147 offset:1024
	ds_read_b128 v[178:181], v147 offset:2048
	ds_read_b128 v[182:185], v147 offset:3072
	ds_read_b128 v[186:189], v148
	ds_read_b128 v[190:193], v148 offset:1024
	ds_read_b128 v[194:197], v148 offset:2048
	ds_read_b128 v[198:201], v148 offset:3072
	s_add_u32 s44, s42, 0xfff50080
	s_addc_u32 s45, s43, -1
	s_cmp_eq_u32 s68, 40
	s_cselect_b32 s47, s9, s45
	s_cselect_b32 s46, s8, s44
	s_cselect_b32 s45, s41, s67
	s_cselect_b32 s44, s40, s66
	v_lshl_add_u64 v[142:143], s[42:43], 0, v[134:135]
	s_add_i32 m0, s48, 0xc000
	ds_read_b128 v[202:205], v149
	ds_read_b128 v[206:209], v149 offset:1024
	ds_read_b128 v[210:213], v149 offset:2048
	ds_read_b128 v[214:217], v149 offset:3072
	ds_read_b128 v[218:221], v149 offset:4096
	ds_read_b128 v[222:225], v149 offset:5120
	ds_read_b128 v[226:229], v149 offset:6144
	ds_read_b128 v[230:233], v149 offset:7168
	global_load_lds_dwordx4 v[142:143], off
	v_lshl_add_u64 v[142:143], s[42:43], 0, v[136:137]
	s_add_i32 m0, s48, 0xe000
	s_nop 0
	global_load_lds_dwordx4 v[142:143], off
	s_waitcnt vmcnt(8)
	s_waitcnt lgkmcnt(0)
	s_barrier
	s_waitcnt lgkmcnt(0)
	v_mfma_f32_16x16x32_bf16 v[126:129], v[170:173], v[202:205], v[126:129]
	v_mfma_f32_16x16x32_bf16 v[122:125], v[178:181], v[202:205], v[122:125]
	v_mfma_f32_16x16x32_bf16 v[118:121], v[170:173], v[210:213], v[118:121]
	v_mfma_f32_16x16x32_bf16 v[114:117], v[178:181], v[210:213], v[114:117]
	v_mfma_f32_16x16x32_bf16 v[94:97], v[170:173], v[218:221], v[94:97]
	v_mfma_f32_16x16x32_bf16 v[90:93], v[178:181], v[218:221], v[90:93]
	v_mfma_f32_16x16x32_bf16 v[86:89], v[170:173], v[226:229], v[86:89]
	v_mfma_f32_16x16x32_bf16 v[82:85], v[178:181], v[226:229], v[82:85]
	v_mfma_f32_16x16x32_bf16 v[126:129], v[174:177], v[206:209], v[126:129]
	v_mfma_f32_16x16x32_bf16 v[122:125], v[182:185], v[206:209], v[122:125]
	v_mfma_f32_16x16x32_bf16 v[118:121], v[174:177], v[214:217], v[118:121]
	v_mfma_f32_16x16x32_bf16 v[114:117], v[182:185], v[214:217], v[114:117]
	v_mfma_f32_16x16x32_bf16 v[94:97], v[174:177], v[222:225], v[94:97]
	v_mfma_f32_16x16x32_bf16 v[90:93], v[182:185], v[222:225], v[90:93]
	v_mfma_f32_16x16x32_bf16 v[86:89], v[174:177], v[230:233], v[86:89]
	v_mfma_f32_16x16x32_bf16 v[82:85], v[182:185], v[230:233], v[82:85]
	v_mfma_f32_16x16x32_bf16 v[110:113], v[186:189], v[202:205], v[110:113]
	v_mfma_f32_16x16x32_bf16 v[106:109], v[194:197], v[202:205], v[106:109]
	v_mfma_f32_16x16x32_bf16 v[102:105], v[186:189], v[210:213], v[102:105]
	v_mfma_f32_16x16x32_bf16 v[98:101], v[194:197], v[210:213], v[98:101]
	v_mfma_f32_16x16x32_bf16 v[78:81], v[186:189], v[218:221], v[78:81]
	v_mfma_f32_16x16x32_bf16 v[74:77], v[194:197], v[218:221], v[74:77]
	v_mfma_f32_16x16x32_bf16 v[70:73], v[186:189], v[226:229], v[70:73]
	v_mfma_f32_16x16x32_bf16 v[66:69], v[194:197], v[226:229], v[66:69]
	v_mfma_f32_16x16x32_bf16 v[110:113], v[190:193], v[206:209], v[110:113]
	v_mfma_f32_16x16x32_bf16 v[106:109], v[198:201], v[206:209], v[106:109]
	v_mfma_f32_16x16x32_bf16 v[102:105], v[190:193], v[214:217], v[102:105]
	v_mfma_f32_16x16x32_bf16 v[98:101], v[198:201], v[214:217], v[98:101]
	v_mfma_f32_16x16x32_bf16 v[78:81], v[190:193], v[222:225], v[78:81]
	v_mfma_f32_16x16x32_bf16 v[74:77], v[198:201], v[222:225], v[74:77]
	v_mfma_f32_16x16x32_bf16 v[70:73], v[190:193], v[230:233], v[70:73]
	v_mfma_f32_16x16x32_bf16 v[66:69], v[198:201], v[230:233], v[66:69]
	s_barrier
	s_add_i32 s69, s56, s19
	v_lshl_add_u64 v[142:143], s[44:45], 0, v[130:131]
	s_mov_b32 m0, s69
	ds_read_b128 v[202:205], v149 offset:16384
	ds_read_b128 v[206:209], v149 offset:17408
	ds_read_b128 v[210:213], v149 offset:18432
	ds_read_b128 v[214:217], v149 offset:19456
	ds_read_b128 v[218:221], v149 offset:20480
	ds_read_b128 v[222:225], v149 offset:21504
	ds_read_b128 v[226:229], v149 offset:22528
	ds_read_b128 v[230:233], v149 offset:23552
	global_load_lds_dwordx4 v[142:143], off
	s_add_i32 m0, s69, 0x2000
	s_add_u32 s70, s44, 0xb0000
	v_lshl_add_u64 v[150:151], s[44:45], 0, v[132:133]
	s_addc_u32 s71, s45, 0
	s_add_i32 s69, s57, s19
	global_load_lds_dwordx4 v[150:151], off
	v_lshl_add_u64 v[166:167], s[70:71], 0, v[130:131]
	s_mov_b32 m0, s69
	v_lshl_add_u64 v[234:235], s[46:47], 0, v[132:133]
	global_load_lds_dwordx4 v[166:167], off
	v_lshl_add_u64 v[166:167], s[70:71], 0, v[132:133]
	s_add_i32 m0, s69, 0x2000
	s_nop 0
	global_load_lds_dwordx4 v[166:167], off
	v_lshl_add_u64 v[166:167], s[46:47], 0, v[130:131]
	s_mov_b32 m0, s48
	s_nop 0
	global_load_lds_dwordx4 v[166:167], off
	s_mov_b32 m0, s49
	s_nop 0
	global_load_lds_dwordx4 v[234:235], off
	s_waitcnt vmcnt(8)
	s_waitcnt lgkmcnt(0)
	s_barrier
; #define PG8_STAGE(bufoff, gbase, voff) do { _Pragma("unroll") for (int _i = 0; _i < 2; ++_i) \
;         __builtin_amdgcn_global_load_lds((const unsigned*)((const char*)(gbase) + (voff)[_i]), (PG8_LAS unsigned*)(lds + (bufoff) + ldsw + _i * 8192), 16, 0, 0); } while (0)
; #define PG8_LDA(dst, b, h) do { _Pragma("unroll") for (int m = 0; m < 4; ++m) _Pragma("unroll") for (int k = 0; k < 2; ++k) dst[m][k] = *(const PG8_LAS bf16x8*)(lds + PG8_SA(b, h) + aoff + m * 2048 + k * 1024); } while (0)
; #define PG8_LDB(dst, b, h) do { _Pragma("unroll") for (int n = 0; n < 2; ++n) _Pragma("unroll") for (int k = 0; k < 2; ++k) dst[n][k] = *(const PG8_LAS bf16x8*)(lds + PG8_SB(b, h) + boff + n * 2048 + k * 1024); } while (0)
; #define PG8_MMA(ai, bj, At, Bt) do { __builtin_amdgcn_s_setprio(1); _Pragma("unroll") for (int m = 0; m < 4; ++m) _Pragma("unroll") for (int n = 0; n < 2; ++n) _Pragma("unroll") for (int k = 0; k < 2; ++k) \
;         acc[ai][bj][m][n] = __builtin_amdgcn_mfma_f32_16x16x32_bf16(Bt[n][k], At[m][k], acc[ai][bj][m][n], 0, 0, 0); __builtin_amdgcn_s_setprio(0); } while (0)
; #define PG8_WAIT_V(n) asm volatile("s_waitcnt vmcnt(" #n ")" ::: "memory")
; #define PG8_WAIT_L(n) asm volatile("s_waitcnt lgkmcnt(" #n ")" ::: "memory")
; #define PG8_BAR __builtin_amdgcn_s_barrier()
; #define PG8_SCHED __builtin_amdgcn_sched_barrier(0)
; template <class Epi, class Sched, bool ALIGN_EPI = false, bool SP2 = false>
; __device__ __forceinline__ void gemm_phase(PG8_LAS unsigned char* lds, const Gemm g, const Sched& S, const Epi& E) {
;     ...
;             PG8_WAIT_V(8); PG8_WAIT_L(0); PG8_BAR; PG8_MMA(1, 0, At, B0); PG8_MMA(1, 1, At, B1); PG8_BAR; PG8_SCHED;
;             PG8_LDB(B0, 1, 0); PG8_LDB(B1, 1, 1); PG8_SCHED; PG8_LDA(At, 1, 0); PG8_STAGE(PG8_SA(0, 1), a2 + hstep, voffA);
;             PG8_WAIT_V(8); PG8_WAIT_L(0); PG8_BAR; PG8_MMA(0, 0, At, B0); PG8_MMA(0, 1, At, B1); PG8_BAR; PG8_SCHED;
	s_waitcnt lgkmcnt(0)
	v_mfma_f32_16x16x32_bf16 v[62:65], v[170:173], v[202:205], v[62:65]
	v_mfma_f32_16x16x32_bf16 v[58:61], v[178:181], v[202:205], v[58:61]
	v_mfma_f32_16x16x32_bf16 v[54:57], v[170:173], v[210:213], v[54:57]
	v_mfma_f32_16x16x32_bf16 v[50:53], v[178:181], v[210:213], v[50:53]
	v_mfma_f32_16x16x32_bf16 v[30:33], v[170:173], v[218:221], v[30:33]
	v_mfma_f32_16x16x32_bf16 v[26:29], v[178:181], v[218:221], v[26:29]
	v_mfma_f32_16x16x32_bf16 v[22:25], v[170:173], v[226:229], v[22:25]
	v_mfma_f32_16x16x32_bf16 v[14:17], v[178:181], v[226:229], v[14:17]
	v_mfma_f32_16x16x32_bf16 v[62:65], v[174:177], v[206:209], v[62:65]
	v_mfma_f32_16x16x32_bf16 v[58:61], v[182:185], v[206:209], v[58:61]
	v_mfma_f32_16x16x32_bf16 v[54:57], v[174:177], v[214:217], v[54:57]
	v_mfma_f32_16x16x32_bf16 v[50:53], v[182:185], v[214:217], v[50:53]
	v_mfma_f32_16x16x32_bf16 v[30:33], v[174:177], v[222:225], v[30:33]
	v_mfma_f32_16x16x32_bf16 v[26:29], v[182:185], v[222:225], v[26:29]
	v_mfma_f32_16x16x32_bf16 v[22:25], v[174:177], v[230:233], v[22:25]
	v_mfma_f32_16x16x32_bf16 v[14:17], v[182:185], v[230:233], v[14:17]
	v_mfma_f32_16x16x32_bf16 v[46:49], v[186:189], v[202:205], v[46:49]
	v_mfma_f32_16x16x32_bf16 v[42:45], v[194:197], v[202:205], v[42:45]
	v_mfma_f32_16x16x32_bf16 v[38:41], v[186:189], v[210:213], v[38:41]
	v_mfma_f32_16x16x32_bf16 v[34:37], v[194:197], v[210:213], v[34:37]
	v_mfma_f32_16x16x32_bf16 v[18:21], v[186:189], v[218:221], v[18:21]
	v_mfma_f32_16x16x32_bf16 v[10:13], v[194:197], v[218:221], v[10:13]
	v_mfma_f32_16x16x32_bf16 v[6:9], v[186:189], v[226:229], v[6:9]
	v_mfma_f32_16x16x32_bf16 v[2:5], v[194:197], v[226:229], v[2:5]
	v_mfma_f32_16x16x32_bf16 v[46:49], v[190:193], v[206:209], v[46:49]
	v_mfma_f32_16x16x32_bf16 v[42:45], v[198:201], v[206:209], v[42:45]
	v_mfma_f32_16x16x32_bf16 v[38:41], v[190:193], v[214:217], v[38:41]
	v_mfma_f32_16x16x32_bf16 v[34:37], v[198:201], v[214:217], v[34:37]
	v_mfma_f32_16x16x32_bf16 v[18:21], v[190:193], v[222:225], v[18:21]
	v_mfma_f32_16x16x32_bf16 v[10:13], v[198:201], v[222:225], v[10:13]
	v_mfma_f32_16x16x32_bf16 v[6:9], v[190:193], v[230:233], v[6:9]
	v_mfma_f32_16x16x32_bf16 v[2:5], v[198:201], v[230:233], v[2:5]
	s_barrier
	s_add_i32 s69, 0, 0x18000
	v_add_u32_e32 v152, s69, v145
	s_add_i32 s70, 0, 0x1c000
	ds_read_b128 v[170:173], v152
	ds_read_b128 v[174:177], v152 offset:1024
	ds_read_b128 v[178:181], v152 offset:2048
	ds_read_b128 v[182:185], v152 offset:3072
	v_add_u32_e32 v152, s70, v145
	ds_read_b128 v[186:189], v152
	ds_read_b128 v[190:193], v152 offset:1024
	ds_read_b128 v[194:197], v152 offset:2048
	ds_read_b128 v[198:201], v152 offset:3072
	s_add_u32 s46, s46, 0xb0000
	s_addc_u32 s47, s47, 0
	s_mov_b32 m0, s50
	v_lshl_add_u64 v[236:237], s[46:47], 0, v[130:131]
	ds_read_b128 v[202:205], v149 offset:32768
	ds_read_b128 v[206:209], v149 offset:33792
	ds_read_b128 v[210:213], v149 offset:34816
	ds_read_b128 v[214:217], v149 offset:35840
	ds_read_b128 v[218:221], v149 offset:36864
	ds_read_b128 v[222:225], v149 offset:37888
	ds_read_b128 v[226:229], v149 offset:38912
	ds_read_b128 v[230:233], v149 offset:39936
	global_load_lds_dwordx4 v[236:237], off
	v_lshl_add_u64 v[236:237], s[46:47], 0, v[132:133]
	s_mov_b32 m0, s51
	s_nop 0
	global_load_lds_dwordx4 v[236:237], off
	s_waitcnt vmcnt(8)
	s_waitcnt lgkmcnt(0)
	s_barrier
	s_waitcnt lgkmcnt(0)
	v_mfma_f32_16x16x32_bf16 v[126:129], v[170:173], v[202:205], v[126:129]
	v_mfma_f32_16x16x32_bf16 v[122:125], v[178:181], v[202:205], v[122:125]
	v_mfma_f32_16x16x32_bf16 v[118:121], v[170:173], v[210:213], v[118:121]
	v_mfma_f32_16x16x32_bf16 v[114:117], v[178:181], v[210:213], v[114:117]
	v_mfma_f32_16x16x32_bf16 v[94:97], v[170:173], v[218:221], v[94:97]
	v_mfma_f32_16x16x32_bf16 v[90:93], v[178:181], v[218:221], v[90:93]
	v_mfma_f32_16x16x32_bf16 v[86:89], v[170:173], v[226:229], v[86:89]
	v_mfma_f32_16x16x32_bf16 v[82:85], v[178:181], v[226:229], v[82:85]
	v_mfma_f32_16x16x32_bf16 v[126:129], v[174:177], v[206:209], v[126:129]
	v_mfma_f32_16x16x32_bf16 v[122:125], v[182:185], v[206:209], v[122:125]
	v_mfma_f32_16x16x32_bf16 v[118:121], v[174:177], v[214:217], v[118:121]
	v_mfma_f32_16x16x32_bf16 v[114:117], v[182:185], v[214:217], v[114:117]
	v_mfma_f32_16x16x32_bf16 v[94:97], v[174:177], v[222:225], v[94:97]
	v_mfma_f32_16x16x32_bf16 v[90:93], v[182:185], v[222:225], v[90:93]
	v_mfma_f32_16x16x32_bf16 v[86:89], v[174:177], v[230:233], v[86:89]
	v_mfma_f32_16x16x32_bf16 v[82:85], v[182:185], v[230:233], v[82:85]
	v_mfma_f32_16x16x32_bf16 v[110:113], v[186:189], v[202:205], v[110:113]
	v_mfma_f32_16x16x32_bf16 v[106:109], v[194:197], v[202:205], v[106:109]
	v_mfma_f32_16x16x32_bf16 v[102:105], v[186:189], v[210:213], v[102:105]
	v_mfma_f32_16x16x32_bf16 v[98:101], v[194:197], v[210:213], v[98:101]
	v_mfma_f32_16x16x32_bf16 v[78:81], v[186:189], v[218:221], v[78:81]
	v_mfma_f32_16x16x32_bf16 v[74:77], v[194:197], v[218:221], v[74:77]
	v_mfma_f32_16x16x32_bf16 v[70:73], v[186:189], v[226:229], v[70:73]
	v_mfma_f32_16x16x32_bf16 v[66:69], v[194:197], v[226:229], v[66:69]
	v_mfma_f32_16x16x32_bf16 v[110:113], v[190:193], v[206:209], v[110:113]
	v_mfma_f32_16x16x32_bf16 v[106:109], v[198:201], v[206:209], v[106:109]
	v_mfma_f32_16x16x32_bf16 v[102:105], v[190:193], v[214:217], v[102:105]
	v_mfma_f32_16x16x32_bf16 v[98:101], v[198:201], v[214:217], v[98:101]
	v_mfma_f32_16x16x32_bf16 v[78:81], v[190:193], v[222:225], v[78:81]
	v_mfma_f32_16x16x32_bf16 v[74:77], v[198:201], v[222:225], v[74:77]
	v_mfma_f32_16x16x32_bf16 v[70:73], v[190:193], v[230:233], v[70:73]
	v_mfma_f32_16x16x32_bf16 v[66:69], v[198:201], v[230:233], v[66:69]
	s_barrier
; #define PG8_STAGE(bufoff, gbase, voff) do { _Pragma("unroll") for (int _i = 0; _i < 2; ++_i) \
;         __builtin_amdgcn_global_load_lds((const unsigned*)((const char*)(gbase) + (voff)[_i]), (PG8_LAS unsigned*)(lds + (bufoff) + ldsw + _i * 8192), 16, 0, 0); } while (0)
; #define PG8_LDA(dst, b, h) do { _Pragma("unroll") for (int m = 0; m < 4; ++m) _Pragma("unroll") for (int k = 0; k < 2; ++k) dst[m][k] = *(const PG8_LAS bf16x8*)(lds + PG8_SA(b, h) + aoff + m * 2048 + k * 1024); } while (0)
; #define PG8_MMA(ai, bj, At, Bt) do { __builtin_amdgcn_s_setprio(1); _Pragma("unroll") for (int m = 0; m < 4; ++m) _Pragma("unroll") for (int n = 0; n < 2; ++n) _Pragma("unroll") for (int k = 0; k < 2; ++k) \
;         acc[ai][bj][m][n] = __builtin_amdgcn_mfma_f32_16x16x32_bf16(Bt[n][k], At[m][k], acc[ai][bj][m][n], 0, 0, 0); __builtin_amdgcn_s_setprio(0); } while (0)
; #define PG8_WAIT_V(n) asm volatile("s_waitcnt vmcnt(" #n ")" ::: "memory")
; #define PG8_WAIT_L(n) asm volatile("s_waitcnt lgkmcnt(" #n ")" ::: "memory")
; #define PG8_BAR __builtin_amdgcn_s_barrier()
; #define PG8_SCHED __builtin_amdgcn_sched_barrier(0)
; template <class Epi, class Sched, bool ALIGN_EPI = false, bool SP2 = false>
; __device__ __forceinline__ void gemm_phase(PG8_LAS unsigned char* lds, const Gemm g, const Sched& S, const Epi& E) {
;     ...
;         for (int t = 0; t < nt; t += 2) {
;             const bool last = (t == nt - 2);
;             const char* a1 = cA + (size_t)(t + 1) * kstep;
;             const char* a2 = last ? nA : cA + (size_t)(t + 2) * kstep; const char* b2 = last ? nB : cB + (size_t)(t + 2) * kstep;
;     ...
;             PG8_LDA(At, 1, 1); PG8_STAGE(PG8_SB(1, 0), b3, voffB); PG8_STAGE(PG8_SB(1, 1), b3 + hstep, voffB); PG8_STAGE(PG8_SA(1, 0), a3, voffA);
;             PG8_WAIT_V(8); PG8_WAIT_L(0); PG8_BAR; PG8_MMA(1, 0, At, B0); PG8_MMA(1, 1, At, B1); PG8_BAR; PG8_SCHED;
	s_add_i32 s46, s69, s19
	v_lshl_add_u64 v[142:143], v[142:143], 0, s[16:17]
	s_mov_b32 m0, s46
	ds_read_b128 v[202:205], v149 offset:49152
	ds_read_b128 v[206:209], v149 offset:50176
	ds_read_b128 v[210:213], v149 offset:51200
	ds_read_b128 v[214:217], v149 offset:52224
	ds_read_b128 v[218:221], v149 offset:53248
	ds_read_b128 v[222:225], v149 offset:54272
	ds_read_b128 v[226:229], v149 offset:55296
	ds_read_b128 v[230:233], v149 offset:56320
	global_load_lds_dwordx4 v[142:143], off
	s_add_i32 m0, s46, 0x2000
	s_add_u32 s44, s44, 0xb0080
	v_lshl_add_u64 v[142:143], v[150:151], 0, s[16:17]
	s_addc_u32 s45, s45, 0
	s_add_i32 s46, s70, s19
	global_load_lds_dwordx4 v[142:143], off
	v_lshl_add_u64 v[142:143], s[44:45], 0, v[130:131]
	s_mov_b32 m0, s46
	s_nop 0
	global_load_lds_dwordx4 v[142:143], off
	v_lshl_add_u64 v[142:143], s[44:45], 0, v[132:133]
	s_add_i32 m0, s46, 0x2000
	s_nop 0
	global_load_lds_dwordx4 v[142:143], off
	v_lshl_add_u64 v[142:143], v[166:167], 0, s[16:17]
	s_mov_b32 m0, s53
	s_nop 0
	global_load_lds_dwordx4 v[142:143], off
	v_lshl_add_u64 v[142:143], v[234:235], 0, s[16:17]
	s_mov_b32 m0, s54
	s_nop 0
	global_load_lds_dwordx4 v[142:143], off
	s_waitcnt vmcnt(8)
	s_waitcnt lgkmcnt(0)
	s_barrier
	s_waitcnt lgkmcnt(0)
	v_mfma_f32_16x16x32_bf16 v[62:65], v[170:173], v[202:205], v[62:65]
	v_mfma_f32_16x16x32_bf16 v[58:61], v[178:181], v[202:205], v[58:61]
	v_mfma_f32_16x16x32_bf16 v[54:57], v[170:173], v[210:213], v[54:57]
	v_mfma_f32_16x16x32_bf16 v[50:53], v[178:181], v[210:213], v[50:53]
	v_mfma_f32_16x16x32_bf16 v[30:33], v[170:173], v[218:221], v[30:33]
	v_mfma_f32_16x16x32_bf16 v[26:29], v[178:181], v[218:221], v[26:29]
	v_mfma_f32_16x16x32_bf16 v[22:25], v[170:173], v[226:229], v[22:25]
	v_mfma_f32_16x16x32_bf16 v[14:17], v[178:181], v[226:229], v[14:17]
	v_mfma_f32_16x16x32_bf16 v[62:65], v[174:177], v[206:209], v[62:65]
	v_mfma_f32_16x16x32_bf16 v[58:61], v[182:185], v[206:209], v[58:61]
	v_mfma_f32_16x16x32_bf16 v[54:57], v[174:177], v[214:217], v[54:57]
	v_mfma_f32_16x16x32_bf16 v[50:53], v[182:185], v[214:217], v[50:53]
	v_mfma_f32_16x16x32_bf16 v[30:33], v[174:177], v[222:225], v[30:33]
	v_mfma_f32_16x16x32_bf16 v[26:29], v[182:185], v[222:225], v[26:29]
	v_mfma_f32_16x16x32_bf16 v[22:25], v[174:177], v[230:233], v[22:25]
	v_mfma_f32_16x16x32_bf16 v[14:17], v[182:185], v[230:233], v[14:17]
	v_mfma_f32_16x16x32_bf16 v[46:49], v[186:189], v[202:205], v[46:49]
	v_mfma_f32_16x16x32_bf16 v[42:45], v[194:197], v[202:205], v[42:45]
	v_mfma_f32_16x16x32_bf16 v[38:41], v[186:189], v[210:213], v[38:41]
	v_mfma_f32_16x16x32_bf16 v[34:37], v[194:197], v[210:213], v[34:37]
	v_mfma_f32_16x16x32_bf16 v[18:21], v[186:189], v[218:221], v[18:21]
	v_mfma_f32_16x16x32_bf16 v[10:13], v[194:197], v[218:221], v[10:13]
	v_mfma_f32_16x16x32_bf16 v[6:9], v[186:189], v[226:229], v[6:9]
	v_mfma_f32_16x16x32_bf16 v[2:5], v[194:197], v[226:229], v[2:5]
	v_mfma_f32_16x16x32_bf16 v[46:49], v[190:193], v[206:209], v[46:49]
	v_mfma_f32_16x16x32_bf16 v[42:45], v[198:201], v[206:209], v[42:45]
	v_mfma_f32_16x16x32_bf16 v[38:41], v[190:193], v[214:217], v[38:41]
	v_mfma_f32_16x16x32_bf16 v[34:37], v[198:201], v[214:217], v[34:37]
	v_mfma_f32_16x16x32_bf16 v[18:21], v[190:193], v[222:225], v[18:21]
	v_mfma_f32_16x16x32_bf16 v[10:13], v[198:201], v[222:225], v[10:13]
	v_mfma_f32_16x16x32_bf16 v[6:9], v[190:193], v[230:233], v[6:9]
	v_mfma_f32_16x16x32_bf16 v[2:5], v[198:201], v[230:233], v[2:5]
	s_barrier
	s_add_i32 s68, s68, 2
	s_add_u32 s42, s42, 0x100
	s_addc_u32 s43, s43, 0
	s_add_u32 s66, s66, 0x100
	s_addc_u32 s67, s67, 0
	s_cmp_gt_u32 s68, 41
	s_cbranch_scc0 .LBB0_1898
	s_and_b64 vcc, exec, s[30:31]
	s_cbranch_vccz .LBB0_1901
	s_barrier

; #define PG8_STAGE(bufoff, gbase, voff) do { _Pragma("unroll") for (int _i = 0; _i < 2; ++_i) \
;         __builtin_amdgcn_global_load_lds((const unsigned*)((const char*)(gbase) + (voff)[_i]), (PG8_LAS unsigned*)(lds + (bufoff) + ldsw + _i * 8192), 16, 0, 0); } while (0)
; #define PG8_LDA(dst, b, h) do { _Pragma("unroll") for (int m = 0; m < 4; ++m) _Pragma("unroll") for (int k = 0; k < 2; ++k) dst[m][k] = *(const PG8_LAS bf16x8*)(lds + PG8_SA(b, h) + aoff + m * 2048 + k * 1024); } while (0)
; #define PG8_LDB(dst, b, h) do { _Pragma("unroll") for (int n = 0; n < 2; ++n) _Pragma("unroll") for (int k = 0; k < 2; ++k) dst[n][k] = *(const PG8_LAS bf16x8*)(lds + PG8_SB(b, h) + boff + n * 2048 + k * 1024); } while (0)
; #define PG8_MMA(ai, bj, At, Bt) do { __builtin_amdgcn_s_setprio(1); _Pragma("unroll") for (int m = 0; m < 4; ++m) _Pragma("unroll") for (int n = 0; n < 2; ++n) _Pragma("unroll") for (int k = 0; k < 2; ++k) \
;         acc[ai][bj][m][n] = __builtin_amdgcn_mfma_f32_16x16x32_bf16(Bt[n][k], At[m][k], acc[ai][bj][m][n], 0, 0, 0); __builtin_amdgcn_s_setprio(0); } while (0)
; #define PG8_WAIT_V(n) asm volatile("s_waitcnt vmcnt(" #n ")" ::: "memory")
; #define PG8_BAR __builtin_amdgcn_s_barrier()
; template <class Epi, class Sched, bool ALIGN_EPI = false, bool SP2 = false>
; __device__ __forceinline__ void gemm_phase(PG8_LAS unsigned char* lds, const Gemm g, const Sched& S, const Epi& E) {
;     ...
;         for (int t = 0; t < nt; t += 2) {
;             const bool last = (t == nt - 2);
;             const char* a1 = cA + (size_t)(t + 1) * kstep;
;             const char* a2 = last ? nA : cA + (size_t)(t + 2) * kstep; const char* b2 = last ? nB : cB + (size_t)(t + 2) * kstep;
;             const char* a3 = a2 + kstep; const char* b3 = b2 + kstep;
;             if (last && has_next) S.a_ready(nxt);
;             if constexpr (SP2) {
;             PG8_LDB(B0, 0, 0); PG8_LDB(B1, 0, 1); PG8_SCHED; PG8_LDA(At, 0, 0); PG8_STAGE(PG8_SA(1, 1), a1 + hstep, voffA);
;             PG8_WAIT_V(8); PG8_WAIT_L(0); PG8_BAR; PG8_MMA(0, 0, At, B0); PG8_MMA(0, 1, At, B1); PG8_BAR; PG8_SCHED;
;             PG8_LDA(At, 0, 1); PG8_STAGE(PG8_SB(0, 0), b2, voffB); PG8_STAGE(PG8_SB(0, 1), b2 + hstep, voffB); PG8_STAGE(PG8_SA(0, 0), a2, voffA);
;             PG8_WAIT_V(8); PG8_WAIT_L(0); PG8_BAR; PG8_MMA(1, 0, At, B0); PG8_MMA(1, 1, At, B1); PG8_BAR; PG8_SCHED;
.LBB0_1928:
	ds_read_b128 v[150:153], v1
	ds_read_b128 v[154:157], v1 offset:1024
	ds_read_b128 v[158:161], v1 offset:2048
	ds_read_b128 v[162:165], v1 offset:3072
	ds_read_b128 v[166:169], v147
	ds_read_b128 v[170:173], v147 offset:1024
	ds_read_b128 v[174:177], v147 offset:2048
	ds_read_b128 v[178:181], v147 offset:3072
	s_add_u32 s44, s42, 0xfff50080
	s_addc_u32 s45, s43, -1
	s_cmp_eq_u32 s68, 40
	s_cselect_b32 s47, s9, s45
	s_cselect_b32 s46, s8, s44
	s_cselect_b32 s45, s41, s67
	s_cselect_b32 s44, s40, s66
	v_lshl_add_u64 v[142:143], s[42:43], 0, v[134:135]
	s_add_i32 m0, s48, 0xc000
	ds_read_b128 v[182:185], v148
	ds_read_b128 v[186:189], v148 offset:1024
	ds_read_b128 v[190:193], v148 offset:2048
	ds_read_b128 v[194:197], v148 offset:3072
	ds_read_b128 v[198:201], v148 offset:4096
	ds_read_b128 v[202:205], v148 offset:5120
	ds_read_b128 v[206:209], v148 offset:6144
	ds_read_b128 v[210:213], v148 offset:7168
	global_load_lds_dwordx4 v[142:143], off
	v_lshl_add_u64 v[142:143], s[42:43], 0, v[136:137]
	s_add_i32 m0, s48, 0xe000
	s_nop 0
	global_load_lds_dwordx4 v[142:143], off
	s_waitcnt vmcnt(8)
	s_waitcnt lgkmcnt(0)
	s_barrier
	s_waitcnt lgkmcnt(0)
	v_mfma_f32_16x16x32_bf16 v[126:129], v[150:153], v[182:185], v[126:129]
	v_mfma_f32_16x16x32_bf16 v[122:125], v[158:161], v[182:185], v[122:125]
	v_mfma_f32_16x16x32_bf16 v[118:121], v[150:153], v[190:193], v[118:121]
	v_mfma_f32_16x16x32_bf16 v[114:117], v[158:161], v[190:193], v[114:117]
	v_mfma_f32_16x16x32_bf16 v[94:97], v[150:153], v[198:201], v[94:97]
	v_mfma_f32_16x16x32_bf16 v[90:93], v[158:161], v[198:201], v[90:93]
	v_mfma_f32_16x16x32_bf16 v[86:89], v[150:153], v[206:209], v[86:89]
	v_mfma_f32_16x16x32_bf16 v[82:85], v[158:161], v[206:209], v[82:85]
	v_mfma_f32_16x16x32_bf16 v[126:129], v[154:157], v[186:189], v[126:129]
	v_mfma_f32_16x16x32_bf16 v[122:125], v[162:165], v[186:189], v[122:125]
	v_mfma_f32_16x16x32_bf16 v[118:121], v[154:157], v[194:197], v[118:121]
	v_mfma_f32_16x16x32_bf16 v[114:117], v[162:165], v[194:197], v[114:117]
	v_mfma_f32_16x16x32_bf16 v[94:97], v[154:157], v[202:205], v[94:97]
	v_mfma_f32_16x16x32_bf16 v[90:93], v[162:165], v[202:205], v[90:93]
	v_mfma_f32_16x16x32_bf16 v[86:89], v[154:157], v[210:213], v[86:89]
	v_mfma_f32_16x16x32_bf16 v[82:85], v[162:165], v[210:213], v[82:85]
	v_mfma_f32_16x16x32_bf16 v[110:113], v[166:169], v[182:185], v[110:113]
	v_mfma_f32_16x16x32_bf16 v[106:109], v[174:177], v[182:185], v[106:109]
	v_mfma_f32_16x16x32_bf16 v[102:105], v[166:169], v[190:193], v[102:105]
	v_mfma_f32_16x16x32_bf16 v[98:101], v[174:177], v[190:193], v[98:101]
	v_mfma_f32_16x16x32_bf16 v[78:81], v[166:169], v[198:201], v[78:81]
	v_mfma_f32_16x16x32_bf16 v[74:77], v[174:177], v[198:201], v[74:77]
	v_mfma_f32_16x16x32_bf16 v[70:73], v[166:169], v[206:209], v[70:73]
	v_mfma_f32_16x16x32_bf16 v[66:69], v[174:177], v[206:209], v[66:69]
	v_mfma_f32_16x16x32_bf16 v[110:113], v[170:173], v[186:189], v[110:113]
	v_mfma_f32_16x16x32_bf16 v[106:109], v[178:181], v[186:189], v[106:109]
	v_mfma_f32_16x16x32_bf16 v[102:105], v[170:173], v[194:197], v[102:105]
	v_mfma_f32_16x16x32_bf16 v[98:101], v[178:181], v[194:197], v[98:101]
	v_mfma_f32_16x16x32_bf16 v[78:81], v[170:173], v[202:205], v[78:81]
	v_mfma_f32_16x16x32_bf16 v[74:77], v[178:181], v[202:205], v[74:77]
	v_mfma_f32_16x16x32_bf16 v[70:73], v[170:173], v[210:213], v[70:73]
	v_mfma_f32_16x16x32_bf16 v[66:69], v[178:181], v[210:213], v[66:69]
	s_barrier
	s_add_i32 s69, s56, s19
	v_lshl_add_u64 v[142:143], s[44:45], 0, v[130:131]
	s_mov_b32 m0, s69
	ds_read_b128 v[182:185], v148 offset:16384
	ds_read_b128 v[186:189], v148 offset:17408
	ds_read_b128 v[190:193], v148 offset:18432
	ds_read_b128 v[194:197], v148 offset:19456
	ds_read_b128 v[198:201], v148 offset:20480
	ds_read_b128 v[202:205], v148 offset:21504
	ds_read_b128 v[206:209], v148 offset:22528
	ds_read_b128 v[210:213], v148 offset:23552
	global_load_lds_dwordx4 v[142:143], off
	s_add_i32 m0, s69, 0x2000
	s_add_u32 s70, s44, 0xb0000
	v_lshl_add_u64 v[214:215], s[44:45], 0, v[132:133]
	s_addc_u32 s71, s45, 0
	s_add_i32 s69, s57, s19
	global_load_lds_dwordx4 v[214:215], off
	v_lshl_add_u64 v[216:217], s[70:71], 0, v[130:131]
	s_mov_b32 m0, s69
	v_lshl_add_u64 v[218:219], s[46:47], 0, v[132:133]
	global_load_lds_dwordx4 v[216:217], off
	v_lshl_add_u64 v[216:217], s[70:71], 0, v[132:133]
	s_add_i32 m0, s69, 0x2000
	s_nop 0
	global_load_lds_dwordx4 v[216:217], off
	v_lshl_add_u64 v[216:217], s[46:47], 0, v[130:131]
	s_mov_b32 m0, s48
	s_nop 0
	global_load_lds_dwordx4 v[216:217], off
	s_mov_b32 m0, s49
	s_nop 0
	global_load_lds_dwordx4 v[218:219], off
	s_waitcnt vmcnt(8)
	s_waitcnt lgkmcnt(0)
	s_barrier
; #define PG8_STAGE(bufoff, gbase, voff) do { _Pragma("unroll") for (int _i = 0; _i < 2; ++_i) \
;         __builtin_amdgcn_global_load_lds((const unsigned*)((const char*)(gbase) + (voff)[_i]), (PG8_LAS unsigned*)(lds + (bufoff) + ldsw + _i * 8192), 16, 0, 0); } while (0)
; #define PG8_LDA(dst, b, h) do { _Pragma("unroll") for (int m = 0; m < 4; ++m) _Pragma("unroll") for (int k = 0; k < 2; ++k) dst[m][k] = *(const PG8_LAS bf16x8*)(lds + PG8_SA(b, h) + aoff + m * 2048 + k * 1024); } while (0)
; #define PG8_LDB(dst, b, h) do { _Pragma("unroll") for (int n = 0; n < 2; ++n) _Pragma("unroll") for (int k = 0; k < 2; ++k) dst[n][k] = *(const PG8_LAS bf16x8*)(lds + PG8_SB(b, h) + boff + n * 2048 + k * 1024); } while (0)
; #define PG8_MMA(ai, bj, At, Bt) do { __builtin_amdgcn_s_setprio(1); _Pragma("unroll") for (int m = 0; m < 4; ++m) _Pragma("unroll") for (int n = 0; n < 2; ++n) _Pragma("unroll") for (int k = 0; k < 2; ++k) \
;         acc[ai][bj][m][n] = __builtin_amdgcn_mfma_f32_16x16x32_bf16(Bt[n][k], At[m][k], acc[ai][bj][m][n], 0, 0, 0); __builtin_amdgcn_s_setprio(0); } while (0)
; #define PG8_WAIT_V(n) asm volatile("s_waitcnt vmcnt(" #n ")" ::: "memory")
; #define PG8_WAIT_L(n) asm volatile("s_waitcnt lgkmcnt(" #n ")" ::: "memory")
; #define PG8_BAR __builtin_amdgcn_s_barrier()
; #define PG8_SCHED __builtin_amdgcn_sched_barrier(0)
; template <class Epi, class Sched, bool ALIGN_EPI = false, bool SP2 = false>
; __device__ __forceinline__ void gemm_phase(PG8_LAS unsigned char* lds, const Gemm g, const Sched& S, const Epi& E) {
;     ...
;             PG8_WAIT_V(8); PG8_WAIT_L(0); PG8_BAR; PG8_MMA(1, 0, At, B0); PG8_MMA(1, 1, At, B1); PG8_BAR; PG8_SCHED;
;             PG8_LDB(B0, 1, 0); PG8_LDB(B1, 1, 1); PG8_SCHED; PG8_LDA(At, 1, 0); PG8_STAGE(PG8_SA(0, 1), a2 + hstep, voffA);
;             PG8_WAIT_V(8); PG8_WAIT_L(0); PG8_BAR; PG8_MMA(0, 0, At, B0); PG8_MMA(0, 1, At, B1); PG8_BAR; PG8_SCHED;
	s_waitcnt lgkmcnt(0)
	v_mfma_f32_16x16x32_bf16 v[62:65], v[150:153], v[182:185], v[62:65]
	v_mfma_f32_16x16x32_bf16 v[58:61], v[158:161], v[182:185], v[58:61]
	v_mfma_f32_16x16x32_bf16 v[54:57], v[150:153], v[190:193], v[54:57]
	v_mfma_f32_16x16x32_bf16 v[50:53], v[158:161], v[190:193], v[50:53]
	v_mfma_f32_16x16x32_bf16 v[30:33], v[150:153], v[198:201], v[30:33]
	v_mfma_f32_16x16x32_bf16 v[26:29], v[158:161], v[198:201], v[26:29]
	v_mfma_f32_16x16x32_bf16 v[22:25], v[150:153], v[206:209], v[22:25]
	v_mfma_f32_16x16x32_bf16 v[14:17], v[158:161], v[206:209], v[14:17]
	v_mfma_f32_16x16x32_bf16 v[62:65], v[154:157], v[186:189], v[62:65]
	v_mfma_f32_16x16x32_bf16 v[58:61], v[162:165], v[186:189], v[58:61]
	v_mfma_f32_16x16x32_bf16 v[54:57], v[154:157], v[194:197], v[54:57]
	v_mfma_f32_16x16x32_bf16 v[50:53], v[162:165], v[194:197], v[50:53]
	v_mfma_f32_16x16x32_bf16 v[30:33], v[154:157], v[202:205], v[30:33]
	v_mfma_f32_16x16x32_bf16 v[26:29], v[162:165], v[202:205], v[26:29]
	v_mfma_f32_16x16x32_bf16 v[22:25], v[154:157], v[210:213], v[22:25]
	v_mfma_f32_16x16x32_bf16 v[14:17], v[162:165], v[210:213], v[14:17]
	v_mfma_f32_16x16x32_bf16 v[46:49], v[166:169], v[182:185], v[46:49]
	v_mfma_f32_16x16x32_bf16 v[42:45], v[174:177], v[182:185], v[42:45]
	v_mfma_f32_16x16x32_bf16 v[38:41], v[166:169], v[190:193], v[38:41]
	v_mfma_f32_16x16x32_bf16 v[34:37], v[174:177], v[190:193], v[34:37]
	v_mfma_f32_16x16x32_bf16 v[18:21], v[166:169], v[198:201], v[18:21]
	v_mfma_f32_16x16x32_bf16 v[10:13], v[174:177], v[198:201], v[10:13]
	v_mfma_f32_16x16x32_bf16 v[6:9], v[166:169], v[206:209], v[6:9]
	v_mfma_f32_16x16x32_bf16 v[2:5], v[174:177], v[206:209], v[2:5]
	v_mfma_f32_16x16x32_bf16 v[46:49], v[170:173], v[186:189], v[46:49]
	v_mfma_f32_16x16x32_bf16 v[42:45], v[178:181], v[186:189], v[42:45]
	v_mfma_f32_16x16x32_bf16 v[38:41], v[170:173], v[194:197], v[38:41]
	v_mfma_f32_16x16x32_bf16 v[34:37], v[178:181], v[194:197], v[34:37]
	v_mfma_f32_16x16x32_bf16 v[18:21], v[170:173], v[202:205], v[18:21]
	v_mfma_f32_16x16x32_bf16 v[10:13], v[178:181], v[202:205], v[10:13]
	v_mfma_f32_16x16x32_bf16 v[6:9], v[170:173], v[210:213], v[6:9]
	v_mfma_f32_16x16x32_bf16 v[2:5], v[178:181], v[210:213], v[2:5]
	s_barrier
	s_add_i32 s69, 0, 0x18000
	v_add_u32_e32 v149, s69, v145
	s_add_i32 s70, 0, 0x1c000
	ds_read_b128 v[150:153], v149
	ds_read_b128 v[154:157], v149 offset:1024
	ds_read_b128 v[158:161], v149 offset:2048
	ds_read_b128 v[162:165], v149 offset:3072
	v_add_u32_e32 v149, s70, v145
	ds_read_b128 v[166:169], v149
	ds_read_b128 v[170:173], v149 offset:1024
	ds_read_b128 v[174:177], v149 offset:2048
	ds_read_b128 v[178:181], v149 offset:3072
	s_add_u32 s46, s46, 0xb0000
	s_addc_u32 s47, s47, 0
	s_mov_b32 m0, s50
	v_lshl_add_u64 v[220:221], s[46:47], 0, v[130:131]
	ds_read_b128 v[182:185], v148 offset:32768
	ds_read_b128 v[186:189], v148 offset:33792
	ds_read_b128 v[190:193], v148 offset:34816
	ds_read_b128 v[194:197], v148 offset:35840
	ds_read_b128 v[198:201], v148 offset:36864
	ds_read_b128 v[202:205], v148 offset:37888
	ds_read_b128 v[206:209], v148 offset:38912
	ds_read_b128 v[210:213], v148 offset:39936
	global_load_lds_dwordx4 v[220:221], off
	v_lshl_add_u64 v[220:221], s[46:47], 0, v[132:133]
	s_mov_b32 m0, s51
	s_nop 0
	global_load_lds_dwordx4 v[220:221], off
	s_waitcnt vmcnt(8)
	s_waitcnt lgkmcnt(0)
	s_barrier
	s_waitcnt lgkmcnt(0)
	v_mfma_f32_16x16x32_bf16 v[126:129], v[150:153], v[182:185], v[126:129]
	v_mfma_f32_16x16x32_bf16 v[122:125], v[158:161], v[182:185], v[122:125]
	v_mfma_f32_16x16x32_bf16 v[118:121], v[150:153], v[190:193], v[118:121]
	v_mfma_f32_16x16x32_bf16 v[114:117], v[158:161], v[190:193], v[114:117]
	v_mfma_f32_16x16x32_bf16 v[94:97], v[150:153], v[198:201], v[94:97]
	v_mfma_f32_16x16x32_bf16 v[90:93], v[158:161], v[198:201], v[90:93]
	v_mfma_f32_16x16x32_bf16 v[86:89], v[150:153], v[206:209], v[86:89]
	v_mfma_f32_16x16x32_bf16 v[82:85], v[158:161], v[206:209], v[82:85]
	v_mfma_f32_16x16x32_bf16 v[126:129], v[154:157], v[186:189], v[126:129]
	v_mfma_f32_16x16x32_bf16 v[122:125], v[162:165], v[186:189], v[122:125]
	v_mfma_f32_16x16x32_bf16 v[118:121], v[154:157], v[194:197], v[118:121]
	v_mfma_f32_16x16x32_bf16 v[114:117], v[162:165], v[194:197], v[114:117]
	v_mfma_f32_16x16x32_bf16 v[94:97], v[154:157], v[202:205], v[94:97]
	v_mfma_f32_16x16x32_bf16 v[90:93], v[162:165], v[202:205], v[90:93]
	v_mfma_f32_16x16x32_bf16 v[86:89], v[154:157], v[210:213], v[86:89]
	v_mfma_f32_16x16x32_bf16 v[82:85], v[162:165], v[210:213], v[82:85]
	v_mfma_f32_16x16x32_bf16 v[110:113], v[166:169], v[182:185], v[110:113]
	v_mfma_f32_16x16x32_bf16 v[106:109], v[174:177], v[182:185], v[106:109]
	v_mfma_f32_16x16x32_bf16 v[102:105], v[166:169], v[190:193], v[102:105]
	v_mfma_f32_16x16x32_bf16 v[98:101], v[174:177], v[190:193], v[98:101]
	v_mfma_f32_16x16x32_bf16 v[78:81], v[166:169], v[198:201], v[78:81]
	v_mfma_f32_16x16x32_bf16 v[74:77], v[174:177], v[198:201], v[74:77]
	v_mfma_f32_16x16x32_bf16 v[70:73], v[166:169], v[206:209], v[70:73]
	v_mfma_f32_16x16x32_bf16 v[66:69], v[174:177], v[206:209], v[66:69]
	v_mfma_f32_16x16x32_bf16 v[110:113], v[170:173], v[186:189], v[110:113]
	v_mfma_f32_16x16x32_bf16 v[106:109], v[178:181], v[186:189], v[106:109]
	v_mfma_f32_16x16x32_bf16 v[102:105], v[170:173], v[194:197], v[102:105]
	v_mfma_f32_16x16x32_bf16 v[98:101], v[178:181], v[194:197], v[98:101]
	v_mfma_f32_16x16x32_bf16 v[78:81], v[170:173], v[202:205], v[78:81]
	v_mfma_f32_16x16x32_bf16 v[74:77], v[178:181], v[202:205], v[74:77]
	v_mfma_f32_16x16x32_bf16 v[70:73], v[170:173], v[210:213], v[70:73]
	v_mfma_f32_16x16x32_bf16 v[66:69], v[178:181], v[210:213], v[66:69]
	s_barrier
; #define PG8_STAGE(bufoff, gbase, voff) do { _Pragma("unroll") for (int _i = 0; _i < 2; ++_i) \
;         __builtin_amdgcn_global_load_lds((const unsigned*)((const char*)(gbase) + (voff)[_i]), (PG8_LAS unsigned*)(lds + (bufoff) + ldsw + _i * 8192), 16, 0, 0); } while (0)
; #define PG8_LDA(dst, b, h) do { _Pragma("unroll") for (int m = 0; m < 4; ++m) _Pragma("unroll") for (int k = 0; k < 2; ++k) dst[m][k] = *(const PG8_LAS bf16x8*)(lds + PG8_SA(b, h) + aoff + m * 2048 + k * 1024); } while (0)
; #define PG8_MMA(ai, bj, At, Bt) do { __builtin_amdgcn_s_setprio(1); _Pragma("unroll") for (int m = 0; m < 4; ++m) _Pragma("unroll") for (int n = 0; n < 2; ++n) _Pragma("unroll") for (int k = 0; k < 2; ++k) \
;         acc[ai][bj][m][n] = __builtin_amdgcn_mfma_f32_16x16x32_bf16(Bt[n][k], At[m][k], acc[ai][bj][m][n], 0, 0, 0); __builtin_amdgcn_s_setprio(0); } while (0)
; #define PG8_WAIT_V(n) asm volatile("s_waitcnt vmcnt(" #n ")" ::: "memory")
; #define PG8_WAIT_L(n) asm volatile("s_waitcnt lgkmcnt(" #n ")" ::: "memory")
; #define PG8_BAR __builtin_amdgcn_s_barrier()
; #define PG8_SCHED __builtin_amdgcn_sched_barrier(0)
; template <class Epi, class Sched, bool ALIGN_EPI = false, bool SP2 = false>
; __device__ __forceinline__ void gemm_phase(PG8_LAS unsigned char* lds, const Gemm g, const Sched& S, const Epi& E) {
;     ...
;         for (int t = 0; t < nt; t += 2) {
;             const bool last = (t == nt - 2);
;             const char* a1 = cA + (size_t)(t + 1) * kstep;
;             const char* a2 = last ? nA : cA + (size_t)(t + 2) * kstep; const char* b2 = last ? nB : cB + (size_t)(t + 2) * kstep;
;     ...
;             PG8_LDA(At, 1, 1); PG8_STAGE(PG8_SB(1, 0), b3, voffB); PG8_STAGE(PG8_SB(1, 1), b3 + hstep, voffB); PG8_STAGE(PG8_SA(1, 0), a3, voffA);
;             PG8_WAIT_V(8); PG8_WAIT_L(0); PG8_BAR; PG8_MMA(1, 0, At, B0); PG8_MMA(1, 1, At, B1); PG8_BAR; PG8_SCHED;
	s_add_i32 s46, s69, s19
	v_lshl_add_u64 v[142:143], v[142:143], 0, s[16:17]
	s_mov_b32 m0, s46
	ds_read_b128 v[182:185], v148 offset:49152
	ds_read_b128 v[186:189], v148 offset:50176
	ds_read_b128 v[190:193], v148 offset:51200
	ds_read_b128 v[194:197], v148 offset:52224
	ds_read_b128 v[198:201], v148 offset:53248
	ds_read_b128 v[202:205], v148 offset:54272
	ds_read_b128 v[206:209], v148 offset:55296
	ds_read_b128 v[210:213], v148 offset:56320
	global_load_lds_dwordx4 v[142:143], off
	s_add_i32 m0, s46, 0x2000
	s_add_u32 s44, s44, 0xb0080
	v_lshl_add_u64 v[142:143], v[214:215], 0, s[16:17]
	s_addc_u32 s45, s45, 0
	s_add_i32 s46, s70, s19
	global_load_lds_dwordx4 v[142:143], off
	v_lshl_add_u64 v[142:143], s[44:45], 0, v[130:131]
	s_mov_b32 m0, s46
	s_nop 0
	global_load_lds_dwordx4 v[142:143], off
	v_lshl_add_u64 v[142:143], s[44:45], 0, v[132:133]
	s_add_i32 m0, s46, 0x2000
	s_nop 0
	global_load_lds_dwordx4 v[142:143], off
	v_lshl_add_u64 v[142:143], v[216:217], 0, s[16:17]
	s_mov_b32 m0, s53
	s_nop 0
	global_load_lds_dwordx4 v[142:143], off
	v_lshl_add_u64 v[142:143], v[218:219], 0, s[16:17]
	s_mov_b32 m0, s54
	s_nop 0
	global_load_lds_dwordx4 v[142:143], off
	s_waitcnt vmcnt(8)
	s_waitcnt lgkmcnt(0)
	s_barrier
	s_waitcnt lgkmcnt(0)
	v_mfma_f32_16x16x32_bf16 v[62:65], v[150:153], v[182:185], v[62:65]
	v_mfma_f32_16x16x32_bf16 v[58:61], v[158:161], v[182:185], v[58:61]
	v_mfma_f32_16x16x32_bf16 v[54:57], v[150:153], v[190:193], v[54:57]
	v_mfma_f32_16x16x32_bf16 v[50:53], v[158:161], v[190:193], v[50:53]
	v_mfma_f32_16x16x32_bf16 v[30:33], v[150:153], v[198:201], v[30:33]
	v_mfma_f32_16x16x32_bf16 v[26:29], v[158:161], v[198:201], v[26:29]
	v_mfma_f32_16x16x32_bf16 v[22:25], v[150:153], v[206:209], v[22:25]
	v_mfma_f32_16x16x32_bf16 v[14:17], v[158:161], v[206:209], v[14:17]
	v_mfma_f32_16x16x32_bf16 v[62:65], v[154:157], v[186:189], v[62:65]
	v_mfma_f32_16x16x32_bf16 v[58:61], v[162:165], v[186:189], v[58:61]
	v_mfma_f32_16x16x32_bf16 v[54:57], v[154:157], v[194:197], v[54:57]
	v_mfma_f32_16x16x32_bf16 v[50:53], v[162:165], v[194:197], v[50:53]
	v_mfma_f32_16x16x32_bf16 v[30:33], v[154:157], v[202:205], v[30:33]
	v_mfma_f32_16x16x32_bf16 v[26:29], v[162:165], v[202:205], v[26:29]
	v_mfma_f32_16x16x32_bf16 v[22:25], v[154:157], v[210:213], v[22:25]
	v_mfma_f32_16x16x32_bf16 v[14:17], v[162:165], v[210:213], v[14:17]
	v_mfma_f32_16x16x32_bf16 v[46:49], v[166:169], v[182:185], v[46:49]
	v_mfma_f32_16x16x32_bf16 v[42:45], v[174:177], v[182:185], v[42:45]
	v_mfma_f32_16x16x32_bf16 v[38:41], v[166:169], v[190:193], v[38:41]
	v_mfma_f32_16x16x32_bf16 v[34:37], v[174:177], v[190:193], v[34:37]
	v_mfma_f32_16x16x32_bf16 v[18:21], v[166:169], v[198:201], v[18:21]
	v_mfma_f32_16x16x32_bf16 v[10:13], v[174:177], v[198:201], v[10:13]
	v_mfma_f32_16x16x32_bf16 v[6:9], v[166:169], v[206:209], v[6:9]
	v_mfma_f32_16x16x32_bf16 v[2:5], v[174:177], v[206:209], v[2:5]
	v_mfma_f32_16x16x32_bf16 v[46:49], v[170:173], v[186:189], v[46:49]
	v_mfma_f32_16x16x32_bf16 v[42:45], v[178:181], v[186:189], v[42:45]
	v_mfma_f32_16x16x32_bf16 v[38:41], v[170:173], v[194:197], v[38:41]
	v_mfma_f32_16x16x32_bf16 v[34:37], v[178:181], v[194:197], v[34:37]
	v_mfma_f32_16x16x32_bf16 v[18:21], v[170:173], v[202:205], v[18:21]
	v_mfma_f32_16x16x32_bf16 v[10:13], v[178:181], v[202:205], v[10:13]
	v_mfma_f32_16x16x32_bf16 v[6:9], v[170:173], v[210:213], v[6:9]
	v_mfma_f32_16x16x32_bf16 v[2:5], v[178:181], v[210:213], v[2:5]
	s_barrier
	s_add_i32 s68, s68, 2
	s_add_u32 s42, s42, 0x100
	s_addc_u32 s43, s43, 0
	s_add_u32 s66, s66, 0x100
	s_addc_u32 s67, s67, 0
	s_cmp_gt_u32 s68, 41
	s_cbranch_scc0 .LBB0_1928
	s_and_b64 vcc, exec, s[30:31]
	s_cbranch_vccz .LBB0_1931
	s_barrier
